# plus 36 duplicate s_waitcnt lgkmcnt(0) removed from the GEMM loops
# speedup vs baseline: 1.0192x; 1.0192x over previous
.LBB0_58:
	s_add_u32 s44, s42, 0x100
	s_addc_u32 s45, s43, 0
	s_add_i32 s23, 0, 0x10000
	v_add_u32_e32 v145, s23, v143
	ds_read_b128 v[146:149], v145
	ds_read_b128 v[150:153], v145 offset:1024
	ds_read_b128 v[154:157], v145 offset:2048
	ds_read_b128 v[158:161], v145 offset:3072
	s_cmp_eq_u32 s22, 40
	s_cselect_b32 s49, s1, s45
	s_cselect_b32 s48, s0, s44
	s_cselect_b32 s47, s41, s21
	s_cselect_b32 s46, s40, s20
	v_lshl_add_u64 v[194:195], s[42:43], 0, v[138:139]
	s_add_i32 m0, s52, 0xc000
	ds_read_b128 v[162:165], v144
	ds_read_b128 v[166:169], v144 offset:1024
	ds_read_b128 v[170:173], v144 offset:2048
	ds_read_b128 v[174:177], v144 offset:3072
	ds_read_b128 v[178:181], v144 offset:4096
	ds_read_b128 v[182:185], v144 offset:5120
	ds_read_b128 v[186:189], v144 offset:6144
	ds_read_b128 v[190:193], v144 offset:7168
	global_load_lds_dwordx4 v[194:195], off
	v_lshl_add_u64 v[194:195], s[42:43], 0, v[140:141]
	s_add_i32 m0, s52, 0xe000
	s_nop 0
	global_load_lds_dwordx4 v[194:195], off
	s_waitcnt lgkmcnt(8)
	s_barrier
	s_waitcnt lgkmcnt(0)
	v_mfma_f32_16x16x32_bf16 v[128:131], v[146:149], v[162:165], v[128:131]
	v_mfma_f32_16x16x32_bf16 v[124:127], v[154:157], v[162:165], v[124:127]
	v_mfma_f32_16x16x32_bf16 v[120:123], v[146:149], v[170:173], v[120:123]
	v_mfma_f32_16x16x32_bf16 v[116:119], v[154:157], v[170:173], v[116:119]
	v_mfma_f32_16x16x32_bf16 v[104:107], v[146:149], v[178:181], v[104:107]
	v_mfma_f32_16x16x32_bf16 v[100:103], v[154:157], v[178:181], v[100:103]
	v_mfma_f32_16x16x32_bf16 v[88:91], v[146:149], v[186:189], v[88:91]
	v_mfma_f32_16x16x32_bf16 v[84:87], v[154:157], v[186:189], v[84:87]
	v_mfma_f32_16x16x32_bf16 v[128:131], v[150:153], v[166:169], v[128:131]
	v_mfma_f32_16x16x32_bf16 v[124:127], v[158:161], v[166:169], v[124:127]
	v_mfma_f32_16x16x32_bf16 v[120:123], v[150:153], v[174:177], v[120:123]
	v_mfma_f32_16x16x32_bf16 v[116:119], v[158:161], v[174:177], v[116:119]
	v_mfma_f32_16x16x32_bf16 v[104:107], v[150:153], v[182:185], v[104:107]
	v_mfma_f32_16x16x32_bf16 v[100:103], v[158:161], v[182:185], v[100:103]
	v_mfma_f32_16x16x32_bf16 v[88:91], v[150:153], v[190:193], v[88:91]
	v_mfma_f32_16x16x32_bf16 v[84:87], v[158:161], v[190:193], v[84:87]
	s_barrier
	s_add_i32 s26, 0, 0x14000
	s_add_i32 s23, s23, s37
	v_add_u32_e32 v145, s26, v143
	v_lshl_add_u64 v[194:195], s[46:47], 0, v[132:133]
	s_mov_b32 m0, s23
	ds_read_b128 v[202:205], v145
	ds_read_b128 v[206:209], v145 offset:1024
	ds_read_b128 v[210:213], v145 offset:2048
	ds_read_b128 v[214:217], v145 offset:3072
	global_load_lds_dwordx4 v[194:195], off
	v_lshl_add_u64 v[198:199], s[46:47], 0, v[136:137]
	s_add_i32 m0, s23, 0x2000
	s_nop 0
	global_load_lds_dwordx4 v[198:199], off
	s_barrier
	s_waitcnt lgkmcnt(0)
	v_mfma_f32_16x16x32_bf16 v[112:115], v[202:205], v[162:165], v[112:115]
	v_mfma_f32_16x16x32_bf16 v[108:111], v[210:213], v[162:165], v[108:111]
	v_mfma_f32_16x16x32_bf16 v[96:99], v[202:205], v[170:173], v[96:99]
	v_mfma_f32_16x16x32_bf16 v[92:95], v[210:213], v[170:173], v[92:95]
	v_mfma_f32_16x16x32_bf16 v[80:83], v[202:205], v[178:181], v[80:83]
	v_mfma_f32_16x16x32_bf16 v[76:79], v[210:213], v[178:181], v[76:79]
	v_mfma_f32_16x16x32_bf16 v[72:75], v[202:205], v[186:189], v[72:75]
	v_mfma_f32_16x16x32_bf16 v[68:71], v[210:213], v[186:189], v[68:71]
	v_mfma_f32_16x16x32_bf16 v[112:115], v[206:209], v[166:169], v[112:115]
	v_mfma_f32_16x16x32_bf16 v[108:111], v[214:217], v[166:169], v[108:111]
	v_mfma_f32_16x16x32_bf16 v[96:99], v[206:209], v[174:177], v[96:99]
	v_mfma_f32_16x16x32_bf16 v[92:95], v[214:217], v[174:177], v[92:95]
	v_mfma_f32_16x16x32_bf16 v[80:83], v[206:209], v[182:185], v[80:83]
	v_mfma_f32_16x16x32_bf16 v[76:79], v[214:217], v[182:185], v[76:79]
	v_mfma_f32_16x16x32_bf16 v[72:75], v[206:209], v[190:193], v[72:75]
	v_mfma_f32_16x16x32_bf16 v[68:71], v[214:217], v[190:193], v[68:71]
	s_mov_b32 m0, s52
	v_lshl_add_u64 v[222:223], s[48:49], 0, v[0:1]
	s_barrier
	ds_read_b128 v[162:165], v144 offset:16384
	ds_read_b128 v[166:169], v144 offset:17408
	ds_read_b128 v[170:173], v144 offset:18432
	ds_read_b128 v[174:177], v144 offset:19456
	ds_read_b128 v[178:181], v144 offset:20480
	ds_read_b128 v[182:185], v144 offset:21504
	ds_read_b128 v[186:189], v144 offset:22528
	ds_read_b128 v[190:193], v144 offset:23552
	global_load_lds_dwordx4 v[222:223], off
	v_lshl_add_u64 v[236:237], s[48:49], 0, v[134:135]
	s_mov_b32 m0, s53
	s_nop 0
	global_load_lds_dwordx4 v[236:237], off
	s_barrier
	s_waitcnt lgkmcnt(0)
	v_mfma_f32_16x16x32_bf16 v[64:67], v[146:149], v[162:165], v[64:67]
	v_mfma_f32_16x16x32_bf16 v[60:63], v[154:157], v[162:165], v[60:63]
	v_mfma_f32_16x16x32_bf16 v[56:59], v[146:149], v[170:173], v[56:59]
	v_mfma_f32_16x16x32_bf16 v[52:55], v[154:157], v[170:173], v[52:55]
	v_mfma_f32_16x16x32_bf16 v[40:43], v[146:149], v[178:181], v[40:43]
	v_mfma_f32_16x16x32_bf16 v[36:39], v[154:157], v[178:181], v[36:39]
	v_mfma_f32_16x16x32_bf16 v[24:27], v[146:149], v[186:189], v[24:27]
	v_mfma_f32_16x16x32_bf16 v[16:19], v[154:157], v[186:189], v[16:19]
	v_mfma_f32_16x16x32_bf16 v[64:67], v[150:153], v[166:169], v[64:67]
	v_mfma_f32_16x16x32_bf16 v[60:63], v[158:161], v[166:169], v[60:63]
	v_mfma_f32_16x16x32_bf16 v[56:59], v[150:153], v[174:177], v[56:59]
	v_mfma_f32_16x16x32_bf16 v[52:55], v[158:161], v[174:177], v[52:55]
	v_mfma_f32_16x16x32_bf16 v[40:43], v[150:153], v[182:185], v[40:43]
	v_mfma_f32_16x16x32_bf16 v[36:39], v[158:161], v[182:185], v[36:39]
	v_mfma_f32_16x16x32_bf16 v[24:27], v[150:153], v[190:193], v[24:27]
	v_mfma_f32_16x16x32_bf16 v[16:19], v[158:161], v[190:193], v[16:19]
	s_barrier
	s_add_u32 s24, s46, 0xb0000
	s_addc_u32 s25, s47, 0
	s_add_i32 s23, s26, s37
	v_lshl_add_u64 v[146:147], s[24:25], 0, v[132:133]
	s_mov_b32 m0, s23
	s_nop 0
	global_load_lds_dwordx4 v[146:147], off
	v_lshl_add_u64 v[146:147], s[24:25], 0, v[136:137]
	s_add_i32 m0, s23, 0x2000
	s_nop 0
	global_load_lds_dwordx4 v[146:147], off
	s_waitcnt vmcnt(6)
	s_barrier
	v_mfma_f32_16x16x32_bf16 v[48:51], v[202:205], v[162:165], v[48:51]
	v_mfma_f32_16x16x32_bf16 v[44:47], v[210:213], v[162:165], v[44:47]
	v_mfma_f32_16x16x32_bf16 v[32:35], v[202:205], v[170:173], v[32:35]
	v_mfma_f32_16x16x32_bf16 v[28:31], v[210:213], v[170:173], v[28:31]
	v_mfma_f32_16x16x32_bf16 v[20:23], v[202:205], v[178:181], v[20:23]
	v_mfma_f32_16x16x32_bf16 v[12:15], v[210:213], v[178:181], v[12:15]
	v_mfma_f32_16x16x32_bf16 v[8:11], v[202:205], v[186:189], v[8:11]
	v_mfma_f32_16x16x32_bf16 v[4:7], v[210:213], v[186:189], v[4:7]
	v_mfma_f32_16x16x32_bf16 v[48:51], v[206:209], v[166:169], v[48:51]
	v_mfma_f32_16x16x32_bf16 v[44:47], v[214:217], v[166:169], v[44:47]
	v_mfma_f32_16x16x32_bf16 v[32:35], v[206:209], v[174:177], v[32:35]
	v_mfma_f32_16x16x32_bf16 v[28:31], v[214:217], v[174:177], v[28:31]
	v_mfma_f32_16x16x32_bf16 v[20:23], v[206:209], v[182:185], v[20:23]
	v_mfma_f32_16x16x32_bf16 v[12:15], v[214:217], v[182:185], v[12:15]
	v_mfma_f32_16x16x32_bf16 v[8:11], v[206:209], v[190:193], v[8:11]
	v_mfma_f32_16x16x32_bf16 v[4:7], v[214:217], v[190:193], v[4:7]
	s_add_i32 s23, 0, 0x18000
	v_add_u32_e32 v145, s23, v143
	s_barrier
	ds_read_b128 v[146:149], v145
	ds_read_b128 v[150:153], v145 offset:1024
	ds_read_b128 v[154:157], v145 offset:2048
	ds_read_b128 v[158:161], v145 offset:3072
	s_add_u32 s24, s48, 0xb0000
	s_addc_u32 s25, s49, 0
	s_mov_b32 m0, s54
	v_lshl_add_u64 v[202:203], s[24:25], 0, v[0:1]
	ds_read_b128 v[162:165], v144 offset:32768
	ds_read_b128 v[166:169], v144 offset:33792
	ds_read_b128 v[170:173], v144 offset:34816
	ds_read_b128 v[174:177], v144 offset:35840
	ds_read_b128 v[178:181], v144 offset:36864
	ds_read_b128 v[182:185], v144 offset:37888
	ds_read_b128 v[186:189], v144 offset:38912
	ds_read_b128 v[190:193], v144 offset:39936
	global_load_lds_dwordx4 v[202:203], off
	v_lshl_add_u64 v[202:203], s[24:25], 0, v[134:135]
	s_mov_b32 m0, s55
	s_nop 0
	global_load_lds_dwordx4 v[202:203], off
	s_waitcnt lgkmcnt(8)
	s_barrier
	s_waitcnt lgkmcnt(0)
	v_mfma_f32_16x16x32_bf16 v[128:131], v[146:149], v[162:165], v[128:131]
	v_mfma_f32_16x16x32_bf16 v[124:127], v[154:157], v[162:165], v[124:127]
	v_mfma_f32_16x16x32_bf16 v[120:123], v[146:149], v[170:173], v[120:123]
	v_mfma_f32_16x16x32_bf16 v[116:119], v[154:157], v[170:173], v[116:119]
	v_mfma_f32_16x16x32_bf16 v[104:107], v[146:149], v[178:181], v[104:107]
	v_mfma_f32_16x16x32_bf16 v[100:103], v[154:157], v[178:181], v[100:103]
	v_mfma_f32_16x16x32_bf16 v[88:91], v[146:149], v[186:189], v[88:91]
	v_mfma_f32_16x16x32_bf16 v[84:87], v[154:157], v[186:189], v[84:87]
	v_mfma_f32_16x16x32_bf16 v[128:131], v[150:153], v[166:169], v[128:131]
	v_mfma_f32_16x16x32_bf16 v[124:127], v[158:161], v[166:169], v[124:127]
	v_mfma_f32_16x16x32_bf16 v[120:123], v[150:153], v[174:177], v[120:123]
	v_mfma_f32_16x16x32_bf16 v[116:119], v[158:161], v[174:177], v[116:119]
	v_mfma_f32_16x16x32_bf16 v[104:107], v[150:153], v[182:185], v[104:107]
	v_mfma_f32_16x16x32_bf16 v[100:103], v[158:161], v[182:185], v[100:103]
	v_mfma_f32_16x16x32_bf16 v[88:91], v[150:153], v[190:193], v[88:91]
	v_mfma_f32_16x16x32_bf16 v[84:87], v[158:161], v[190:193], v[84:87]
	s_barrier
	s_add_i32 s26, 0, 0x1c000
	s_add_i32 s23, s23, s37
	v_add_u32_e32 v145, s26, v143
	v_lshl_add_u64 v[194:195], v[194:195], 0, s[76:77]
	s_mov_b32 m0, s23
	ds_read_b128 v[202:205], v145
	ds_read_b128 v[206:209], v145 offset:1024
	ds_read_b128 v[210:213], v145 offset:2048
	ds_read_b128 v[214:217], v145 offset:3072
	global_load_lds_dwordx4 v[194:195], off
	v_lshl_add_u64 v[194:195], v[198:199], 0, s[76:77]
	s_add_i32 m0, s23, 0x2000
	s_nop 0
	global_load_lds_dwordx4 v[194:195], off
	s_barrier
	s_waitcnt lgkmcnt(0)
	v_mfma_f32_16x16x32_bf16 v[112:115], v[202:205], v[162:165], v[112:115]
	v_mfma_f32_16x16x32_bf16 v[108:111], v[210:213], v[162:165], v[108:111]
	v_mfma_f32_16x16x32_bf16 v[96:99], v[202:205], v[170:173], v[96:99]
	v_mfma_f32_16x16x32_bf16 v[92:95], v[210:213], v[170:173], v[92:95]
	v_mfma_f32_16x16x32_bf16 v[80:83], v[202:205], v[178:181], v[80:83]
	v_mfma_f32_16x16x32_bf16 v[76:79], v[210:213], v[178:181], v[76:79]
	v_mfma_f32_16x16x32_bf16 v[72:75], v[202:205], v[186:189], v[72:75]
	v_mfma_f32_16x16x32_bf16 v[68:71], v[210:213], v[186:189], v[68:71]
	v_mfma_f32_16x16x32_bf16 v[112:115], v[206:209], v[166:169], v[112:115]
	v_mfma_f32_16x16x32_bf16 v[108:111], v[214:217], v[166:169], v[108:111]
	v_mfma_f32_16x16x32_bf16 v[96:99], v[206:209], v[174:177], v[96:99]
	v_mfma_f32_16x16x32_bf16 v[92:95], v[214:217], v[174:177], v[92:95]
	v_mfma_f32_16x16x32_bf16 v[80:83], v[206:209], v[182:185], v[80:83]
	v_mfma_f32_16x16x32_bf16 v[76:79], v[214:217], v[182:185], v[76:79]
	v_mfma_f32_16x16x32_bf16 v[72:75], v[206:209], v[190:193], v[72:75]
	v_mfma_f32_16x16x32_bf16 v[68:71], v[214:217], v[190:193], v[68:71]
	s_mov_b32 m0, s56
	v_lshl_add_u64 v[194:195], v[222:223], 0, s[76:77]
	s_barrier
	ds_read_b128 v[162:165], v144 offset:49152
	ds_read_b128 v[166:169], v144 offset:50176
	ds_read_b128 v[170:173], v144 offset:51200
	ds_read_b128 v[174:177], v144 offset:52224
	ds_read_b128 v[178:181], v144 offset:53248
	ds_read_b128 v[182:185], v144 offset:54272
	ds_read_b128 v[186:189], v144 offset:55296
	ds_read_b128 v[190:193], v144 offset:56320
	global_load_lds_dwordx4 v[194:195], off
	v_lshl_add_u64 v[194:195], v[236:237], 0, s[76:77]
	s_mov_b32 m0, s57
	s_nop 0
	global_load_lds_dwordx4 v[194:195], off
	s_barrier
	s_waitcnt lgkmcnt(0)
	v_mfma_f32_16x16x32_bf16 v[64:67], v[146:149], v[162:165], v[64:67]
	v_mfma_f32_16x16x32_bf16 v[60:63], v[154:157], v[162:165], v[60:63]
	v_mfma_f32_16x16x32_bf16 v[56:59], v[146:149], v[170:173], v[56:59]
	v_mfma_f32_16x16x32_bf16 v[52:55], v[154:157], v[170:173], v[52:55]
	v_mfma_f32_16x16x32_bf16 v[40:43], v[146:149], v[178:181], v[40:43]
	v_mfma_f32_16x16x32_bf16 v[36:39], v[154:157], v[178:181], v[36:39]
	v_mfma_f32_16x16x32_bf16 v[24:27], v[146:149], v[186:189], v[24:27]
	v_mfma_f32_16x16x32_bf16 v[16:19], v[154:157], v[186:189], v[16:19]
	v_mfma_f32_16x16x32_bf16 v[64:67], v[150:153], v[166:169], v[64:67]
	v_mfma_f32_16x16x32_bf16 v[60:63], v[158:161], v[166:169], v[60:63]
	v_mfma_f32_16x16x32_bf16 v[56:59], v[150:153], v[174:177], v[56:59]
	v_mfma_f32_16x16x32_bf16 v[52:55], v[158:161], v[174:177], v[52:55]
	v_mfma_f32_16x16x32_bf16 v[40:43], v[150:153], v[182:185], v[40:43]
	v_mfma_f32_16x16x32_bf16 v[36:39], v[158:161], v[182:185], v[36:39]
	v_mfma_f32_16x16x32_bf16 v[24:27], v[150:153], v[190:193], v[24:27]
	v_mfma_f32_16x16x32_bf16 v[16:19], v[158:161], v[190:193], v[16:19]
	s_barrier
	s_add_u32 s24, s46, 0xb0080
	s_addc_u32 s25, s47, 0
	s_add_i32 s23, s26, s37
	v_lshl_add_u64 v[146:147], s[24:25], 0, v[132:133]
	s_mov_b32 m0, s23
	s_nop 0
	global_load_lds_dwordx4 v[146:147], off
	v_lshl_add_u64 v[146:147], s[24:25], 0, v[136:137]
	s_add_i32 m0, s23, 0x2000
	s_nop 0
	global_load_lds_dwordx4 v[146:147], off
	s_waitcnt vmcnt(6)
	s_barrier
	v_mfma_f32_16x16x32_bf16 v[48:51], v[202:205], v[162:165], v[48:51]
	v_mfma_f32_16x16x32_bf16 v[44:47], v[210:213], v[162:165], v[44:47]
	v_mfma_f32_16x16x32_bf16 v[32:35], v[202:205], v[170:173], v[32:35]
	v_mfma_f32_16x16x32_bf16 v[28:31], v[210:213], v[170:173], v[28:31]
	v_mfma_f32_16x16x32_bf16 v[20:23], v[202:205], v[178:181], v[20:23]
	v_mfma_f32_16x16x32_bf16 v[12:15], v[210:213], v[178:181], v[12:15]
	v_mfma_f32_16x16x32_bf16 v[8:11], v[202:205], v[186:189], v[8:11]
	v_mfma_f32_16x16x32_bf16 v[4:7], v[210:213], v[186:189], v[4:7]
	v_mfma_f32_16x16x32_bf16 v[48:51], v[206:209], v[166:169], v[48:51]
	v_mfma_f32_16x16x32_bf16 v[44:47], v[214:217], v[166:169], v[44:47]
	v_mfma_f32_16x16x32_bf16 v[32:35], v[206:209], v[174:177], v[32:35]
	v_mfma_f32_16x16x32_bf16 v[28:31], v[214:217], v[174:177], v[28:31]
	v_mfma_f32_16x16x32_bf16 v[20:23], v[206:209], v[182:185], v[20:23]
	v_mfma_f32_16x16x32_bf16 v[12:15], v[214:217], v[182:185], v[12:15]
	v_mfma_f32_16x16x32_bf16 v[8:11], v[206:209], v[190:193], v[8:11]
	v_mfma_f32_16x16x32_bf16 v[4:7], v[214:217], v[190:193], v[4:7]
	s_add_i32 s22, s22, 2
	s_add_u32 s20, s20, 0x100
	s_addc_u32 s21, s21, 0
	s_cmp_gt_u32 s22, 41
	s_mov_b64 s[42:43], s[44:45]
	s_barrier
	s_cbranch_scc0 .LBB0_58
	v_lshl_add_u32 v146, s61, 8, v142
	v_cvt_pk_bf16_f32 v72, v72, v73
	v_cvt_pk_bf16_f32 v73, v74, v75
	v_cvt_pk_bf16_f32 v74, v68, v69
	v_add_u32_e32 v68, 0x80, v146
	s_lshl_b32 s20, s62, 8
	v_ashrrev_i32_e32 v147, 31, v146
	v_readlane_b32 s22, v252, 10
	v_cvt_pk_bf16_f32 v112, v112, v113
	v_cvt_pk_bf16_f32 v113, v114, v115
	v_cvt_pk_bf16_f32 v114, v108, v109
	v_or_b32_e32 v108, 16, v146
	v_ashrrev_i32_e32 v69, 31, v68
	v_cvt_pk_bf16_f32 v48, v48, v49
	v_cvt_pk_bf16_f32 v49, v50, v51
	v_cvt_pk_bf16_f32 v50, v44, v45
	v_add_u32_e32 v44, 0x90, v146
	s_ashr_i32 s21, s20, 31
	v_lshlrev_b64 v[148:149], 11, v[146:147]
	v_readlane_b32 s23, v252, 11
	v_ashrrev_i32_e32 v109, 31, v108
	v_cvt_pk_bf16_f32 v96, v96, v97
	v_cvt_pk_bf16_f32 v97, v98, v99
	v_cvt_pk_bf16_f32 v98, v92, v93
	v_or_b32_e32 v92, 32, v146
	v_lshlrev_b64 v[68:69], 11, v[68:69]
	v_ashrrev_i32_e32 v45, 31, v44
	v_cvt_pk_bf16_f32 v32, v32, v33
	v_cvt_pk_bf16_f32 v33, v34, v35
	v_cvt_pk_bf16_f32 v34, v28, v29
	v_add_u32_e32 v28, 0xa0, v146
	v_lshl_add_u64 v[148:149], s[22:23], 0, v[148:149]
	s_lshl_b64 s[42:43], s[20:21], 1
	v_lshlrev_b64 v[108:109], 11, v[108:109]
	v_ashrrev_i32_e32 v93, 31, v92
	v_cvt_pk_bf16_f32 v80, v80, v81
	v_cvt_pk_bf16_f32 v81, v82, v83
	v_cvt_pk_bf16_f32 v82, v76, v77
	v_or_b32_e32 v76, 48, v146
	v_lshl_add_u64 v[68:69], s[22:23], 0, v[68:69]
	v_lshlrev_b64 v[44:45], 11, v[44:45]
	v_ashrrev_i32_e32 v29, 31, v28
	v_cvt_pk_bf16_f32 v20, v20, v21
	v_cvt_pk_bf16_f32 v21, v22, v23
	v_cvt_pk_bf16_f32 v22, v12, v13
	v_add_u32_e32 v12, 0xb0, v146
	v_lshl_add_u64 v[148:149], v[148:149], 0, s[42:43]
	v_lshl_add_u64 v[108:109], s[22:23], 0, v[108:109]
	v_lshlrev_b64 v[92:93], 11, v[92:93]
	v_ashrrev_i32_e32 v77, 31, v76
	v_lshl_add_u64 v[68:69], v[68:69], 0, s[42:43]
	v_lshl_add_u64 v[44:45], s[22:23], 0, v[44:45]
	v_lshlrev_b64 v[28:29], 11, v[28:29]
	v_ashrrev_i32_e32 v13, 31, v12
	v_lshl_add_u64 v[148:149], v[148:149], 0, s[72:73]
	v_lshl_add_u64 v[108:109], v[108:109], 0, s[42:43]
	v_lshl_add_u64 v[92:93], s[22:23], 0, v[92:93]
	v_lshlrev_b64 v[76:77], 11, v[76:77]
	v_lshl_add_u64 v[68:69], v[68:69], 0, s[72:73]
	v_lshl_add_u64 v[44:45], v[44:45], 0, s[42:43]
	v_lshl_add_u64 v[28:29], s[22:23], 0, v[28:29]
	v_lshlrev_b64 v[12:13], 11, v[12:13]
	v_lshl_add_u64 v[148:149], v[148:149], 0, v[2:3]
	v_cvt_pk_bf16_f32 v115, v110, v111
	v_lshl_add_u64 v[108:109], v[108:109], 0, s[72:73]
	v_lshl_add_u64 v[92:93], v[92:93], 0, s[42:43]
	v_lshl_add_u64 v[76:77], s[22:23], 0, v[76:77]
	v_lshl_add_u64 v[68:69], v[68:69], 0, v[2:3]
	v_cvt_pk_bf16_f32 v51, v46, v47
	v_lshl_add_u64 v[44:45], v[44:45], 0, s[72:73]
	v_lshl_add_u64 v[28:29], v[28:29], 0, s[42:43]
	v_lshl_add_u64 v[12:13], s[22:23], 0, v[12:13]
	global_store_dwordx4 v[148:149], v[112:115], off offset:256
	v_cvt_pk_bf16_f32 v99, v94, v95
	v_lshl_add_u64 v[92:93], v[92:93], 0, s[72:73]
	v_lshl_add_u64 v[112:113], v[108:109], 0, v[2:3]
	v_lshl_add_u64 v[76:77], v[76:77], 0, s[42:43]
	global_store_dwordx4 v[68:69], v[48:51], off offset:256
	v_cvt_pk_bf16_f32 v35, v30, v31
	v_lshl_add_u64 v[28:29], v[28:29], 0, s[72:73]
	v_lshl_add_u64 v[48:49], v[44:45], 0, v[2:3]
	v_lshl_add_u64 v[12:13], v[12:13], 0, s[42:43]
	global_store_dwordx4 v[112:113], v[96:99], off offset:256
	v_cvt_pk_bf16_f32 v83, v78, v79
	v_lshl_add_u64 v[76:77], v[76:77], 0, s[72:73]
	v_lshl_add_u64 v[96:97], v[92:93], 0, v[2:3]
	global_store_dwordx4 v[48:49], v[32:35], off offset:256
	v_cvt_pk_bf16_f32 v23, v14, v15
	v_lshl_add_u64 v[12:13], v[12:13], 0, s[72:73]
	v_lshl_add_u64 v[32:33], v[28:29], 0, v[2:3]
	v_cvt_pk_bf16_f32 v128, v128, v129
	v_cvt_pk_bf16_f32 v129, v130, v131
	v_cvt_pk_bf16_f32 v130, v124, v125
	v_cvt_pk_bf16_f32 v131, v126, v127
	v_cvt_pk_bf16_f32 v108, v120, v121
	v_cvt_pk_bf16_f32 v109, v122, v123
	v_cvt_pk_bf16_f32 v110, v116, v117
	v_cvt_pk_bf16_f32 v111, v118, v119
	v_cvt_pk_bf16_f32 v92, v104, v105
	v_cvt_pk_bf16_f32 v93, v106, v107
	v_cvt_pk_bf16_f32 v94, v100, v101
	v_cvt_pk_bf16_f32 v95, v102, v103
	global_store_dwordx4 v[96:97], v[80:83], off offset:256
	v_cvt_pk_bf16_f32 v78, v84, v85
	v_cvt_pk_bf16_f32 v79, v86, v87
	v_lshl_add_u64 v[80:81], v[76:77], 0, v[2:3]
	v_cvt_pk_bf16_f32 v76, v88, v89
	v_cvt_pk_bf16_f32 v77, v90, v91
	v_cvt_pk_bf16_f32 v75, v70, v71
	v_cvt_pk_bf16_f32 v64, v64, v65
	v_cvt_pk_bf16_f32 v65, v66, v67
	v_cvt_pk_bf16_f32 v66, v60, v61
	v_cvt_pk_bf16_f32 v67, v62, v63
	v_cvt_pk_bf16_f32 v44, v56, v57
	v_cvt_pk_bf16_f32 v45, v58, v59
	v_cvt_pk_bf16_f32 v46, v52, v53
	v_cvt_pk_bf16_f32 v47, v54, v55
	v_cvt_pk_bf16_f32 v28, v40, v41
	v_cvt_pk_bf16_f32 v29, v42, v43
	v_cvt_pk_bf16_f32 v30, v36, v37
	v_cvt_pk_bf16_f32 v31, v38, v39
	global_store_dwordx4 v[32:33], v[20:23], off offset:256
	v_cvt_pk_bf16_f32 v14, v16, v17
	v_cvt_pk_bf16_f32 v15, v18, v19
	v_lshl_add_u64 v[20:21], v[12:13], 0, v[2:3]
	v_cvt_pk_bf16_f32 v12, v24, v25
	v_cvt_pk_bf16_f32 v13, v26, v27
	v_cvt_pk_bf16_f32 v8, v8, v9
	v_cvt_pk_bf16_f32 v9, v10, v11
	v_cvt_pk_bf16_f32 v10, v4, v5
	v_cvt_pk_bf16_f32 v11, v6, v7
	s_and_b64 vcc, exec, s[38:39]
	s_mov_b32 s62, s59
	s_mov_b32 s61, s60
	s_mov_b64 s[44:45], s[40:41]
	s_mov_b64 s[42:43], s[0:1]
	global_store_dwordx4 v[148:149], v[128:131], off
	global_store_dwordx4 v[112:113], v[108:111], off
	global_store_dwordx4 v[96:97], v[92:95], off
	global_store_dwordx4 v[80:81], v[76:79], off
	global_store_dwordx4 v[80:81], v[72:75], off offset:256
	global_store_dwordx4 v[68:69], v[64:67], off
	global_store_dwordx4 v[48:49], v[44:47], off
	global_store_dwordx4 v[32:33], v[28:31], off
	global_store_dwordx4 v[20:21], v[12:15], off
	global_store_dwordx4 v[20:21], v[8:11], off offset:256
	s_cbranch_vccz .LBB0_51
	s_waitcnt vmcnt(0)
	s_cmpk_gt_u32 s36, 0xff
	s_cbranch_scc1 .LBB0_62
	s_barrier

.LBB0_80:
	s_add_u32 s22, s52, 0xfffc0080
	s_addc_u32 s23, s53, -1
	s_add_i32 s24, 0, 0x10000
	v_add_u32_e32 v64, s24, v235
	ds_read_b128 v[52:55], v64
	ds_read_b128 v[56:59], v64 offset:1024
	ds_read_b128 v[60:63], v64 offset:2048
	ds_read_b128 v[64:67], v64 offset:3072
	s_cmp_eq_u32 s21, 12
	s_cselect_b32 s57, s47, s23
	s_cselect_b32 s56, s46, s22
	s_cselect_b32 s55, s49, s20
	s_cselect_b32 s54, s48, s1
	v_lshl_add_u64 v[116:117], s[52:53], 0, v[206:207]
	s_add_i32 m0, s62, 0xc000
	ds_read_b128 v[76:79], v239
	ds_read_b128 v[80:83], v239 offset:1024
	ds_read_b128 v[84:87], v239 offset:2048
	ds_read_b128 v[88:91], v239 offset:3072
	ds_read_b128 v[92:95], v239 offset:4096
	ds_read_b128 v[96:99], v239 offset:5120
	ds_read_b128 v[100:103], v239 offset:6144
	ds_read_b128 v[104:107], v239 offset:7168
	global_load_lds_dwordx4 v[116:117], off
	v_lshl_add_u64 v[116:117], s[52:53], 0, v[208:209]
	s_add_i32 m0, s62, 0xe000
	s_nop 0
	global_load_lds_dwordx4 v[116:117], off
	s_waitcnt lgkmcnt(8)
	s_barrier
	s_waitcnt lgkmcnt(0)
	v_mfma_f32_16x16x32_bf16 v[160:163], v[52:55], v[92:95], v[160:163]
	v_mfma_f32_16x16x32_bf16 v[152:155], v[60:63], v[92:95], v[152:155]
	v_mfma_f32_16x16x32_bf16 v[144:147], v[52:55], v[100:103], v[144:147]
	v_mfma_f32_16x16x32_bf16 v[140:143], v[60:63], v[100:103], v[140:143]
	v_mfma_f32_16x16x32_bf16 v[116:119], v[52:55], v[76:79], v[192:195]
	v_mfma_f32_16x16x32_bf16 v[120:123], v[60:63], v[76:79], v[184:187]
	v_mfma_f32_16x16x32_bf16 v[124:127], v[52:55], v[84:87], v[176:179]
	v_mfma_f32_16x16x32_bf16 v[128:131], v[60:63], v[84:87], v[168:171]
	v_mfma_f32_16x16x32_bf16 v[160:163], v[56:59], v[96:99], v[160:163]
	v_mfma_f32_16x16x32_bf16 v[152:155], v[64:67], v[96:99], v[152:155]
	v_mfma_f32_16x16x32_bf16 v[144:147], v[56:59], v[104:107], v[144:147]
	v_mfma_f32_16x16x32_bf16 v[140:143], v[64:67], v[104:107], v[140:143]
	v_mfma_f32_16x16x32_bf16 v[116:119], v[56:59], v[80:83], v[116:119]
	v_mfma_f32_16x16x32_bf16 v[120:123], v[64:67], v[80:83], v[120:123]
	v_mfma_f32_16x16x32_bf16 v[124:127], v[56:59], v[88:91], v[124:127]
	v_mfma_f32_16x16x32_bf16 v[128:131], v[64:67], v[88:91], v[128:131]
	s_barrier
	s_add_i32 s25, 0, 0x14000
	s_add_i32 s22, s24, s60
	v_add_u32_e32 v192, s25, v235
	v_lshl_add_u64 v[198:199], s[54:55], 0, v[2:3]
	s_mov_b32 m0, s22
	ds_read_b128 v[168:171], v192
	ds_read_b128 v[176:179], v192 offset:1024
	ds_read_b128 v[184:187], v192 offset:2048
	ds_read_b128 v[192:195], v192 offset:3072
	global_load_lds_dwordx4 v[198:199], off
	v_lshl_add_u64 v[222:223], s[54:55], 0, v[0:1]
	s_add_i32 m0, s22, 0x2000
	s_nop 0
	global_load_lds_dwordx4 v[222:223], off
	s_barrier
	s_waitcnt lgkmcnt(0)
	v_mfma_f32_16x16x32_bf16 v[188:191], v[168:171], v[76:79], v[188:191]
	v_mfma_f32_16x16x32_bf16 v[76:79], v[184:187], v[76:79], v[180:183]
	v_mfma_f32_16x16x32_bf16 v[188:191], v[176:179], v[80:83], v[188:191]
	v_mfma_f32_16x16x32_bf16 v[76:79], v[192:195], v[80:83], v[76:79]
	v_mfma_f32_16x16x32_bf16 v[80:83], v[168:171], v[84:87], v[172:175]
	v_mfma_f32_16x16x32_bf16 v[84:87], v[184:187], v[84:87], v[164:167]
	v_mfma_f32_16x16x32_bf16 v[80:83], v[176:179], v[88:91], v[80:83]
	v_mfma_f32_16x16x32_bf16 v[84:87], v[192:195], v[88:91], v[84:87]
	v_mfma_f32_16x16x32_bf16 v[88:91], v[168:171], v[92:95], v[156:159]
	v_mfma_f32_16x16x32_bf16 v[92:95], v[184:187], v[92:95], v[148:151]
	v_mfma_f32_16x16x32_bf16 v[88:91], v[176:179], v[96:99], v[88:91]
	v_mfma_f32_16x16x32_bf16 v[92:95], v[192:195], v[96:99], v[92:95]
	v_mfma_f32_16x16x32_bf16 v[96:99], v[168:171], v[100:103], v[136:139]
	v_mfma_f32_16x16x32_bf16 v[100:103], v[184:187], v[100:103], v[132:135]
	v_mfma_f32_16x16x32_bf16 v[96:99], v[176:179], v[104:107], v[96:99]
	v_mfma_f32_16x16x32_bf16 v[100:103], v[192:195], v[104:107], v[100:103]
	s_mov_b32 m0, s62
	v_lshl_add_u64 v[248:249], s[56:57], 0, v[204:205]
	s_barrier
	ds_read_b128 v[104:107], v239 offset:16384
	ds_read_b128 v[132:135], v239 offset:17408
	ds_read_b128 v[136:139], v239 offset:18432
	ds_read_b128 v[148:151], v239 offset:19456
	ds_read_b128 v[156:159], v239 offset:20480
	ds_read_b128 v[164:167], v239 offset:21504
	ds_read_b128 v[172:175], v239 offset:22528
	ds_read_b128 v[180:183], v239 offset:23552
	global_load_lds_dwordx4 v[248:249], off
	v_lshl_add_u64 v[250:251], s[56:57], 0, v[202:203]
	s_mov_b32 m0, s63
	s_nop 0
	global_load_lds_dwordx4 v[250:251], off
	s_barrier
	s_waitcnt lgkmcnt(0)
	v_mfma_f32_16x16x32_bf16 v[112:115], v[52:55], v[104:107], v[112:115]
	v_mfma_f32_16x16x32_bf16 v[72:75], v[60:63], v[104:107], v[72:75]
	v_mfma_f32_16x16x32_bf16 v[48:51], v[52:55], v[136:139], v[48:51]
	v_mfma_f32_16x16x32_bf16 v[40:43], v[60:63], v[136:139], v[40:43]
	v_mfma_f32_16x16x32_bf16 v[32:35], v[52:55], v[156:159], v[32:35]
	v_mfma_f32_16x16x32_bf16 v[24:27], v[60:63], v[156:159], v[24:27]
	v_mfma_f32_16x16x32_bf16 v[16:19], v[52:55], v[172:175], v[16:19]
	v_mfma_f32_16x16x32_bf16 v[12:15], v[60:63], v[172:175], v[12:15]
	v_mfma_f32_16x16x32_bf16 v[112:115], v[56:59], v[132:135], v[112:115]
	v_mfma_f32_16x16x32_bf16 v[72:75], v[64:67], v[132:135], v[72:75]
	v_mfma_f32_16x16x32_bf16 v[48:51], v[56:59], v[148:151], v[48:51]
	v_mfma_f32_16x16x32_bf16 v[40:43], v[64:67], v[148:151], v[40:43]
	v_mfma_f32_16x16x32_bf16 v[32:35], v[56:59], v[164:167], v[32:35]
	v_mfma_f32_16x16x32_bf16 v[24:27], v[64:67], v[164:167], v[24:27]
	v_mfma_f32_16x16x32_bf16 v[16:19], v[56:59], v[180:183], v[16:19]
	v_mfma_f32_16x16x32_bf16 v[12:15], v[64:67], v[180:183], v[12:15]
	s_barrier
	s_add_u32 s22, s54, 0x40000
	s_addc_u32 s23, s55, 0
	s_add_i32 s24, s25, s60
	v_lshl_add_u64 v[52:53], s[22:23], 0, v[2:3]
	s_mov_b32 m0, s24
	s_nop 0
	global_load_lds_dwordx4 v[52:53], off
	v_lshl_add_u64 v[52:53], s[22:23], 0, v[0:1]
	s_add_i32 m0, s24, 0x2000
	s_nop 0
	global_load_lds_dwordx4 v[52:53], off
	s_waitcnt vmcnt(6)
	s_barrier
	v_mfma_f32_16x16x32_bf16 v[44:47], v[168:171], v[136:139], v[44:47]
	v_mfma_f32_16x16x32_bf16 v[36:39], v[184:187], v[136:139], v[36:39]
	v_mfma_f32_16x16x32_bf16 v[28:31], v[168:171], v[156:159], v[28:31]
	v_mfma_f32_16x16x32_bf16 v[20:23], v[184:187], v[156:159], v[20:23]
	v_mfma_f32_16x16x32_bf16 v[8:11], v[168:171], v[172:175], v[8:11]
	v_mfma_f32_16x16x32_bf16 v[4:7], v[184:187], v[172:175], v[4:7]
	v_mfma_f32_16x16x32_bf16 v[52:55], v[168:171], v[104:107], v[108:111]
	v_mfma_f32_16x16x32_bf16 v[56:59], v[184:187], v[104:107], v[68:71]
	v_mfma_f32_16x16x32_bf16 v[44:47], v[176:179], v[148:151], v[44:47]
	v_mfma_f32_16x16x32_bf16 v[36:39], v[192:195], v[148:151], v[36:39]
	v_mfma_f32_16x16x32_bf16 v[28:31], v[176:179], v[164:167], v[28:31]
	v_mfma_f32_16x16x32_bf16 v[20:23], v[192:195], v[164:167], v[20:23]
	v_mfma_f32_16x16x32_bf16 v[8:11], v[176:179], v[180:183], v[8:11]
	v_mfma_f32_16x16x32_bf16 v[4:7], v[192:195], v[180:183], v[4:7]
	v_mfma_f32_16x16x32_bf16 v[52:55], v[176:179], v[132:135], v[52:55]
	v_mfma_f32_16x16x32_bf16 v[56:59], v[192:195], v[132:135], v[56:59]
	s_add_i32 s24, 0, 0x18000
	v_add_u32_e32 v104, s24, v235
	s_barrier
	ds_read_b128 v[60:63], v104
	ds_read_b128 v[64:67], v104 offset:1024
	ds_read_b128 v[68:71], v104 offset:2048
	ds_read_b128 v[104:107], v104 offset:3072
	s_add_u32 s22, s56, 0x40000
	s_addc_u32 s23, s57, 0
	s_mov_b32 m0, s64
	v_lshl_add_u64 v[156:157], s[22:23], 0, v[204:205]
	ds_read_b128 v[108:111], v239 offset:32768
	ds_read_b128 v[132:135], v239 offset:33792
	ds_read_b128 v[136:139], v239 offset:34816
	ds_read_b128 v[148:151], v239 offset:35840
	ds_read_b128 v[210:213], v239 offset:36864
	ds_read_b128 v[214:217], v239 offset:37888
	ds_read_b128 v[240:243], v239 offset:38912
	ds_read_b128 v[244:247], v239 offset:39936
	global_load_lds_dwordx4 v[156:157], off
	v_lshl_add_u64 v[156:157], s[22:23], 0, v[202:203]
	s_mov_b32 m0, s65
	s_nop 0
	global_load_lds_dwordx4 v[156:157], off
	s_waitcnt lgkmcnt(8)
	s_barrier
	s_waitcnt lgkmcnt(0)
	v_mfma_f32_16x16x32_bf16 v[116:119], v[60:63], v[108:111], v[116:119]
	v_mfma_f32_16x16x32_bf16 v[192:195], v[64:67], v[132:135], v[116:119]
	v_mfma_f32_16x16x32_bf16 v[116:119], v[68:71], v[108:111], v[120:123]
	v_mfma_f32_16x16x32_bf16 v[184:187], v[104:107], v[132:135], v[116:119]
	v_mfma_f32_16x16x32_bf16 v[116:119], v[60:63], v[136:139], v[124:127]
	v_mfma_f32_16x16x32_bf16 v[176:179], v[64:67], v[148:151], v[116:119]
	v_mfma_f32_16x16x32_bf16 v[116:119], v[68:71], v[136:139], v[128:131]
	v_mfma_f32_16x16x32_bf16 v[168:171], v[104:107], v[148:151], v[116:119]
	v_mfma_f32_16x16x32_bf16 v[116:119], v[60:63], v[210:213], v[160:163]
	v_mfma_f32_16x16x32_bf16 v[160:163], v[64:67], v[214:217], v[116:119]
	v_mfma_f32_16x16x32_bf16 v[116:119], v[68:71], v[210:213], v[152:155]
	v_mfma_f32_16x16x32_bf16 v[152:155], v[104:107], v[214:217], v[116:119]
	v_mfma_f32_16x16x32_bf16 v[116:119], v[60:63], v[240:243], v[144:147]
	v_mfma_f32_16x16x32_bf16 v[144:147], v[64:67], v[244:247], v[116:119]
	v_mfma_f32_16x16x32_bf16 v[116:119], v[68:71], v[240:243], v[140:143]
	v_mfma_f32_16x16x32_bf16 v[140:143], v[104:107], v[244:247], v[116:119]
	s_barrier
	s_add_i32 s25, 0, 0x1c000
	s_add_i32 s22, s24, s60
	v_add_u32_e32 v128, s25, v235
	v_lshl_add_u64 v[156:157], v[198:199], 0, s[76:77]
	s_mov_b32 m0, s22
	ds_read_b128 v[116:119], v128
	ds_read_b128 v[120:123], v128 offset:1024
	ds_read_b128 v[124:127], v128 offset:2048
	ds_read_b128 v[128:131], v128 offset:3072
	global_load_lds_dwordx4 v[156:157], off
	v_lshl_add_u64 v[156:157], v[222:223], 0, s[76:77]
	s_add_i32 m0, s22, 0x2000
	s_nop 0
	global_load_lds_dwordx4 v[156:157], off
	s_barrier
	s_waitcnt lgkmcnt(0)
	v_mfma_f32_16x16x32_bf16 v[76:79], v[124:127], v[108:111], v[76:79]
	v_mfma_f32_16x16x32_bf16 v[180:183], v[128:131], v[132:135], v[76:79]
	v_mfma_f32_16x16x32_bf16 v[76:79], v[116:119], v[136:139], v[80:83]
	v_mfma_f32_16x16x32_bf16 v[172:175], v[120:123], v[148:151], v[76:79]
	v_mfma_f32_16x16x32_bf16 v[76:79], v[124:127], v[136:139], v[84:87]
	v_mfma_f32_16x16x32_bf16 v[156:159], v[116:119], v[108:111], v[188:191]
	v_mfma_f32_16x16x32_bf16 v[164:167], v[128:131], v[148:151], v[76:79]
	v_mfma_f32_16x16x32_bf16 v[76:79], v[116:119], v[210:213], v[88:91]
	v_mfma_f32_16x16x32_bf16 v[188:191], v[120:123], v[132:135], v[156:159]
	v_mfma_f32_16x16x32_bf16 v[156:159], v[120:123], v[214:217], v[76:79]
	v_mfma_f32_16x16x32_bf16 v[76:79], v[124:127], v[210:213], v[92:95]
	v_mfma_f32_16x16x32_bf16 v[148:151], v[128:131], v[214:217], v[76:79]
	v_mfma_f32_16x16x32_bf16 v[76:79], v[116:119], v[240:243], v[96:99]
	v_mfma_f32_16x16x32_bf16 v[136:139], v[120:123], v[244:247], v[76:79]
	v_mfma_f32_16x16x32_bf16 v[76:79], v[124:127], v[240:243], v[100:103]
	v_mfma_f32_16x16x32_bf16 v[132:135], v[128:131], v[244:247], v[76:79]
	s_mov_b32 m0, s72
	v_lshl_add_u64 v[108:109], v[248:249], 0, s[76:77]
	s_barrier
	s_nop 2
	ds_read_b128 v[76:79], v239 offset:49152
	ds_read_b128 v[80:83], v239 offset:50176
	ds_read_b128 v[84:87], v239 offset:51200
	ds_read_b128 v[88:91], v239 offset:52224
	ds_read_b128 v[92:95], v239 offset:53248
	ds_read_b128 v[96:99], v239 offset:54272
	ds_read_b128 v[100:103], v239 offset:55296
	ds_read_b128 v[210:213], v239 offset:56320
	global_load_lds_dwordx4 v[108:109], off
	v_lshl_add_u64 v[108:109], v[250:251], 0, s[76:77]
	s_mov_b32 m0, s74
	s_nop 0
	global_load_lds_dwordx4 v[108:109], off
	s_barrier
	s_waitcnt lgkmcnt(0)
	v_mfma_f32_16x16x32_bf16 v[108:111], v[60:63], v[76:79], v[112:115]
	v_mfma_f32_16x16x32_bf16 v[72:75], v[68:71], v[76:79], v[72:75]
	v_mfma_f32_16x16x32_bf16 v[48:51], v[60:63], v[84:87], v[48:51]
	v_mfma_f32_16x16x32_bf16 v[40:43], v[68:71], v[84:87], v[40:43]
	v_mfma_f32_16x16x32_bf16 v[32:35], v[60:63], v[92:95], v[32:35]
	v_mfma_f32_16x16x32_bf16 v[24:27], v[68:71], v[92:95], v[24:27]
	v_mfma_f32_16x16x32_bf16 v[16:19], v[60:63], v[100:103], v[16:19]
	v_mfma_f32_16x16x32_bf16 v[12:15], v[68:71], v[100:103], v[12:15]
	v_mfma_f32_16x16x32_bf16 v[112:115], v[64:67], v[80:83], v[108:111]
	v_mfma_f32_16x16x32_bf16 v[72:75], v[104:107], v[80:83], v[72:75]
	v_mfma_f32_16x16x32_bf16 v[48:51], v[64:67], v[88:91], v[48:51]
	v_mfma_f32_16x16x32_bf16 v[40:43], v[104:107], v[88:91], v[40:43]
	v_mfma_f32_16x16x32_bf16 v[32:35], v[64:67], v[96:99], v[32:35]
	v_mfma_f32_16x16x32_bf16 v[24:27], v[104:107], v[96:99], v[24:27]
	v_mfma_f32_16x16x32_bf16 v[16:19], v[64:67], v[210:213], v[16:19]
	v_mfma_f32_16x16x32_bf16 v[12:15], v[104:107], v[210:213], v[12:15]
	s_barrier
	s_add_u32 s22, s54, 0x40080
	s_addc_u32 s23, s55, 0
	s_add_i32 s24, s25, s60
	v_lshl_add_u64 v[60:61], s[22:23], 0, v[2:3]
	s_mov_b32 m0, s24
	s_nop 0
	global_load_lds_dwordx4 v[60:61], off
	v_lshl_add_u64 v[60:61], s[22:23], 0, v[0:1]
	s_add_i32 m0, s24, 0x2000
	s_nop 0
	global_load_lds_dwordx4 v[60:61], off
	s_waitcnt vmcnt(6)
	s_barrier
	v_mfma_f32_16x16x32_bf16 v[52:55], v[116:119], v[76:79], v[52:55]
	v_mfma_f32_16x16x32_bf16 v[108:111], v[120:123], v[80:83], v[52:55]
	v_mfma_f32_16x16x32_bf16 v[52:55], v[124:127], v[76:79], v[56:59]
	v_mfma_f32_16x16x32_bf16 v[44:47], v[116:119], v[84:87], v[44:47]
	v_mfma_f32_16x16x32_bf16 v[36:39], v[124:127], v[84:87], v[36:39]
	v_mfma_f32_16x16x32_bf16 v[28:31], v[116:119], v[92:95], v[28:31]
	v_mfma_f32_16x16x32_bf16 v[20:23], v[124:127], v[92:95], v[20:23]
	v_mfma_f32_16x16x32_bf16 v[8:11], v[116:119], v[100:103], v[8:11]
	v_mfma_f32_16x16x32_bf16 v[4:7], v[124:127], v[100:103], v[4:7]
	v_mfma_f32_16x16x32_bf16 v[68:71], v[128:131], v[80:83], v[52:55]
	v_mfma_f32_16x16x32_bf16 v[44:47], v[120:123], v[88:91], v[44:47]
	v_mfma_f32_16x16x32_bf16 v[36:39], v[128:131], v[88:91], v[36:39]
	v_mfma_f32_16x16x32_bf16 v[28:31], v[120:123], v[96:99], v[28:31]
	v_mfma_f32_16x16x32_bf16 v[20:23], v[128:131], v[96:99], v[20:23]
	v_mfma_f32_16x16x32_bf16 v[8:11], v[120:123], v[210:213], v[8:11]
	v_mfma_f32_16x16x32_bf16 v[4:7], v[128:131], v[210:213], v[4:7]
	s_add_i32 s21, s21, 2
	s_add_u32 s52, s52, 0x100
	s_addc_u32 s53, s53, 0
	s_add_u32 s1, s1, 0x100
	s_addc_u32 s20, s20, 0
	s_cmp_gt_u32 s21, 13
	s_barrier
	s_cbranch_scc0 .LBB0_80
	v_lshl_or_b32 v210, s30, 7, v238
	s_lshl_b32 s1, s50, 8
	s_add_i32 s1, s1, s67
	v_lshlrev_b32_e32 v211, 2, v210
	v_lshlrev_b32_e32 v219, 1, v210
	v_readlane_b32 s2, v252, 4
	v_readlane_b32 s3, v252, 5
	v_readlane_b32 s20, v252, 20
	v_readlane_b32 s21, v252, 21
	v_readlane_b32 s22, v252, 2
	v_readlane_b32 s23, v252, 3
	v_readlane_b32 s24, v252, 22
	v_readlane_b32 s25, v252, 23
	v_readlane_b32 s26, v252, 24
	v_readlane_b32 s27, v252, 25
	v_readlane_b32 s50, v252, 26
	v_readlane_b32 s51, v252, 27
	v_readlane_b32 s56, v252, 28
	v_readlane_b32 s57, v252, 29
	v_readlane_b32 s98, v252, 30
	v_readlane_b32 s99, v252, 31
	v_lshl_add_u32 v240, v201, 2, s1
	v_mul_u32_u24_e32 v240, 0x1600, v240
	v_add_u32_e32 v240, v240, v219
	global_load_dwordx4 v[120:123], v211, s[2:3]
	global_load_dwordx4 v[80:83], v211, s[2:3] offset:16
	global_load_dwordx4 v[116:119], v211, s[20:21]
	global_load_dwordx4 v[76:79], v211, s[20:21] offset:16
	global_load_dwordx4 v[96:99], v211, s[22:23]
	global_load_dwordx4 v[56:59], v211, s[22:23] offset:16
	global_load_dwordx4 v[92:95], v211, s[24:25]
	global_load_dwordx4 v[52:55], v211, s[24:25] offset:16
	global_load_dwordx4 v[104:107], v211, s[26:27]
	global_load_dwordx4 v[64:67], v211, s[26:27] offset:16
	global_load_dwordx4 v[100:103], v211, s[50:51]
	global_load_dwordx4 v[60:63], v211, s[50:51] offset:16
	global_load_dwordx4 v[124:127], v211, s[56:57]
	global_load_dwordx4 v[84:87], v211, s[56:57] offset:16
	global_load_dwordx4 v[128:131], v211, s[98:99]
	global_load_dwordx4 v[88:91], v211, s[98:99] offset:16
	v_readlane_b32 s56, v254, 63
	v_readlane_b32 s57, v255, 0
	v_cmp_eq_u32_e64 s[2:3], 0, v201
	v_cmp_eq_u32_e64 s[26:27], 15, v201
	s_lshr_b32 s24, s1, 4
	s_mov_b64 exec, s[2:3]
	v_cvt_pk_bf16_f32 v212, v192, v193
	v_cvt_pk_bf16_f32 v213, v194, v195
	v_cvt_pk_bf16_f32 v214, v184, v185
	v_cvt_pk_bf16_f32 v215, v186, v187
	s_add_i32 s20, s24, 2
	s_mulk_i32 s20, 0x2c00
	s_add_u32 s22, s56, s20
	s_addc_u32 s23, s57, 0
	global_store_dwordx4 v219, v[212:215], s[22:23]
	v_cvt_pk_bf16_f32 v242, v188, v189
	v_cvt_pk_bf16_f32 v243, v190, v191
	v_cvt_pk_bf16_f32 v244, v180, v181
	v_cvt_pk_bf16_f32 v245, v182, v183
	s_add_u32 s22, s22, 0x1600
	s_addc_u32 s23, s23, 0
	global_store_dwordx4 v219, v[242:245], s[22:23]
	v_cvt_pk_bf16_f32 v246, v176, v177
	v_cvt_pk_bf16_f32 v247, v178, v179
	v_cvt_pk_bf16_f32 v248, v168, v169
	v_cvt_pk_bf16_f32 v249, v170, v171
	s_add_i32 s20, s24, 3
	s_mulk_i32 s20, 0x2c00
	s_add_u32 s22, s56, s20
	s_addc_u32 s23, s57, 0
	global_store_dwordx4 v219, v[246:249], s[22:23]
	v_cvt_pk_bf16_f32 v212, v172, v173
	v_cvt_pk_bf16_f32 v213, v174, v175
	v_cvt_pk_bf16_f32 v214, v164, v165
	v_cvt_pk_bf16_f32 v215, v166, v167
	s_add_u32 s22, s22, 0x1600
	s_addc_u32 s23, s23, 0
	global_store_dwordx4 v219, v[212:215], s[22:23]
	s_mov_b64 exec, s[26:27]
	v_cvt_pk_bf16_f32 v242, v160, v161
	v_cvt_pk_bf16_f32 v243, v162, v163
	v_cvt_pk_bf16_f32 v244, v152, v153
	v_cvt_pk_bf16_f32 v245, v154, v155
	s_add_i32 s20, s24, 0
	s_mulk_i32 s20, 0x2c00
	s_add_u32 s22, s56, s20
	s_addc_u32 s23, s57, 0
	global_store_dwordx4 v219, v[242:245], s[22:23]
	v_cvt_pk_bf16_f32 v246, v156, v157
	v_cvt_pk_bf16_f32 v247, v158, v159
	v_cvt_pk_bf16_f32 v248, v148, v149
	v_cvt_pk_bf16_f32 v249, v150, v151
	s_add_u32 s22, s22, 0x1600
	s_addc_u32 s23, s23, 0
	global_store_dwordx4 v219, v[246:249], s[22:23]
	v_cvt_pk_bf16_f32 v212, v144, v145
	v_cvt_pk_bf16_f32 v213, v146, v147
	v_cvt_pk_bf16_f32 v214, v140, v141
	v_cvt_pk_bf16_f32 v215, v142, v143
	s_add_i32 s20, s24, 1
	s_mulk_i32 s20, 0x2c00
	s_add_u32 s22, s56, s20
	s_addc_u32 s23, s57, 0
	global_store_dwordx4 v219, v[212:215], s[22:23]
	v_cvt_pk_bf16_f32 v242, v136, v137
	v_cvt_pk_bf16_f32 v243, v138, v139
	v_cvt_pk_bf16_f32 v244, v132, v133
	v_cvt_pk_bf16_f32 v245, v134, v135
	s_add_u32 s22, s22, 0x1600
	s_addc_u32 s23, s23, 0
	global_store_dwordx4 v219, v[242:245], s[22:23]
	s_mov_b64 exec, s[2:3]
	v_cvt_pk_bf16_f32 v246, v112, v113
	v_cvt_pk_bf16_f32 v247, v114, v115
	v_cvt_pk_bf16_f32 v248, v72, v73
	v_cvt_pk_bf16_f32 v249, v74, v75
	s_add_i32 s20, s24, 10
	s_mulk_i32 s20, 0x2c00
	s_add_u32 s22, s56, s20
	s_addc_u32 s23, s57, 0
	global_store_dwordx4 v219, v[246:249], s[22:23]
	v_cvt_pk_bf16_f32 v212, v108, v109
	v_cvt_pk_bf16_f32 v213, v110, v111
	v_cvt_pk_bf16_f32 v214, v68, v69
	v_cvt_pk_bf16_f32 v215, v70, v71
	s_add_u32 s22, s22, 0x1600
	s_addc_u32 s23, s23, 0
	global_store_dwordx4 v219, v[212:215], s[22:23]
	v_cvt_pk_bf16_f32 v242, v48, v49
	v_cvt_pk_bf16_f32 v243, v50, v51
	v_cvt_pk_bf16_f32 v244, v40, v41
	v_cvt_pk_bf16_f32 v245, v42, v43
	s_add_i32 s20, s24, 11
	s_mulk_i32 s20, 0x2c00
	s_add_u32 s22, s56, s20
	s_addc_u32 s23, s57, 0
	global_store_dwordx4 v219, v[242:245], s[22:23]
	v_cvt_pk_bf16_f32 v246, v44, v45
	v_cvt_pk_bf16_f32 v247, v46, v47
	v_cvt_pk_bf16_f32 v248, v36, v37
	v_cvt_pk_bf16_f32 v249, v38, v39
	s_add_u32 s22, s22, 0x1600
	s_addc_u32 s23, s23, 0
	global_store_dwordx4 v219, v[246:249], s[22:23]
	s_mov_b64 exec, s[26:27]
	v_cvt_pk_bf16_f32 v212, v32, v33
	v_cvt_pk_bf16_f32 v213, v34, v35
	v_cvt_pk_bf16_f32 v214, v24, v25
	v_cvt_pk_bf16_f32 v215, v26, v27
	s_add_i32 s20, s24, 8
	s_mulk_i32 s20, 0x2c00
	s_add_u32 s22, s56, s20
	s_addc_u32 s23, s57, 0
	global_store_dwordx4 v219, v[212:215], s[22:23]
	v_cvt_pk_bf16_f32 v242, v28, v29
	v_cvt_pk_bf16_f32 v243, v30, v31
	v_cvt_pk_bf16_f32 v244, v20, v21
	v_cvt_pk_bf16_f32 v245, v22, v23
	s_add_u32 s22, s22, 0x1600
	s_addc_u32 s23, s23, 0
	global_store_dwordx4 v219, v[242:245], s[22:23]
	v_cvt_pk_bf16_f32 v246, v16, v17
	v_cvt_pk_bf16_f32 v247, v18, v19
	v_cvt_pk_bf16_f32 v248, v12, v13
	v_cvt_pk_bf16_f32 v249, v14, v15
	s_add_i32 s20, s24, 9
	s_mulk_i32 s20, 0x2c00
	s_add_u32 s22, s56, s20
	s_addc_u32 s23, s57, 0
	global_store_dwordx4 v219, v[246:249], s[22:23]
	v_cvt_pk_bf16_f32 v212, v8, v9
	v_cvt_pk_bf16_f32 v213, v10, v11
	v_cvt_pk_bf16_f32 v214, v4, v5
	v_cvt_pk_bf16_f32 v215, v6, v7
	s_add_u32 s22, s22, 0x1600
	s_addc_u32 s23, s23, 0
	global_store_dwordx4 v219, v[212:215], s[22:23]
	s_mov_b64 exec, -1
	s_mov_b32 s50, 0xbfb8aa3b
	s_mov_b32 s51, 0xbfb8aa3b
	s_waitcnt vmcnt(16)
	v_mov_b32_dpp v198, v144 row_shr:1 row_mask:0xf bank_mask:0xf bound_ctrl:1
	v_mov_b32_dpp v199, v145 row_shr:1 row_mask:0xf bank_mask:0xf bound_ctrl:1
	v_mov_b32_dpp v214, v136 row_shr:1 row_mask:0xf bank_mask:0xf bound_ctrl:1
	v_mov_b32_dpp v215, v137 row_shr:1 row_mask:0xf bank_mask:0xf bound_ctrl:1
	v_mov_b32_dpp v212, v160 row_shr:1 row_mask:0xf bank_mask:0xf bound_ctrl:1
	v_mov_b32_dpp v213, v161 row_shr:1 row_mask:0xf bank_mask:0xf bound_ctrl:1
	v_mov_b32_dpp v216, v156 row_shr:1 row_mask:0xf bank_mask:0xf bound_ctrl:1
	v_mov_b32_dpp v217, v157 row_shr:1 row_mask:0xf bank_mask:0xf bound_ctrl:1
	v_pk_fma_f32 v[144:145], v[144:145], v[124:125], v[120:121]
	v_pk_fma_f32 v[136:137], v[136:137], v[128:129], v[116:117]
	v_pk_fma_f32 v[144:145], v[160:161], v[104:105], v[144:145]
	v_pk_fma_f32 v[136:137], v[156:157], v[100:101], v[136:137]
	v_pk_fma_f32 v[144:145], v[176:177], v[96:97], v[144:145]
	v_pk_fma_f32 v[136:137], v[172:173], v[92:93], v[136:137]
	v_pk_fma_f32 v[160:161], v[160:161], v[124:125], v[120:121]
	v_pk_fma_f32 v[156:157], v[156:157], v[128:129], v[116:117]
	v_pk_fma_f32 v[160:161], v[176:177], v[104:105], v[160:161]
	v_pk_fma_f32 v[156:157], v[172:173], v[100:101], v[156:157]
	v_pk_fma_f32 v[160:161], v[192:193], v[96:97], v[160:161]
	v_pk_fma_f32 v[156:157], v[188:189], v[92:93], v[156:157]
	v_pk_fma_f32 v[176:177], v[176:177], v[124:125], v[120:121]
	v_pk_fma_f32 v[172:173], v[172:173], v[128:129], v[116:117]
	v_pk_fma_f32 v[176:177], v[192:193], v[104:105], v[176:177]
	v_pk_fma_f32 v[172:173], v[188:189], v[100:101], v[172:173]
	v_pk_fma_f32 v[176:177], v[198:199], v[96:97], v[176:177]
	v_pk_fma_f32 v[172:173], v[214:215], v[92:93], v[172:173]
	v_pk_fma_f32 v[192:193], v[192:193], v[124:125], v[120:121]
	v_pk_fma_f32 v[188:189], v[188:189], v[128:129], v[116:117]
	v_pk_fma_f32 v[192:193], v[198:199], v[104:105], v[192:193]
	v_pk_fma_f32 v[188:189], v[214:215], v[100:101], v[188:189]
	v_pk_fma_f32 v[192:193], v[212:213], v[96:97], v[192:193]
	v_pk_fma_f32 v[188:189], v[216:217], v[92:93], v[188:189]
	v_pk_mul_f32 v[222:223], v[192:193], s[50:51]
	v_pk_mul_f32 v[242:243], v[176:177], s[50:51]
	v_pk_mul_f32 v[244:245], v[160:161], s[50:51]
	v_pk_mul_f32 v[246:247], v[144:145], s[50:51]
	v_exp_f32_e32 v222, v222
	v_exp_f32_e32 v223, v223
	v_exp_f32_e32 v242, v242
	v_exp_f32_e32 v243, v243
	v_exp_f32_e32 v244, v244
	v_exp_f32_e32 v245, v245
	v_exp_f32_e32 v246, v246
	v_exp_f32_e32 v247, v247
	v_pk_add_f32 v[222:223], v[222:223], 1.0 op_sel_hi:[1,0]
	v_pk_add_f32 v[242:243], v[242:243], 1.0 op_sel_hi:[1,0]
	v_pk_add_f32 v[244:245], v[244:245], 1.0 op_sel_hi:[1,0]
	v_pk_add_f32 v[246:247], v[246:247], 1.0 op_sel_hi:[1,0]
	v_rcp_f32_e32 v222, v222
	v_rcp_f32_e32 v223, v223
	v_rcp_f32_e32 v242, v242
	v_rcp_f32_e32 v243, v243
	v_rcp_f32_e32 v244, v244
	v_rcp_f32_e32 v245, v245
	v_rcp_f32_e32 v246, v246
	v_rcp_f32_e32 v247, v247
	v_pk_mul_f32 v[192:193], v[192:193], v[222:223]
	v_pk_mul_f32 v[176:177], v[176:177], v[242:243]
	v_pk_mul_f32 v[160:161], v[160:161], v[244:245]
	v_pk_mul_f32 v[144:145], v[144:145], v[246:247]
	v_pk_mul_f32 v[192:193], v[192:193], v[188:189]
	v_pk_mul_f32 v[176:177], v[176:177], v[172:173]
	v_pk_mul_f32 v[160:161], v[160:161], v[156:157]
	v_pk_mul_f32 v[144:145], v[144:145], v[136:137]
	v_cvt_pk_bf16_f32 v192, v192, v193
	v_cvt_pk_bf16_f32 v176, v176, v177
	v_cvt_pk_bf16_f32 v160, v160, v161
	v_cvt_pk_bf16_f32 v144, v144, v145
	v_mov_b32_dpp v198, v146 row_shr:1 row_mask:0xf bank_mask:0xf bound_ctrl:1
	v_mov_b32_dpp v199, v147 row_shr:1 row_mask:0xf bank_mask:0xf bound_ctrl:1
	v_mov_b32_dpp v214, v138 row_shr:1 row_mask:0xf bank_mask:0xf bound_ctrl:1
	v_mov_b32_dpp v215, v139 row_shr:1 row_mask:0xf bank_mask:0xf bound_ctrl:1
	v_mov_b32_dpp v212, v162 row_shr:1 row_mask:0xf bank_mask:0xf bound_ctrl:1
	v_mov_b32_dpp v213, v163 row_shr:1 row_mask:0xf bank_mask:0xf bound_ctrl:1
	v_mov_b32_dpp v216, v158 row_shr:1 row_mask:0xf bank_mask:0xf bound_ctrl:1
	v_mov_b32_dpp v217, v159 row_shr:1 row_mask:0xf bank_mask:0xf bound_ctrl:1
	v_pk_fma_f32 v[146:147], v[146:147], v[126:127], v[122:123]
	v_pk_fma_f32 v[138:139], v[138:139], v[130:131], v[118:119]
	v_pk_fma_f32 v[146:147], v[162:163], v[106:107], v[146:147]
	v_pk_fma_f32 v[138:139], v[158:159], v[102:103], v[138:139]
	v_pk_fma_f32 v[146:147], v[178:179], v[98:99], v[146:147]
	v_pk_fma_f32 v[138:139], v[174:175], v[94:95], v[138:139]
	v_pk_fma_f32 v[162:163], v[162:163], v[126:127], v[122:123]
	v_pk_fma_f32 v[158:159], v[158:159], v[130:131], v[118:119]
	v_pk_fma_f32 v[162:163], v[178:179], v[106:107], v[162:163]
	v_pk_fma_f32 v[158:159], v[174:175], v[102:103], v[158:159]
	v_pk_fma_f32 v[162:163], v[194:195], v[98:99], v[162:163]
	v_pk_fma_f32 v[158:159], v[190:191], v[94:95], v[158:159]
	v_pk_fma_f32 v[178:179], v[178:179], v[126:127], v[122:123]
	v_pk_fma_f32 v[174:175], v[174:175], v[130:131], v[118:119]
	v_pk_fma_f32 v[178:179], v[194:195], v[106:107], v[178:179]
	v_pk_fma_f32 v[174:175], v[190:191], v[102:103], v[174:175]
	v_pk_fma_f32 v[178:179], v[198:199], v[98:99], v[178:179]
	v_pk_fma_f32 v[174:175], v[214:215], v[94:95], v[174:175]
	v_pk_fma_f32 v[194:195], v[194:195], v[126:127], v[122:123]
	v_pk_fma_f32 v[190:191], v[190:191], v[130:131], v[118:119]
	v_pk_fma_f32 v[194:195], v[198:199], v[106:107], v[194:195]
	v_pk_fma_f32 v[190:191], v[214:215], v[102:103], v[190:191]
	v_pk_fma_f32 v[194:195], v[212:213], v[98:99], v[194:195]
	v_pk_fma_f32 v[190:191], v[216:217], v[94:95], v[190:191]
	v_pk_mul_f32 v[222:223], v[194:195], s[50:51]
	v_pk_mul_f32 v[242:243], v[178:179], s[50:51]
	v_pk_mul_f32 v[244:245], v[162:163], s[50:51]
	v_pk_mul_f32 v[246:247], v[146:147], s[50:51]
	v_exp_f32_e32 v222, v222
	v_exp_f32_e32 v223, v223
	v_exp_f32_e32 v242, v242
	v_exp_f32_e32 v243, v243
	v_exp_f32_e32 v244, v244
	v_exp_f32_e32 v245, v245
	v_exp_f32_e32 v246, v246
	v_exp_f32_e32 v247, v247
	v_pk_add_f32 v[222:223], v[222:223], 1.0 op_sel_hi:[1,0]
	v_pk_add_f32 v[242:243], v[242:243], 1.0 op_sel_hi:[1,0]
	v_pk_add_f32 v[244:245], v[244:245], 1.0 op_sel_hi:[1,0]
	v_pk_add_f32 v[246:247], v[246:247], 1.0 op_sel_hi:[1,0]
	v_rcp_f32_e32 v222, v222
	v_rcp_f32_e32 v223, v223
	v_rcp_f32_e32 v242, v242
	v_rcp_f32_e32 v243, v243
	v_rcp_f32_e32 v244, v244
	v_rcp_f32_e32 v245, v245
	v_rcp_f32_e32 v246, v246
	v_rcp_f32_e32 v247, v247
	v_pk_mul_f32 v[194:195], v[194:195], v[222:223]
	v_pk_mul_f32 v[178:179], v[178:179], v[242:243]
	v_pk_mul_f32 v[162:163], v[162:163], v[244:245]
	v_pk_mul_f32 v[146:147], v[146:147], v[246:247]
	v_pk_mul_f32 v[194:195], v[194:195], v[190:191]
	v_pk_mul_f32 v[178:179], v[178:179], v[174:175]
	v_pk_mul_f32 v[162:163], v[162:163], v[158:159]
	v_pk_mul_f32 v[146:147], v[146:147], v[138:139]
	v_cvt_pk_bf16_f32 v193, v194, v195
	v_cvt_pk_bf16_f32 v177, v178, v179
	v_cvt_pk_bf16_f32 v161, v162, v163
	v_cvt_pk_bf16_f32 v145, v146, v147
	v_mov_b32_dpp v198, v140 row_shr:1 row_mask:0xf bank_mask:0xf bound_ctrl:1
	v_mov_b32_dpp v199, v141 row_shr:1 row_mask:0xf bank_mask:0xf bound_ctrl:1
	v_mov_b32_dpp v214, v132 row_shr:1 row_mask:0xf bank_mask:0xf bound_ctrl:1
	v_mov_b32_dpp v215, v133 row_shr:1 row_mask:0xf bank_mask:0xf bound_ctrl:1
	v_mov_b32_dpp v212, v152 row_shr:1 row_mask:0xf bank_mask:0xf bound_ctrl:1
	v_mov_b32_dpp v213, v153 row_shr:1 row_mask:0xf bank_mask:0xf bound_ctrl:1
	v_mov_b32_dpp v216, v148 row_shr:1 row_mask:0xf bank_mask:0xf bound_ctrl:1
	v_mov_b32_dpp v217, v149 row_shr:1 row_mask:0xf bank_mask:0xf bound_ctrl:1
	v_pk_fma_f32 v[140:141], v[140:141], v[84:85], v[80:81]
	v_pk_fma_f32 v[132:133], v[132:133], v[88:89], v[76:77]
	v_pk_fma_f32 v[140:141], v[152:153], v[64:65], v[140:141]
	v_pk_fma_f32 v[132:133], v[148:149], v[60:61], v[132:133]
	v_pk_fma_f32 v[140:141], v[168:169], v[56:57], v[140:141]
	v_pk_fma_f32 v[132:133], v[164:165], v[52:53], v[132:133]
	v_pk_fma_f32 v[152:153], v[152:153], v[84:85], v[80:81]
	v_pk_fma_f32 v[148:149], v[148:149], v[88:89], v[76:77]
	v_pk_fma_f32 v[152:153], v[168:169], v[64:65], v[152:153]
	v_pk_fma_f32 v[148:149], v[164:165], v[60:61], v[148:149]
	v_pk_fma_f32 v[152:153], v[184:185], v[56:57], v[152:153]
	v_pk_fma_f32 v[148:149], v[180:181], v[52:53], v[148:149]
	v_pk_fma_f32 v[168:169], v[168:169], v[84:85], v[80:81]
	v_pk_fma_f32 v[164:165], v[164:165], v[88:89], v[76:77]
	v_pk_fma_f32 v[168:169], v[184:185], v[64:65], v[168:169]
	v_pk_fma_f32 v[164:165], v[180:181], v[60:61], v[164:165]
	v_pk_fma_f32 v[168:169], v[198:199], v[56:57], v[168:169]
	v_pk_fma_f32 v[164:165], v[214:215], v[52:53], v[164:165]
	v_pk_fma_f32 v[184:185], v[184:185], v[84:85], v[80:81]
	v_pk_fma_f32 v[180:181], v[180:181], v[88:89], v[76:77]
	v_pk_fma_f32 v[184:185], v[198:199], v[64:65], v[184:185]
	v_pk_fma_f32 v[180:181], v[214:215], v[60:61], v[180:181]
	v_pk_fma_f32 v[184:185], v[212:213], v[56:57], v[184:185]
	v_pk_fma_f32 v[180:181], v[216:217], v[52:53], v[180:181]
	v_pk_mul_f32 v[222:223], v[184:185], s[50:51]
	v_pk_mul_f32 v[242:243], v[168:169], s[50:51]
	v_pk_mul_f32 v[244:245], v[152:153], s[50:51]
	v_pk_mul_f32 v[246:247], v[140:141], s[50:51]
	v_exp_f32_e32 v222, v222
	v_exp_f32_e32 v223, v223
	v_exp_f32_e32 v242, v242
	v_exp_f32_e32 v243, v243
	v_exp_f32_e32 v244, v244
	v_exp_f32_e32 v245, v245
	v_exp_f32_e32 v246, v246
	v_exp_f32_e32 v247, v247
	v_pk_add_f32 v[222:223], v[222:223], 1.0 op_sel_hi:[1,0]
	v_pk_add_f32 v[242:243], v[242:243], 1.0 op_sel_hi:[1,0]
	v_pk_add_f32 v[244:245], v[244:245], 1.0 op_sel_hi:[1,0]
	v_pk_add_f32 v[246:247], v[246:247], 1.0 op_sel_hi:[1,0]
	v_rcp_f32_e32 v222, v222
	v_rcp_f32_e32 v223, v223
	v_rcp_f32_e32 v242, v242
	v_rcp_f32_e32 v243, v243
	v_rcp_f32_e32 v244, v244
	v_rcp_f32_e32 v245, v245
	v_rcp_f32_e32 v246, v246
	v_rcp_f32_e32 v247, v247
	v_pk_mul_f32 v[184:185], v[184:185], v[222:223]
	v_pk_mul_f32 v[168:169], v[168:169], v[242:243]
	v_pk_mul_f32 v[152:153], v[152:153], v[244:245]
	v_pk_mul_f32 v[140:141], v[140:141], v[246:247]
	v_pk_mul_f32 v[184:185], v[184:185], v[180:181]
	v_pk_mul_f32 v[168:169], v[168:169], v[164:165]
	v_pk_mul_f32 v[152:153], v[152:153], v[148:149]
	v_pk_mul_f32 v[140:141], v[140:141], v[132:133]
	v_cvt_pk_bf16_f32 v194, v184, v185
	v_cvt_pk_bf16_f32 v178, v168, v169
	v_cvt_pk_bf16_f32 v162, v152, v153
	v_cvt_pk_bf16_f32 v146, v140, v141
	v_mov_b32_dpp v198, v142 row_shr:1 row_mask:0xf bank_mask:0xf bound_ctrl:1
	v_mov_b32_dpp v199, v143 row_shr:1 row_mask:0xf bank_mask:0xf bound_ctrl:1
	v_mov_b32_dpp v214, v134 row_shr:1 row_mask:0xf bank_mask:0xf bound_ctrl:1
	v_mov_b32_dpp v215, v135 row_shr:1 row_mask:0xf bank_mask:0xf bound_ctrl:1
	v_mov_b32_dpp v212, v154 row_shr:1 row_mask:0xf bank_mask:0xf bound_ctrl:1
	v_mov_b32_dpp v213, v155 row_shr:1 row_mask:0xf bank_mask:0xf bound_ctrl:1
	v_mov_b32_dpp v216, v150 row_shr:1 row_mask:0xf bank_mask:0xf bound_ctrl:1
	v_mov_b32_dpp v217, v151 row_shr:1 row_mask:0xf bank_mask:0xf bound_ctrl:1
	v_pk_fma_f32 v[142:143], v[142:143], v[86:87], v[82:83]
	v_pk_fma_f32 v[134:135], v[134:135], v[90:91], v[78:79]
	v_pk_fma_f32 v[142:143], v[154:155], v[66:67], v[142:143]
	v_pk_fma_f32 v[134:135], v[150:151], v[62:63], v[134:135]
	v_pk_fma_f32 v[142:143], v[170:171], v[58:59], v[142:143]
	v_pk_fma_f32 v[134:135], v[166:167], v[54:55], v[134:135]
	v_pk_fma_f32 v[154:155], v[154:155], v[86:87], v[82:83]
	v_pk_fma_f32 v[150:151], v[150:151], v[90:91], v[78:79]
	v_pk_fma_f32 v[154:155], v[170:171], v[66:67], v[154:155]
	v_pk_fma_f32 v[150:151], v[166:167], v[62:63], v[150:151]
	v_pk_fma_f32 v[154:155], v[186:187], v[58:59], v[154:155]
	v_pk_fma_f32 v[150:151], v[182:183], v[54:55], v[150:151]
	v_pk_fma_f32 v[170:171], v[170:171], v[86:87], v[82:83]
	v_pk_fma_f32 v[166:167], v[166:167], v[90:91], v[78:79]
	v_pk_fma_f32 v[170:171], v[186:187], v[66:67], v[170:171]
	v_pk_fma_f32 v[166:167], v[182:183], v[62:63], v[166:167]
	v_pk_fma_f32 v[170:171], v[198:199], v[58:59], v[170:171]
	v_pk_fma_f32 v[166:167], v[214:215], v[54:55], v[166:167]
	v_pk_fma_f32 v[186:187], v[186:187], v[86:87], v[82:83]
	v_pk_fma_f32 v[182:183], v[182:183], v[90:91], v[78:79]
	v_pk_fma_f32 v[186:187], v[198:199], v[66:67], v[186:187]
	v_pk_fma_f32 v[182:183], v[214:215], v[62:63], v[182:183]
	v_pk_fma_f32 v[186:187], v[212:213], v[58:59], v[186:187]
	v_pk_fma_f32 v[182:183], v[216:217], v[54:55], v[182:183]
	v_pk_mul_f32 v[222:223], v[186:187], s[50:51]
	v_pk_mul_f32 v[242:243], v[170:171], s[50:51]
	v_pk_mul_f32 v[244:245], v[154:155], s[50:51]
	v_pk_mul_f32 v[246:247], v[142:143], s[50:51]
	v_exp_f32_e32 v222, v222
	v_exp_f32_e32 v223, v223
	v_exp_f32_e32 v242, v242
	v_exp_f32_e32 v243, v243
	v_exp_f32_e32 v244, v244
	v_exp_f32_e32 v245, v245
	v_exp_f32_e32 v246, v246
	v_exp_f32_e32 v247, v247
	v_pk_add_f32 v[222:223], v[222:223], 1.0 op_sel_hi:[1,0]
	v_pk_add_f32 v[242:243], v[242:243], 1.0 op_sel_hi:[1,0]
	v_pk_add_f32 v[244:245], v[244:245], 1.0 op_sel_hi:[1,0]
	v_pk_add_f32 v[246:247], v[246:247], 1.0 op_sel_hi:[1,0]
	v_rcp_f32_e32 v222, v222
	v_rcp_f32_e32 v223, v223
	v_rcp_f32_e32 v242, v242
	v_rcp_f32_e32 v243, v243
	v_rcp_f32_e32 v244, v244
	v_rcp_f32_e32 v245, v245
	v_rcp_f32_e32 v246, v246
	v_rcp_f32_e32 v247, v247
	v_pk_mul_f32 v[186:187], v[186:187], v[222:223]
	v_pk_mul_f32 v[170:171], v[170:171], v[242:243]
	v_pk_mul_f32 v[154:155], v[154:155], v[244:245]
	v_pk_mul_f32 v[142:143], v[142:143], v[246:247]
	v_pk_mul_f32 v[186:187], v[186:187], v[182:183]
	v_pk_mul_f32 v[170:171], v[170:171], v[166:167]
	v_pk_mul_f32 v[154:155], v[154:155], v[150:151]
	v_pk_mul_f32 v[142:143], v[142:143], v[134:135]
	v_cvt_pk_bf16_f32 v195, v186, v187
	v_cvt_pk_bf16_f32 v179, v170, v171
	v_cvt_pk_bf16_f32 v163, v154, v155
	v_cvt_pk_bf16_f32 v147, v142, v143
	s_mov_b64 s[20:21], s[82:83]
	global_store_dwordx4 v240, v[192:195], s[20:21]
	s_add_u32 s20, s82, 0x1600
	s_addc_u32 s21, s83, 0
	global_store_dwordx4 v240, v[176:179], s[20:21]
	s_add_u32 s20, s82, 0x2c00
	s_addc_u32 s21, s83, 0
	global_store_dwordx4 v240, v[160:163], s[20:21]
	s_add_u32 s20, s82, 0x4200
	s_addc_u32 s21, s83, 0
	global_store_dwordx4 v240, v[144:147], s[20:21]
	v_mov_b32_dpp v198, v16 row_shr:1 row_mask:0xf bank_mask:0xf bound_ctrl:1
	v_mov_b32_dpp v199, v17 row_shr:1 row_mask:0xf bank_mask:0xf bound_ctrl:1
	v_mov_b32_dpp v214, v8 row_shr:1 row_mask:0xf bank_mask:0xf bound_ctrl:1
	v_mov_b32_dpp v215, v9 row_shr:1 row_mask:0xf bank_mask:0xf bound_ctrl:1
	v_mov_b32_dpp v212, v32 row_shr:1 row_mask:0xf bank_mask:0xf bound_ctrl:1
	v_mov_b32_dpp v213, v33 row_shr:1 row_mask:0xf bank_mask:0xf bound_ctrl:1
	v_mov_b32_dpp v216, v28 row_shr:1 row_mask:0xf bank_mask:0xf bound_ctrl:1
	v_mov_b32_dpp v217, v29 row_shr:1 row_mask:0xf bank_mask:0xf bound_ctrl:1
	v_pk_fma_f32 v[16:17], v[16:17], v[124:125], v[120:121]
	v_pk_fma_f32 v[8:9], v[8:9], v[128:129], v[116:117]
	v_pk_fma_f32 v[16:17], v[32:33], v[104:105], v[16:17]
	v_pk_fma_f32 v[8:9], v[28:29], v[100:101], v[8:9]
	v_pk_fma_f32 v[16:17], v[48:49], v[96:97], v[16:17]
	v_pk_fma_f32 v[8:9], v[44:45], v[92:93], v[8:9]
	v_pk_fma_f32 v[32:33], v[32:33], v[124:125], v[120:121]
	v_pk_fma_f32 v[28:29], v[28:29], v[128:129], v[116:117]
	v_pk_fma_f32 v[32:33], v[48:49], v[104:105], v[32:33]
	v_pk_fma_f32 v[28:29], v[44:45], v[100:101], v[28:29]
	v_pk_fma_f32 v[32:33], v[112:113], v[96:97], v[32:33]
	v_pk_fma_f32 v[28:29], v[108:109], v[92:93], v[28:29]
	v_pk_fma_f32 v[48:49], v[48:49], v[124:125], v[120:121]
	v_pk_fma_f32 v[44:45], v[44:45], v[128:129], v[116:117]
	v_pk_fma_f32 v[48:49], v[112:113], v[104:105], v[48:49]
	v_pk_fma_f32 v[44:45], v[108:109], v[100:101], v[44:45]
	v_pk_fma_f32 v[48:49], v[198:199], v[96:97], v[48:49]
	v_pk_fma_f32 v[44:45], v[214:215], v[92:93], v[44:45]
	v_pk_fma_f32 v[112:113], v[112:113], v[124:125], v[120:121]
	v_pk_fma_f32 v[108:109], v[108:109], v[128:129], v[116:117]
	v_pk_fma_f32 v[112:113], v[198:199], v[104:105], v[112:113]
	v_pk_fma_f32 v[108:109], v[214:215], v[100:101], v[108:109]
	v_pk_fma_f32 v[112:113], v[212:213], v[96:97], v[112:113]
	v_pk_fma_f32 v[108:109], v[216:217], v[92:93], v[108:109]
	v_pk_mul_f32 v[222:223], v[112:113], s[50:51]
	v_pk_mul_f32 v[242:243], v[48:49], s[50:51]
	v_pk_mul_f32 v[244:245], v[32:33], s[50:51]
	v_pk_mul_f32 v[246:247], v[16:17], s[50:51]
	v_exp_f32_e32 v222, v222
	v_exp_f32_e32 v223, v223
	v_exp_f32_e32 v242, v242
	v_exp_f32_e32 v243, v243
	v_exp_f32_e32 v244, v244
	v_exp_f32_e32 v245, v245
	v_exp_f32_e32 v246, v246
	v_exp_f32_e32 v247, v247
	v_pk_add_f32 v[222:223], v[222:223], 1.0 op_sel_hi:[1,0]
	v_pk_add_f32 v[242:243], v[242:243], 1.0 op_sel_hi:[1,0]
	v_pk_add_f32 v[244:245], v[244:245], 1.0 op_sel_hi:[1,0]
	v_pk_add_f32 v[246:247], v[246:247], 1.0 op_sel_hi:[1,0]
	v_rcp_f32_e32 v222, v222
	v_rcp_f32_e32 v223, v223
	v_rcp_f32_e32 v242, v242
	v_rcp_f32_e32 v243, v243
	v_rcp_f32_e32 v244, v244
	v_rcp_f32_e32 v245, v245
	v_rcp_f32_e32 v246, v246
	v_rcp_f32_e32 v247, v247
	v_pk_mul_f32 v[112:113], v[112:113], v[222:223]
	v_pk_mul_f32 v[48:49], v[48:49], v[242:243]
	v_pk_mul_f32 v[32:33], v[32:33], v[244:245]
	v_pk_mul_f32 v[16:17], v[16:17], v[246:247]
	v_pk_mul_f32 v[112:113], v[112:113], v[108:109]
	v_pk_mul_f32 v[48:49], v[48:49], v[44:45]
	v_pk_mul_f32 v[32:33], v[32:33], v[28:29]
	v_pk_mul_f32 v[16:17], v[16:17], v[8:9]
	v_cvt_pk_bf16_f32 v112, v112, v113
	v_cvt_pk_bf16_f32 v48, v48, v49
	v_cvt_pk_bf16_f32 v32, v32, v33
	v_cvt_pk_bf16_f32 v16, v16, v17
	v_mov_b32_dpp v198, v18 row_shr:1 row_mask:0xf bank_mask:0xf bound_ctrl:1
	v_mov_b32_dpp v199, v19 row_shr:1 row_mask:0xf bank_mask:0xf bound_ctrl:1
	v_mov_b32_dpp v214, v10 row_shr:1 row_mask:0xf bank_mask:0xf bound_ctrl:1
	v_mov_b32_dpp v215, v11 row_shr:1 row_mask:0xf bank_mask:0xf bound_ctrl:1
	v_mov_b32_dpp v212, v34 row_shr:1 row_mask:0xf bank_mask:0xf bound_ctrl:1
	v_mov_b32_dpp v213, v35 row_shr:1 row_mask:0xf bank_mask:0xf bound_ctrl:1
	v_mov_b32_dpp v216, v30 row_shr:1 row_mask:0xf bank_mask:0xf bound_ctrl:1
	v_mov_b32_dpp v217, v31 row_shr:1 row_mask:0xf bank_mask:0xf bound_ctrl:1
	v_pk_fma_f32 v[18:19], v[18:19], v[126:127], v[122:123]
	v_pk_fma_f32 v[10:11], v[10:11], v[130:131], v[118:119]
	v_pk_fma_f32 v[18:19], v[34:35], v[106:107], v[18:19]
	v_pk_fma_f32 v[10:11], v[30:31], v[102:103], v[10:11]
	v_pk_fma_f32 v[18:19], v[50:51], v[98:99], v[18:19]
	v_pk_fma_f32 v[10:11], v[46:47], v[94:95], v[10:11]
	v_pk_fma_f32 v[34:35], v[34:35], v[126:127], v[122:123]
	v_pk_fma_f32 v[30:31], v[30:31], v[130:131], v[118:119]
	v_pk_fma_f32 v[34:35], v[50:51], v[106:107], v[34:35]
	v_pk_fma_f32 v[30:31], v[46:47], v[102:103], v[30:31]
	v_pk_fma_f32 v[34:35], v[114:115], v[98:99], v[34:35]
	v_pk_fma_f32 v[30:31], v[110:111], v[94:95], v[30:31]
	v_pk_fma_f32 v[50:51], v[50:51], v[126:127], v[122:123]
	v_pk_fma_f32 v[46:47], v[46:47], v[130:131], v[118:119]
	v_pk_fma_f32 v[50:51], v[114:115], v[106:107], v[50:51]
	v_pk_fma_f32 v[46:47], v[110:111], v[102:103], v[46:47]
	v_pk_fma_f32 v[50:51], v[198:199], v[98:99], v[50:51]
	v_pk_fma_f32 v[46:47], v[214:215], v[94:95], v[46:47]
	v_pk_fma_f32 v[114:115], v[114:115], v[126:127], v[122:123]
	v_pk_fma_f32 v[110:111], v[110:111], v[130:131], v[118:119]
	v_pk_fma_f32 v[114:115], v[198:199], v[106:107], v[114:115]
	v_pk_fma_f32 v[110:111], v[214:215], v[102:103], v[110:111]
	v_pk_fma_f32 v[114:115], v[212:213], v[98:99], v[114:115]
	v_pk_fma_f32 v[110:111], v[216:217], v[94:95], v[110:111]
	v_pk_mul_f32 v[222:223], v[114:115], s[50:51]
	v_pk_mul_f32 v[242:243], v[50:51], s[50:51]
	v_pk_mul_f32 v[244:245], v[34:35], s[50:51]
	v_pk_mul_f32 v[246:247], v[18:19], s[50:51]
	v_exp_f32_e32 v222, v222
	v_exp_f32_e32 v223, v223
	v_exp_f32_e32 v242, v242
	v_exp_f32_e32 v243, v243
	v_exp_f32_e32 v244, v244
	v_exp_f32_e32 v245, v245
	v_exp_f32_e32 v246, v246
	v_exp_f32_e32 v247, v247
	v_pk_add_f32 v[222:223], v[222:223], 1.0 op_sel_hi:[1,0]
	v_pk_add_f32 v[242:243], v[242:243], 1.0 op_sel_hi:[1,0]
	v_pk_add_f32 v[244:245], v[244:245], 1.0 op_sel_hi:[1,0]
	v_pk_add_f32 v[246:247], v[246:247], 1.0 op_sel_hi:[1,0]
	v_rcp_f32_e32 v222, v222
	v_rcp_f32_e32 v223, v223
	v_rcp_f32_e32 v242, v242
	v_rcp_f32_e32 v243, v243
	v_rcp_f32_e32 v244, v244
	v_rcp_f32_e32 v245, v245
	v_rcp_f32_e32 v246, v246
	v_rcp_f32_e32 v247, v247
	v_pk_mul_f32 v[114:115], v[114:115], v[222:223]
	v_pk_mul_f32 v[50:51], v[50:51], v[242:243]
	v_pk_mul_f32 v[34:35], v[34:35], v[244:245]
	v_pk_mul_f32 v[18:19], v[18:19], v[246:247]
	v_pk_mul_f32 v[114:115], v[114:115], v[110:111]
	v_pk_mul_f32 v[50:51], v[50:51], v[46:47]
	v_pk_mul_f32 v[34:35], v[34:35], v[30:31]
	v_pk_mul_f32 v[18:19], v[18:19], v[10:11]
	v_cvt_pk_bf16_f32 v113, v114, v115
	v_cvt_pk_bf16_f32 v49, v50, v51
	v_cvt_pk_bf16_f32 v33, v34, v35
	v_cvt_pk_bf16_f32 v17, v18, v19
	v_mov_b32_dpp v198, v12 row_shr:1 row_mask:0xf bank_mask:0xf bound_ctrl:1
	v_mov_b32_dpp v199, v13 row_shr:1 row_mask:0xf bank_mask:0xf bound_ctrl:1
	v_mov_b32_dpp v214, v4 row_shr:1 row_mask:0xf bank_mask:0xf bound_ctrl:1
	v_mov_b32_dpp v215, v5 row_shr:1 row_mask:0xf bank_mask:0xf bound_ctrl:1
	v_mov_b32_dpp v212, v24 row_shr:1 row_mask:0xf bank_mask:0xf bound_ctrl:1
	v_mov_b32_dpp v213, v25 row_shr:1 row_mask:0xf bank_mask:0xf bound_ctrl:1
	v_mov_b32_dpp v216, v20 row_shr:1 row_mask:0xf bank_mask:0xf bound_ctrl:1
	v_mov_b32_dpp v217, v21 row_shr:1 row_mask:0xf bank_mask:0xf bound_ctrl:1
	v_pk_fma_f32 v[12:13], v[12:13], v[84:85], v[80:81]
	v_pk_fma_f32 v[4:5], v[4:5], v[88:89], v[76:77]
	v_pk_fma_f32 v[12:13], v[24:25], v[64:65], v[12:13]
	v_pk_fma_f32 v[4:5], v[20:21], v[60:61], v[4:5]
	v_pk_fma_f32 v[12:13], v[40:41], v[56:57], v[12:13]
	v_pk_fma_f32 v[4:5], v[36:37], v[52:53], v[4:5]
	v_pk_fma_f32 v[24:25], v[24:25], v[84:85], v[80:81]
	v_pk_fma_f32 v[20:21], v[20:21], v[88:89], v[76:77]
	v_pk_fma_f32 v[24:25], v[40:41], v[64:65], v[24:25]
	v_pk_fma_f32 v[20:21], v[36:37], v[60:61], v[20:21]
	v_pk_fma_f32 v[24:25], v[72:73], v[56:57], v[24:25]
	v_pk_fma_f32 v[20:21], v[68:69], v[52:53], v[20:21]
	v_pk_fma_f32 v[40:41], v[40:41], v[84:85], v[80:81]
	v_pk_fma_f32 v[36:37], v[36:37], v[88:89], v[76:77]
	v_pk_fma_f32 v[40:41], v[72:73], v[64:65], v[40:41]
	v_pk_fma_f32 v[36:37], v[68:69], v[60:61], v[36:37]
	v_pk_fma_f32 v[40:41], v[198:199], v[56:57], v[40:41]
	v_pk_fma_f32 v[36:37], v[214:215], v[52:53], v[36:37]
	v_pk_fma_f32 v[72:73], v[72:73], v[84:85], v[80:81]
	v_pk_fma_f32 v[68:69], v[68:69], v[88:89], v[76:77]
	v_pk_fma_f32 v[72:73], v[198:199], v[64:65], v[72:73]
	v_pk_fma_f32 v[68:69], v[214:215], v[60:61], v[68:69]
	v_pk_fma_f32 v[72:73], v[212:213], v[56:57], v[72:73]
	v_pk_fma_f32 v[68:69], v[216:217], v[52:53], v[68:69]
	v_pk_mul_f32 v[222:223], v[72:73], s[50:51]
	v_pk_mul_f32 v[242:243], v[40:41], s[50:51]
	v_pk_mul_f32 v[244:245], v[24:25], s[50:51]
	v_pk_mul_f32 v[246:247], v[12:13], s[50:51]
	v_exp_f32_e32 v222, v222
	v_exp_f32_e32 v223, v223
	v_exp_f32_e32 v242, v242
	v_exp_f32_e32 v243, v243
	v_exp_f32_e32 v244, v244
	v_exp_f32_e32 v245, v245
	v_exp_f32_e32 v246, v246
	v_exp_f32_e32 v247, v247
	v_pk_add_f32 v[222:223], v[222:223], 1.0 op_sel_hi:[1,0]
	v_pk_add_f32 v[242:243], v[242:243], 1.0 op_sel_hi:[1,0]
	v_pk_add_f32 v[244:245], v[244:245], 1.0 op_sel_hi:[1,0]
	v_pk_add_f32 v[246:247], v[246:247], 1.0 op_sel_hi:[1,0]
	v_rcp_f32_e32 v222, v222
	v_rcp_f32_e32 v223, v223
	v_rcp_f32_e32 v242, v242
	v_rcp_f32_e32 v243, v243
	v_rcp_f32_e32 v244, v244
	v_rcp_f32_e32 v245, v245
	v_rcp_f32_e32 v246, v246
	v_rcp_f32_e32 v247, v247
	v_pk_mul_f32 v[72:73], v[72:73], v[222:223]
	v_pk_mul_f32 v[40:41], v[40:41], v[242:243]
	v_pk_mul_f32 v[24:25], v[24:25], v[244:245]
	v_pk_mul_f32 v[12:13], v[12:13], v[246:247]
	v_pk_mul_f32 v[72:73], v[72:73], v[68:69]
	v_pk_mul_f32 v[40:41], v[40:41], v[36:37]
	v_pk_mul_f32 v[24:25], v[24:25], v[20:21]
	v_pk_mul_f32 v[12:13], v[12:13], v[4:5]
	v_cvt_pk_bf16_f32 v114, v72, v73
	v_cvt_pk_bf16_f32 v50, v40, v41
	v_cvt_pk_bf16_f32 v34, v24, v25
	v_cvt_pk_bf16_f32 v18, v12, v13
	v_mov_b32_dpp v198, v14 row_shr:1 row_mask:0xf bank_mask:0xf bound_ctrl:1
	v_mov_b32_dpp v199, v15 row_shr:1 row_mask:0xf bank_mask:0xf bound_ctrl:1
	v_mov_b32_dpp v214, v6 row_shr:1 row_mask:0xf bank_mask:0xf bound_ctrl:1
	v_mov_b32_dpp v215, v7 row_shr:1 row_mask:0xf bank_mask:0xf bound_ctrl:1
	v_mov_b32_dpp v212, v26 row_shr:1 row_mask:0xf bank_mask:0xf bound_ctrl:1
	v_mov_b32_dpp v213, v27 row_shr:1 row_mask:0xf bank_mask:0xf bound_ctrl:1
	v_mov_b32_dpp v216, v22 row_shr:1 row_mask:0xf bank_mask:0xf bound_ctrl:1
	v_mov_b32_dpp v217, v23 row_shr:1 row_mask:0xf bank_mask:0xf bound_ctrl:1
	v_pk_fma_f32 v[14:15], v[14:15], v[86:87], v[82:83]
	v_pk_fma_f32 v[6:7], v[6:7], v[90:91], v[78:79]
	v_pk_fma_f32 v[14:15], v[26:27], v[66:67], v[14:15]
	v_pk_fma_f32 v[6:7], v[22:23], v[62:63], v[6:7]
	v_pk_fma_f32 v[14:15], v[42:43], v[58:59], v[14:15]
	v_pk_fma_f32 v[6:7], v[38:39], v[54:55], v[6:7]
	v_pk_fma_f32 v[26:27], v[26:27], v[86:87], v[82:83]
	v_pk_fma_f32 v[22:23], v[22:23], v[90:91], v[78:79]
	v_pk_fma_f32 v[26:27], v[42:43], v[66:67], v[26:27]
	v_pk_fma_f32 v[22:23], v[38:39], v[62:63], v[22:23]
	v_pk_fma_f32 v[26:27], v[74:75], v[58:59], v[26:27]
	v_pk_fma_f32 v[22:23], v[70:71], v[54:55], v[22:23]
	v_pk_fma_f32 v[42:43], v[42:43], v[86:87], v[82:83]
	v_pk_fma_f32 v[38:39], v[38:39], v[90:91], v[78:79]
	v_pk_fma_f32 v[42:43], v[74:75], v[66:67], v[42:43]
	v_pk_fma_f32 v[38:39], v[70:71], v[62:63], v[38:39]
	v_pk_fma_f32 v[42:43], v[198:199], v[58:59], v[42:43]
	v_pk_fma_f32 v[38:39], v[214:215], v[54:55], v[38:39]
	v_pk_fma_f32 v[74:75], v[74:75], v[86:87], v[82:83]
	v_pk_fma_f32 v[70:71], v[70:71], v[90:91], v[78:79]
	v_pk_fma_f32 v[74:75], v[198:199], v[66:67], v[74:75]
	v_pk_fma_f32 v[70:71], v[214:215], v[62:63], v[70:71]
	v_pk_fma_f32 v[74:75], v[212:213], v[58:59], v[74:75]
	v_pk_fma_f32 v[70:71], v[216:217], v[54:55], v[70:71]
	v_pk_mul_f32 v[222:223], v[74:75], s[50:51]
	v_pk_mul_f32 v[242:243], v[42:43], s[50:51]
	v_pk_mul_f32 v[244:245], v[26:27], s[50:51]
	v_pk_mul_f32 v[246:247], v[14:15], s[50:51]
	v_exp_f32_e32 v222, v222
	v_exp_f32_e32 v223, v223
	v_exp_f32_e32 v242, v242
	v_exp_f32_e32 v243, v243
	v_exp_f32_e32 v244, v244
	v_exp_f32_e32 v245, v245
	v_exp_f32_e32 v246, v246
	v_exp_f32_e32 v247, v247
	v_pk_add_f32 v[222:223], v[222:223], 1.0 op_sel_hi:[1,0]
	v_pk_add_f32 v[242:243], v[242:243], 1.0 op_sel_hi:[1,0]
	v_pk_add_f32 v[244:245], v[244:245], 1.0 op_sel_hi:[1,0]
	v_pk_add_f32 v[246:247], v[246:247], 1.0 op_sel_hi:[1,0]
	v_rcp_f32_e32 v222, v222
	v_rcp_f32_e32 v223, v223
	v_rcp_f32_e32 v242, v242
	v_rcp_f32_e32 v243, v243
	v_rcp_f32_e32 v244, v244
	v_rcp_f32_e32 v245, v245
	v_rcp_f32_e32 v246, v246
	v_rcp_f32_e32 v247, v247
	v_pk_mul_f32 v[74:75], v[74:75], v[222:223]
	v_pk_mul_f32 v[42:43], v[42:43], v[242:243]
	v_pk_mul_f32 v[26:27], v[26:27], v[244:245]
	v_pk_mul_f32 v[14:15], v[14:15], v[246:247]
	v_pk_mul_f32 v[74:75], v[74:75], v[70:71]
	v_pk_mul_f32 v[42:43], v[42:43], v[38:39]
	v_pk_mul_f32 v[26:27], v[26:27], v[22:23]
	v_pk_mul_f32 v[14:15], v[14:15], v[6:7]
	v_cvt_pk_bf16_f32 v115, v74, v75
	v_cvt_pk_bf16_f32 v51, v42, v43
	v_cvt_pk_bf16_f32 v35, v26, v27
	v_cvt_pk_bf16_f32 v19, v14, v15
	s_add_u32 s20, s82, 0xb0000
	s_addc_u32 s21, s83, 0
	global_store_dwordx4 v240, v[112:115], s[20:21]
	s_add_u32 s20, s82, 0xb1600
	s_addc_u32 s21, s83, 0
	global_store_dwordx4 v240, v[48:51], s[20:21]
	s_add_u32 s20, s82, 0xb2c00
	s_addc_u32 s21, s83, 0
	global_store_dwordx4 v240, v[32:35], s[20:21]
	s_add_u32 s20, s82, 0xb4200
	s_addc_u32 s21, s83, 0
	global_store_dwordx4 v240, v[16:19], s[20:21]
	s_mov_b64 s[50:51], -1
	s_branch .LBB0_76

.LBB0_136:
	s_add_u32 s23, s48, 0xfffc0080
	s_addc_u32 s24, s49, -1
	s_add_i32 s25, 0, 0x10000
	v_add_u32_e32 v145, s25, v143
	ds_read_b128 v[146:149], v145
	ds_read_b128 v[150:153], v145 offset:1024
	ds_read_b128 v[154:157], v145 offset:2048
	ds_read_b128 v[158:161], v145 offset:3072
	s_cmp_eq_u32 s22, 12
	s_cselect_b32 s53, s45, s24
	s_cselect_b32 s52, s44, s23
	s_cselect_b32 s51, s47, s21
	s_cselect_b32 s50, s46, s20
	v_lshl_add_u64 v[194:195], s[48:49], 0, v[138:139]
	s_add_i32 m0, s54, 0xc000
	ds_read_b128 v[162:165], v144
	ds_read_b128 v[166:169], v144 offset:1024
	ds_read_b128 v[170:173], v144 offset:2048
	ds_read_b128 v[174:177], v144 offset:3072
	ds_read_b128 v[178:181], v144 offset:4096
	ds_read_b128 v[182:185], v144 offset:5120
	ds_read_b128 v[186:189], v144 offset:6144
	ds_read_b128 v[190:193], v144 offset:7168
	global_load_lds_dwordx4 v[194:195], off
	v_lshl_add_u64 v[194:195], s[48:49], 0, v[140:141]
	s_add_i32 m0, s54, 0xe000
	s_nop 0
	global_load_lds_dwordx4 v[194:195], off
	s_waitcnt lgkmcnt(8)
	s_barrier
	s_waitcnt lgkmcnt(0)
	v_mfma_f32_16x16x32_bf16 v[128:131], v[146:149], v[162:165], v[128:131]
	v_mfma_f32_16x16x32_bf16 v[124:127], v[154:157], v[162:165], v[124:127]
	v_mfma_f32_16x16x32_bf16 v[120:123], v[146:149], v[170:173], v[120:123]
	v_mfma_f32_16x16x32_bf16 v[116:119], v[154:157], v[170:173], v[116:119]
	v_mfma_f32_16x16x32_bf16 v[104:107], v[146:149], v[178:181], v[104:107]
	v_mfma_f32_16x16x32_bf16 v[100:103], v[154:157], v[178:181], v[100:103]
	v_mfma_f32_16x16x32_bf16 v[88:91], v[146:149], v[186:189], v[88:91]
	v_mfma_f32_16x16x32_bf16 v[84:87], v[154:157], v[186:189], v[84:87]
	v_mfma_f32_16x16x32_bf16 v[128:131], v[150:153], v[166:169], v[128:131]
	v_mfma_f32_16x16x32_bf16 v[124:127], v[158:161], v[166:169], v[124:127]
	v_mfma_f32_16x16x32_bf16 v[120:123], v[150:153], v[174:177], v[120:123]
	v_mfma_f32_16x16x32_bf16 v[116:119], v[158:161], v[174:177], v[116:119]
	v_mfma_f32_16x16x32_bf16 v[104:107], v[150:153], v[182:185], v[104:107]
	v_mfma_f32_16x16x32_bf16 v[100:103], v[158:161], v[182:185], v[100:103]
	v_mfma_f32_16x16x32_bf16 v[88:91], v[150:153], v[190:193], v[88:91]
	v_mfma_f32_16x16x32_bf16 v[84:87], v[158:161], v[190:193], v[84:87]
	s_barrier
	s_add_i32 s23, 0, 0x14000
	s_add_i32 s24, s25, s37
	v_add_u32_e32 v145, s23, v143
	v_lshl_add_u64 v[194:195], s[50:51], 0, v[132:133]
	s_mov_b32 m0, s24
	ds_read_b128 v[202:205], v145
	ds_read_b128 v[206:209], v145 offset:1024
	ds_read_b128 v[210:213], v145 offset:2048
	ds_read_b128 v[214:217], v145 offset:3072
	global_load_lds_dwordx4 v[194:195], off
	v_lshl_add_u64 v[198:199], s[50:51], 0, v[136:137]
	s_add_i32 m0, s24, 0x2000
	s_nop 0
	global_load_lds_dwordx4 v[198:199], off
	s_barrier
	s_waitcnt lgkmcnt(0)
	v_mfma_f32_16x16x32_bf16 v[112:115], v[202:205], v[162:165], v[112:115]
	v_mfma_f32_16x16x32_bf16 v[108:111], v[210:213], v[162:165], v[108:111]
	v_mfma_f32_16x16x32_bf16 v[96:99], v[202:205], v[170:173], v[96:99]
	v_mfma_f32_16x16x32_bf16 v[92:95], v[210:213], v[170:173], v[92:95]
	v_mfma_f32_16x16x32_bf16 v[80:83], v[202:205], v[178:181], v[80:83]
	v_mfma_f32_16x16x32_bf16 v[76:79], v[210:213], v[178:181], v[76:79]
	v_mfma_f32_16x16x32_bf16 v[72:75], v[202:205], v[186:189], v[72:75]
	v_mfma_f32_16x16x32_bf16 v[68:71], v[210:213], v[186:189], v[68:71]
	v_mfma_f32_16x16x32_bf16 v[112:115], v[206:209], v[166:169], v[112:115]
	v_mfma_f32_16x16x32_bf16 v[108:111], v[214:217], v[166:169], v[108:111]
	v_mfma_f32_16x16x32_bf16 v[96:99], v[206:209], v[174:177], v[96:99]
	v_mfma_f32_16x16x32_bf16 v[92:95], v[214:217], v[174:177], v[92:95]
	v_mfma_f32_16x16x32_bf16 v[80:83], v[206:209], v[182:185], v[80:83]
	v_mfma_f32_16x16x32_bf16 v[76:79], v[214:217], v[182:185], v[76:79]
	v_mfma_f32_16x16x32_bf16 v[72:75], v[206:209], v[190:193], v[72:75]
	v_mfma_f32_16x16x32_bf16 v[68:71], v[214:217], v[190:193], v[68:71]
	s_mov_b32 m0, s54
	v_lshl_add_u64 v[222:223], s[52:53], 0, v[0:1]
	s_barrier
	ds_read_b128 v[162:165], v144 offset:16384
	ds_read_b128 v[166:169], v144 offset:17408
	ds_read_b128 v[170:173], v144 offset:18432
	ds_read_b128 v[174:177], v144 offset:19456
	ds_read_b128 v[178:181], v144 offset:20480
	ds_read_b128 v[182:185], v144 offset:21504
	ds_read_b128 v[186:189], v144 offset:22528
	ds_read_b128 v[190:193], v144 offset:23552
	global_load_lds_dwordx4 v[222:223], off
	v_lshl_add_u64 v[236:237], s[52:53], 0, v[134:135]
	s_mov_b32 m0, s55
	s_nop 0
	global_load_lds_dwordx4 v[236:237], off
	s_barrier
	s_waitcnt lgkmcnt(0)
	v_mfma_f32_16x16x32_bf16 v[64:67], v[146:149], v[162:165], v[64:67]
	v_mfma_f32_16x16x32_bf16 v[60:63], v[154:157], v[162:165], v[60:63]
	v_mfma_f32_16x16x32_bf16 v[56:59], v[146:149], v[170:173], v[56:59]
	v_mfma_f32_16x16x32_bf16 v[52:55], v[154:157], v[170:173], v[52:55]
	v_mfma_f32_16x16x32_bf16 v[40:43], v[146:149], v[178:181], v[40:43]
	v_mfma_f32_16x16x32_bf16 v[36:39], v[154:157], v[178:181], v[36:39]
	v_mfma_f32_16x16x32_bf16 v[24:27], v[146:149], v[186:189], v[24:27]
	v_mfma_f32_16x16x32_bf16 v[16:19], v[154:157], v[186:189], v[16:19]
	v_mfma_f32_16x16x32_bf16 v[64:67], v[150:153], v[166:169], v[64:67]
	v_mfma_f32_16x16x32_bf16 v[60:63], v[158:161], v[166:169], v[60:63]
	v_mfma_f32_16x16x32_bf16 v[56:59], v[150:153], v[174:177], v[56:59]
	v_mfma_f32_16x16x32_bf16 v[52:55], v[158:161], v[174:177], v[52:55]
	v_mfma_f32_16x16x32_bf16 v[40:43], v[150:153], v[182:185], v[40:43]
	v_mfma_f32_16x16x32_bf16 v[36:39], v[158:161], v[182:185], v[36:39]
	v_mfma_f32_16x16x32_bf16 v[24:27], v[150:153], v[190:193], v[24:27]
	v_mfma_f32_16x16x32_bf16 v[16:19], v[158:161], v[190:193], v[16:19]
	s_barrier
	s_add_u32 s24, s50, 0x40000
	s_addc_u32 s25, s51, 0
	s_add_i32 s23, s23, s37
	v_lshl_add_u64 v[146:147], s[24:25], 0, v[132:133]
	s_mov_b32 m0, s23
	s_nop 0
	global_load_lds_dwordx4 v[146:147], off
	v_lshl_add_u64 v[146:147], s[24:25], 0, v[136:137]
	s_add_i32 m0, s23, 0x2000
	s_nop 0
	global_load_lds_dwordx4 v[146:147], off
	s_waitcnt vmcnt(6)
	s_barrier
	v_mfma_f32_16x16x32_bf16 v[48:51], v[202:205], v[162:165], v[48:51]
	v_mfma_f32_16x16x32_bf16 v[44:47], v[210:213], v[162:165], v[44:47]
	v_mfma_f32_16x16x32_bf16 v[32:35], v[202:205], v[170:173], v[32:35]
	v_mfma_f32_16x16x32_bf16 v[28:31], v[210:213], v[170:173], v[28:31]
	v_mfma_f32_16x16x32_bf16 v[20:23], v[202:205], v[178:181], v[20:23]
	v_mfma_f32_16x16x32_bf16 v[12:15], v[210:213], v[178:181], v[12:15]
	v_mfma_f32_16x16x32_bf16 v[8:11], v[202:205], v[186:189], v[8:11]
	v_mfma_f32_16x16x32_bf16 v[4:7], v[210:213], v[186:189], v[4:7]
	v_mfma_f32_16x16x32_bf16 v[48:51], v[206:209], v[166:169], v[48:51]
	v_mfma_f32_16x16x32_bf16 v[44:47], v[214:217], v[166:169], v[44:47]
	v_mfma_f32_16x16x32_bf16 v[32:35], v[206:209], v[174:177], v[32:35]
	v_mfma_f32_16x16x32_bf16 v[28:31], v[214:217], v[174:177], v[28:31]
	v_mfma_f32_16x16x32_bf16 v[20:23], v[206:209], v[182:185], v[20:23]
	v_mfma_f32_16x16x32_bf16 v[12:15], v[214:217], v[182:185], v[12:15]
	v_mfma_f32_16x16x32_bf16 v[8:11], v[206:209], v[190:193], v[8:11]
	v_mfma_f32_16x16x32_bf16 v[4:7], v[214:217], v[190:193], v[4:7]
	s_add_i32 s23, 0, 0x18000
	v_add_u32_e32 v145, s23, v143
	s_barrier
	ds_read_b128 v[146:149], v145
	ds_read_b128 v[150:153], v145 offset:1024
	ds_read_b128 v[154:157], v145 offset:2048
	ds_read_b128 v[158:161], v145 offset:3072
	s_add_u32 s24, s52, 0x40000
	s_addc_u32 s25, s53, 0
	s_mov_b32 m0, s56
	v_lshl_add_u64 v[202:203], s[24:25], 0, v[0:1]
	ds_read_b128 v[162:165], v144 offset:32768
	ds_read_b128 v[166:169], v144 offset:33792
	ds_read_b128 v[170:173], v144 offset:34816
	ds_read_b128 v[174:177], v144 offset:35840
	ds_read_b128 v[178:181], v144 offset:36864
	ds_read_b128 v[182:185], v144 offset:37888
	ds_read_b128 v[186:189], v144 offset:38912
	ds_read_b128 v[190:193], v144 offset:39936
	global_load_lds_dwordx4 v[202:203], off
	v_lshl_add_u64 v[202:203], s[24:25], 0, v[134:135]
	s_mov_b32 m0, s57
	s_nop 0
	global_load_lds_dwordx4 v[202:203], off
	s_waitcnt lgkmcnt(8)
	s_barrier
	s_waitcnt lgkmcnt(0)
	v_mfma_f32_16x16x32_bf16 v[128:131], v[146:149], v[162:165], v[128:131]
	v_mfma_f32_16x16x32_bf16 v[124:127], v[154:157], v[162:165], v[124:127]
	v_mfma_f32_16x16x32_bf16 v[120:123], v[146:149], v[170:173], v[120:123]
	v_mfma_f32_16x16x32_bf16 v[116:119], v[154:157], v[170:173], v[116:119]
	v_mfma_f32_16x16x32_bf16 v[104:107], v[146:149], v[178:181], v[104:107]
	v_mfma_f32_16x16x32_bf16 v[100:103], v[154:157], v[178:181], v[100:103]
	v_mfma_f32_16x16x32_bf16 v[88:91], v[146:149], v[186:189], v[88:91]
	v_mfma_f32_16x16x32_bf16 v[84:87], v[154:157], v[186:189], v[84:87]
	v_mfma_f32_16x16x32_bf16 v[128:131], v[150:153], v[166:169], v[128:131]
	v_mfma_f32_16x16x32_bf16 v[124:127], v[158:161], v[166:169], v[124:127]
	v_mfma_f32_16x16x32_bf16 v[120:123], v[150:153], v[174:177], v[120:123]
	v_mfma_f32_16x16x32_bf16 v[116:119], v[158:161], v[174:177], v[116:119]
	v_mfma_f32_16x16x32_bf16 v[104:107], v[150:153], v[182:185], v[104:107]
	v_mfma_f32_16x16x32_bf16 v[100:103], v[158:161], v[182:185], v[100:103]
	v_mfma_f32_16x16x32_bf16 v[88:91], v[150:153], v[190:193], v[88:91]
	v_mfma_f32_16x16x32_bf16 v[84:87], v[158:161], v[190:193], v[84:87]
	s_barrier
	s_add_i32 s26, 0, 0x1c000
	s_add_i32 s23, s23, s37
	v_add_u32_e32 v145, s26, v143
	v_lshl_add_u64 v[194:195], v[194:195], 0, s[76:77]
	s_mov_b32 m0, s23
	ds_read_b128 v[202:205], v145
	ds_read_b128 v[206:209], v145 offset:1024
	ds_read_b128 v[210:213], v145 offset:2048
	ds_read_b128 v[214:217], v145 offset:3072
	global_load_lds_dwordx4 v[194:195], off
	v_lshl_add_u64 v[194:195], v[198:199], 0, s[76:77]
	s_add_i32 m0, s23, 0x2000
	s_nop 0
	global_load_lds_dwordx4 v[194:195], off
	s_barrier
	s_waitcnt lgkmcnt(0)
	v_mfma_f32_16x16x32_bf16 v[112:115], v[202:205], v[162:165], v[112:115]
	v_mfma_f32_16x16x32_bf16 v[108:111], v[210:213], v[162:165], v[108:111]
	v_mfma_f32_16x16x32_bf16 v[96:99], v[202:205], v[170:173], v[96:99]
	v_mfma_f32_16x16x32_bf16 v[92:95], v[210:213], v[170:173], v[92:95]
	v_mfma_f32_16x16x32_bf16 v[80:83], v[202:205], v[178:181], v[80:83]
	v_mfma_f32_16x16x32_bf16 v[76:79], v[210:213], v[178:181], v[76:79]
	v_mfma_f32_16x16x32_bf16 v[72:75], v[202:205], v[186:189], v[72:75]
	v_mfma_f32_16x16x32_bf16 v[68:71], v[210:213], v[186:189], v[68:71]
	v_mfma_f32_16x16x32_bf16 v[112:115], v[206:209], v[166:169], v[112:115]
	v_mfma_f32_16x16x32_bf16 v[108:111], v[214:217], v[166:169], v[108:111]
	v_mfma_f32_16x16x32_bf16 v[96:99], v[206:209], v[174:177], v[96:99]
	v_mfma_f32_16x16x32_bf16 v[92:95], v[214:217], v[174:177], v[92:95]
	v_mfma_f32_16x16x32_bf16 v[80:83], v[206:209], v[182:185], v[80:83]
	v_mfma_f32_16x16x32_bf16 v[76:79], v[214:217], v[182:185], v[76:79]
	v_mfma_f32_16x16x32_bf16 v[72:75], v[206:209], v[190:193], v[72:75]
	v_mfma_f32_16x16x32_bf16 v[68:71], v[214:217], v[190:193], v[68:71]
	s_mov_b32 m0, s59
	v_lshl_add_u64 v[194:195], v[222:223], 0, s[76:77]
	s_barrier
	ds_read_b128 v[162:165], v144 offset:49152
	ds_read_b128 v[166:169], v144 offset:50176
	ds_read_b128 v[170:173], v144 offset:51200
	ds_read_b128 v[174:177], v144 offset:52224
	ds_read_b128 v[178:181], v144 offset:53248
	ds_read_b128 v[182:185], v144 offset:54272
	ds_read_b128 v[186:189], v144 offset:55296
	ds_read_b128 v[190:193], v144 offset:56320
	global_load_lds_dwordx4 v[194:195], off
	v_lshl_add_u64 v[194:195], v[236:237], 0, s[76:77]
	s_mov_b32 m0, s60
	s_nop 0
	global_load_lds_dwordx4 v[194:195], off
	s_barrier
	s_waitcnt lgkmcnt(0)
	v_mfma_f32_16x16x32_bf16 v[64:67], v[146:149], v[162:165], v[64:67]
	v_mfma_f32_16x16x32_bf16 v[60:63], v[154:157], v[162:165], v[60:63]
	v_mfma_f32_16x16x32_bf16 v[56:59], v[146:149], v[170:173], v[56:59]
	v_mfma_f32_16x16x32_bf16 v[52:55], v[154:157], v[170:173], v[52:55]
	v_mfma_f32_16x16x32_bf16 v[40:43], v[146:149], v[178:181], v[40:43]
	v_mfma_f32_16x16x32_bf16 v[36:39], v[154:157], v[178:181], v[36:39]
	v_mfma_f32_16x16x32_bf16 v[24:27], v[146:149], v[186:189], v[24:27]
	v_mfma_f32_16x16x32_bf16 v[16:19], v[154:157], v[186:189], v[16:19]
	v_mfma_f32_16x16x32_bf16 v[64:67], v[150:153], v[166:169], v[64:67]
	v_mfma_f32_16x16x32_bf16 v[60:63], v[158:161], v[166:169], v[60:63]
	v_mfma_f32_16x16x32_bf16 v[56:59], v[150:153], v[174:177], v[56:59]
	v_mfma_f32_16x16x32_bf16 v[52:55], v[158:161], v[174:177], v[52:55]
	v_mfma_f32_16x16x32_bf16 v[40:43], v[150:153], v[182:185], v[40:43]
	v_mfma_f32_16x16x32_bf16 v[36:39], v[158:161], v[182:185], v[36:39]
	v_mfma_f32_16x16x32_bf16 v[24:27], v[150:153], v[190:193], v[24:27]
	v_mfma_f32_16x16x32_bf16 v[16:19], v[158:161], v[190:193], v[16:19]
	s_barrier
	s_add_u32 s24, s50, 0x40080
	s_addc_u32 s25, s51, 0
	s_add_i32 s23, s26, s37
	v_lshl_add_u64 v[146:147], s[24:25], 0, v[132:133]
	s_mov_b32 m0, s23
	s_nop 0
	global_load_lds_dwordx4 v[146:147], off
	v_lshl_add_u64 v[146:147], s[24:25], 0, v[136:137]
	s_add_i32 m0, s23, 0x2000
	s_nop 0
	global_load_lds_dwordx4 v[146:147], off
	s_waitcnt vmcnt(6)
	s_barrier
	v_mfma_f32_16x16x32_bf16 v[48:51], v[202:205], v[162:165], v[48:51]
	v_mfma_f32_16x16x32_bf16 v[44:47], v[210:213], v[162:165], v[44:47]
	v_mfma_f32_16x16x32_bf16 v[32:35], v[202:205], v[170:173], v[32:35]
	v_mfma_f32_16x16x32_bf16 v[28:31], v[210:213], v[170:173], v[28:31]
	v_mfma_f32_16x16x32_bf16 v[20:23], v[202:205], v[178:181], v[20:23]
	v_mfma_f32_16x16x32_bf16 v[12:15], v[210:213], v[178:181], v[12:15]
	v_mfma_f32_16x16x32_bf16 v[8:11], v[202:205], v[186:189], v[8:11]
	v_mfma_f32_16x16x32_bf16 v[4:7], v[210:213], v[186:189], v[4:7]
	v_mfma_f32_16x16x32_bf16 v[48:51], v[206:209], v[166:169], v[48:51]
	v_mfma_f32_16x16x32_bf16 v[44:47], v[214:217], v[166:169], v[44:47]
	v_mfma_f32_16x16x32_bf16 v[32:35], v[206:209], v[174:177], v[32:35]
	v_mfma_f32_16x16x32_bf16 v[28:31], v[214:217], v[174:177], v[28:31]
	v_mfma_f32_16x16x32_bf16 v[20:23], v[206:209], v[182:185], v[20:23]
	v_mfma_f32_16x16x32_bf16 v[12:15], v[214:217], v[182:185], v[12:15]
	v_mfma_f32_16x16x32_bf16 v[8:11], v[206:209], v[190:193], v[8:11]
	v_mfma_f32_16x16x32_bf16 v[4:7], v[214:217], v[190:193], v[4:7]
	s_add_i32 s22, s22, 2
	s_add_u32 s48, s48, 0x100
	s_addc_u32 s49, s49, 0
	s_add_u32 s20, s20, 0x100
	s_addc_u32 s21, s21, 0
	s_cmp_gt_u32 s22, 13
	s_barrier
	s_cbranch_scc0 .LBB0_136
	v_lshl_add_u32 v146, s0, 8, v142
	v_cvt_pk_bf16_f32 v72, v72, v73
	v_cvt_pk_bf16_f32 v73, v74, v75
	v_cvt_pk_bf16_f32 v74, v68, v69
	v_add_u32_e32 v68, 0x80, v146
	s_lshl_b32 s0, s1, 8
	v_ashrrev_i32_e32 v147, 31, v146
	v_readlane_b32 s20, v252, 12
	v_cvt_pk_bf16_f32 v112, v112, v113
	v_cvt_pk_bf16_f32 v113, v114, v115
	v_cvt_pk_bf16_f32 v114, v108, v109
	v_or_b32_e32 v108, 16, v146
	v_ashrrev_i32_e32 v69, 31, v68
	v_cvt_pk_bf16_f32 v48, v48, v49
	v_cvt_pk_bf16_f32 v49, v50, v51
	v_cvt_pk_bf16_f32 v50, v44, v45
	v_add_u32_e32 v44, 0x90, v146
	s_ashr_i32 s1, s0, 31
	v_lshlrev_b64 v[148:149], 11, v[146:147]
	v_readlane_b32 s21, v252, 13
	v_ashrrev_i32_e32 v109, 31, v108
	v_cvt_pk_bf16_f32 v96, v96, v97
	v_cvt_pk_bf16_f32 v97, v98, v99
	v_cvt_pk_bf16_f32 v98, v92, v93
	v_or_b32_e32 v92, 32, v146
	v_lshlrev_b64 v[68:69], 11, v[68:69]
	v_ashrrev_i32_e32 v45, 31, v44
	v_cvt_pk_bf16_f32 v32, v32, v33
	v_cvt_pk_bf16_f32 v33, v34, v35
	v_cvt_pk_bf16_f32 v34, v28, v29
	v_add_u32_e32 v28, 0xa0, v146
	v_lshl_add_u64 v[148:149], s[20:21], 0, v[148:149]
	s_lshl_b64 s[0:1], s[0:1], 1
	v_lshlrev_b64 v[108:109], 11, v[108:109]
	v_ashrrev_i32_e32 v93, 31, v92
	v_cvt_pk_bf16_f32 v80, v80, v81
	v_cvt_pk_bf16_f32 v81, v82, v83
	v_cvt_pk_bf16_f32 v82, v76, v77
	v_or_b32_e32 v76, 48, v146
	v_lshl_add_u64 v[68:69], s[20:21], 0, v[68:69]
	v_lshlrev_b64 v[44:45], 11, v[44:45]
	v_ashrrev_i32_e32 v29, 31, v28
	v_cvt_pk_bf16_f32 v20, v20, v21
	v_cvt_pk_bf16_f32 v21, v22, v23
	v_cvt_pk_bf16_f32 v22, v12, v13
	v_add_u32_e32 v12, 0xb0, v146
	v_lshl_add_u64 v[148:149], v[148:149], 0, s[0:1]
	v_lshl_add_u64 v[108:109], s[20:21], 0, v[108:109]
	v_lshlrev_b64 v[92:93], 11, v[92:93]
	v_ashrrev_i32_e32 v77, 31, v76
	v_lshl_add_u64 v[68:69], v[68:69], 0, s[0:1]
	v_lshl_add_u64 v[44:45], s[20:21], 0, v[44:45]
	v_lshlrev_b64 v[28:29], 11, v[28:29]
	v_ashrrev_i32_e32 v13, 31, v12
	v_lshl_add_u64 v[148:149], v[148:149], 0, s[72:73]
	v_lshl_add_u64 v[108:109], v[108:109], 0, s[0:1]
	v_lshl_add_u64 v[92:93], s[20:21], 0, v[92:93]
	v_lshlrev_b64 v[76:77], 11, v[76:77]
	v_lshl_add_u64 v[68:69], v[68:69], 0, s[72:73]
	v_lshl_add_u64 v[44:45], v[44:45], 0, s[0:1]
	v_lshl_add_u64 v[28:29], s[20:21], 0, v[28:29]
	v_lshlrev_b64 v[12:13], 11, v[12:13]
	v_lshl_add_u64 v[148:149], v[148:149], 0, v[2:3]
	v_cvt_pk_bf16_f32 v115, v110, v111
	v_lshl_add_u64 v[108:109], v[108:109], 0, s[72:73]
	v_lshl_add_u64 v[92:93], v[92:93], 0, s[0:1]
	v_lshl_add_u64 v[76:77], s[20:21], 0, v[76:77]
	v_lshl_add_u64 v[68:69], v[68:69], 0, v[2:3]
	v_cvt_pk_bf16_f32 v51, v46, v47
	v_lshl_add_u64 v[44:45], v[44:45], 0, s[72:73]
	v_lshl_add_u64 v[28:29], v[28:29], 0, s[0:1]
	v_lshl_add_u64 v[12:13], s[20:21], 0, v[12:13]
	global_store_dwordx4 v[148:149], v[112:115], off offset:256
	v_cvt_pk_bf16_f32 v99, v94, v95
	v_lshl_add_u64 v[92:93], v[92:93], 0, s[72:73]
	v_lshl_add_u64 v[112:113], v[108:109], 0, v[2:3]
	v_lshl_add_u64 v[76:77], v[76:77], 0, s[0:1]
	global_store_dwordx4 v[68:69], v[48:51], off offset:256
	v_cvt_pk_bf16_f32 v35, v30, v31
	v_lshl_add_u64 v[28:29], v[28:29], 0, s[72:73]
	v_lshl_add_u64 v[48:49], v[44:45], 0, v[2:3]
	v_lshl_add_u64 v[12:13], v[12:13], 0, s[0:1]
	global_store_dwordx4 v[112:113], v[96:99], off offset:256
	v_cvt_pk_bf16_f32 v83, v78, v79
	v_lshl_add_u64 v[76:77], v[76:77], 0, s[72:73]
	v_lshl_add_u64 v[96:97], v[92:93], 0, v[2:3]
	global_store_dwordx4 v[48:49], v[32:35], off offset:256
	v_cvt_pk_bf16_f32 v23, v14, v15
	v_lshl_add_u64 v[12:13], v[12:13], 0, s[72:73]
	v_lshl_add_u64 v[32:33], v[28:29], 0, v[2:3]
	v_cvt_pk_bf16_f32 v128, v128, v129
	v_cvt_pk_bf16_f32 v129, v130, v131
	v_cvt_pk_bf16_f32 v130, v124, v125
	v_cvt_pk_bf16_f32 v131, v126, v127
	v_cvt_pk_bf16_f32 v108, v120, v121
	v_cvt_pk_bf16_f32 v109, v122, v123
	v_cvt_pk_bf16_f32 v110, v116, v117
	v_cvt_pk_bf16_f32 v111, v118, v119
	v_cvt_pk_bf16_f32 v92, v104, v105
	v_cvt_pk_bf16_f32 v93, v106, v107
	v_cvt_pk_bf16_f32 v94, v100, v101
	v_cvt_pk_bf16_f32 v95, v102, v103
	global_store_dwordx4 v[96:97], v[80:83], off offset:256
	v_cvt_pk_bf16_f32 v78, v84, v85
	v_cvt_pk_bf16_f32 v79, v86, v87
	v_lshl_add_u64 v[80:81], v[76:77], 0, v[2:3]
	v_cvt_pk_bf16_f32 v76, v88, v89
	v_cvt_pk_bf16_f32 v77, v90, v91
	v_cvt_pk_bf16_f32 v75, v70, v71
	v_cvt_pk_bf16_f32 v64, v64, v65
	v_cvt_pk_bf16_f32 v65, v66, v67
	v_cvt_pk_bf16_f32 v66, v60, v61
	v_cvt_pk_bf16_f32 v67, v62, v63
	v_cvt_pk_bf16_f32 v44, v56, v57
	v_cvt_pk_bf16_f32 v45, v58, v59
	v_cvt_pk_bf16_f32 v46, v52, v53
	v_cvt_pk_bf16_f32 v47, v54, v55
	v_cvt_pk_bf16_f32 v28, v40, v41
	v_cvt_pk_bf16_f32 v29, v42, v43
	v_cvt_pk_bf16_f32 v30, v36, v37
	v_cvt_pk_bf16_f32 v31, v38, v39
	global_store_dwordx4 v[32:33], v[20:23], off offset:256
	v_cvt_pk_bf16_f32 v14, v16, v17
	v_cvt_pk_bf16_f32 v15, v18, v19
	v_lshl_add_u64 v[20:21], v[12:13], 0, v[2:3]
	v_cvt_pk_bf16_f32 v12, v24, v25
	v_cvt_pk_bf16_f32 v13, v26, v27
	v_cvt_pk_bf16_f32 v8, v8, v9
	v_cvt_pk_bf16_f32 v9, v10, v11
	v_cvt_pk_bf16_f32 v10, v4, v5
	v_cvt_pk_bf16_f32 v11, v6, v7
	s_and_b64 vcc, exec, s[38:39]
	s_mov_b32 s1, s40
	s_mov_b32 s0, s42
	s_mov_b64 s[50:51], s[46:47]
	s_mov_b64 s[48:49], s[44:45]
	global_store_dwordx4 v[148:149], v[128:131], off
	global_store_dwordx4 v[112:113], v[108:111], off
	global_store_dwordx4 v[96:97], v[92:95], off
	global_store_dwordx4 v[80:81], v[76:79], off
	global_store_dwordx4 v[80:81], v[72:75], off offset:256
	global_store_dwordx4 v[68:69], v[64:67], off
	global_store_dwordx4 v[48:49], v[44:47], off
	global_store_dwordx4 v[32:33], v[28:31], off
	global_store_dwordx4 v[20:21], v[12:15], off
	global_store_dwordx4 v[20:21], v[8:11], off offset:256
	s_cbranch_vccz .LBB0_129
	s_waitcnt vmcnt(0)
	s_cmpk_gt_u32 s31, 0xff
	s_cbranch_scc1 .LBB0_140
	s_barrier

.LBB0_175:
	s_add_i32 s26, s27, 2
	s_add_u32 s44, s40, 0x100
	s_addc_u32 s45, s41, 0
	s_add_i32 s30, 0, 0x10000
	v_add_u32_e32 v0, s30, v157
	ds_read_b128 v[132:135], v0
	ds_read_b128 v[164:167], v0 offset:1024
	ds_read_b128 v[168:171], v0 offset:2048
	ds_read_b128 v[174:177], v0 offset:3072
	s_cmp_eq_u32 s23, s27
	s_cselect_b32 s49, s1, s45
	s_cselect_b32 s48, s0, s44
	s_cselect_b32 s47, s43, s25
	s_cselect_b32 s46, s42, s24
	v_lshl_add_u64 v[0:1], s[40:41], 0, v[160:161]
	s_add_i32 m0, s53, 0xc000
	ds_read_b128 v[178:181], v172
	ds_read_b128 v[182:185], v172 offset:1024
	ds_read_b128 v[186:189], v172 offset:2048
	ds_read_b128 v[190:193], v172 offset:3072
	ds_read_b128 v[202:205], v172 offset:4096
	ds_read_b128 v[206:209], v172 offset:5120
	ds_read_b128 v[210:213], v172 offset:6144
	ds_read_b128 v[214:217], v172 offset:7168
	global_load_lds_dwordx4 v[0:1], off
	v_lshl_add_u64 v[0:1], s[40:41], 0, v[162:163]
	s_add_i32 m0, s53, 0xe000
	s_nop 0
	global_load_lds_dwordx4 v[0:1], off
	s_waitcnt lgkmcnt(8)
	s_barrier
	s_waitcnt lgkmcnt(0)
	v_mfma_f32_16x16x32_bf16 v[4:7], v[132:135], v[178:181], v[4:7]
	v_mfma_f32_16x16x32_bf16 v[8:11], v[168:171], v[178:181], v[8:11]
	v_mfma_f32_16x16x32_bf16 v[128:131], v[132:135], v[186:189], v[128:131]
	v_mfma_f32_16x16x32_bf16 v[124:127], v[168:171], v[186:189], v[124:127]
	v_mfma_f32_16x16x32_bf16 v[120:123], v[132:135], v[202:205], v[120:123]
	v_mfma_f32_16x16x32_bf16 v[116:119], v[168:171], v[202:205], v[116:119]
	v_mfma_f32_16x16x32_bf16 v[112:115], v[132:135], v[210:213], v[112:115]
	v_mfma_f32_16x16x32_bf16 v[108:111], v[168:171], v[210:213], v[108:111]
	v_mfma_f32_16x16x32_bf16 v[4:7], v[164:167], v[182:185], v[4:7]
	v_mfma_f32_16x16x32_bf16 v[8:11], v[174:177], v[182:185], v[8:11]
	v_mfma_f32_16x16x32_bf16 v[128:131], v[164:167], v[190:193], v[128:131]
	v_mfma_f32_16x16x32_bf16 v[124:127], v[174:177], v[190:193], v[124:127]
	v_mfma_f32_16x16x32_bf16 v[120:123], v[164:167], v[206:209], v[120:123]
	v_mfma_f32_16x16x32_bf16 v[116:119], v[174:177], v[206:209], v[116:119]
	v_mfma_f32_16x16x32_bf16 v[112:115], v[164:167], v[214:217], v[112:115]
	v_mfma_f32_16x16x32_bf16 v[108:111], v[174:177], v[214:217], v[108:111]
	s_barrier
	s_add_i32 s27, 0, 0x14000
	v_add_u32_e32 v0, s27, v157
	s_add_i32 s30, s30, s52
	ds_read_b128 v[236:239], v0
	ds_read_b128 v[240:243], v0 offset:1024
	ds_read_b128 v[244:247], v0 offset:2048
	ds_read_b128 v[248:251], v0 offset:3072
	v_lshl_add_u64 v[0:1], s[46:47], 0, v[138:139]
	s_mov_b32 m0, s30
	v_lshl_add_u64 v[194:195], s[46:47], 0, v[142:143]
	global_load_lds_dwordx4 v[0:1], off
	s_add_i32 m0, s30, 0x2000
	s_nop 0
	global_load_lds_dwordx4 v[194:195], off
	s_barrier
	s_waitcnt lgkmcnt(0)
	v_mfma_f32_16x16x32_bf16 v[12:15], v[236:239], v[178:181], v[12:15]
	v_mfma_f32_16x16x32_bf16 v[16:19], v[244:247], v[178:181], v[16:19]
	v_mfma_f32_16x16x32_bf16 v[104:107], v[236:239], v[186:189], v[104:107]
	v_mfma_f32_16x16x32_bf16 v[100:103], v[244:247], v[186:189], v[100:103]
	v_mfma_f32_16x16x32_bf16 v[96:99], v[236:239], v[202:205], v[96:99]
	v_mfma_f32_16x16x32_bf16 v[92:95], v[244:247], v[202:205], v[92:95]
	v_mfma_f32_16x16x32_bf16 v[88:91], v[236:239], v[210:213], v[88:91]
	v_mfma_f32_16x16x32_bf16 v[84:87], v[244:247], v[210:213], v[84:87]
	v_mfma_f32_16x16x32_bf16 v[12:15], v[240:243], v[182:185], v[12:15]
	v_mfma_f32_16x16x32_bf16 v[16:19], v[248:251], v[182:185], v[16:19]
	v_mfma_f32_16x16x32_bf16 v[104:107], v[240:243], v[190:193], v[104:107]
	v_mfma_f32_16x16x32_bf16 v[100:103], v[248:251], v[190:193], v[100:103]
	v_mfma_f32_16x16x32_bf16 v[96:99], v[240:243], v[206:209], v[96:99]
	v_mfma_f32_16x16x32_bf16 v[92:95], v[248:251], v[206:209], v[92:95]
	v_mfma_f32_16x16x32_bf16 v[88:91], v[240:243], v[214:217], v[88:91]
	v_mfma_f32_16x16x32_bf16 v[84:87], v[248:251], v[214:217], v[84:87]
	s_mov_b32 m0, s53
	v_lshl_add_u64 v[222:223], s[48:49], 0, v[136:137]
	s_barrier
	ds_read_b128 v[178:181], v172 offset:16384
	ds_read_b128 v[182:185], v172 offset:17408
	ds_read_b128 v[186:189], v172 offset:18432
	ds_read_b128 v[190:193], v172 offset:19456
	ds_read_b128 v[202:205], v172 offset:20480
	ds_read_b128 v[206:209], v172 offset:21504
	ds_read_b128 v[210:213], v172 offset:22528
	ds_read_b128 v[214:217], v172 offset:23552
	global_load_lds_dwordx4 v[222:223], off
	v_lshl_add_u64 v[198:199], s[48:49], 0, v[140:141]
	s_mov_b32 m0, s54
	s_nop 0
	global_load_lds_dwordx4 v[198:199], off
	s_barrier
	s_waitcnt lgkmcnt(0)
	v_mfma_f32_16x16x32_bf16 v[80:83], v[132:135], v[178:181], v[80:83]
	v_mfma_f32_16x16x32_bf16 v[76:79], v[168:171], v[178:181], v[76:79]
	v_mfma_f32_16x16x32_bf16 v[72:75], v[132:135], v[186:189], v[72:75]
	v_mfma_f32_16x16x32_bf16 v[68:71], v[168:171], v[186:189], v[68:71]
	v_mfma_f32_16x16x32_bf16 v[64:67], v[132:135], v[202:205], v[64:67]
	v_mfma_f32_16x16x32_bf16 v[60:63], v[168:171], v[202:205], v[60:63]
	v_mfma_f32_16x16x32_bf16 v[56:59], v[132:135], v[210:213], v[56:59]
	v_mfma_f32_16x16x32_bf16 v[52:55], v[168:171], v[210:213], v[52:55]
	v_mfma_f32_16x16x32_bf16 v[80:83], v[164:167], v[182:185], v[80:83]
	v_mfma_f32_16x16x32_bf16 v[76:79], v[174:177], v[182:185], v[76:79]
	v_mfma_f32_16x16x32_bf16 v[72:75], v[164:167], v[190:193], v[72:75]
	v_mfma_f32_16x16x32_bf16 v[68:71], v[174:177], v[190:193], v[68:71]
	v_mfma_f32_16x16x32_bf16 v[64:67], v[164:167], v[206:209], v[64:67]
	v_mfma_f32_16x16x32_bf16 v[60:63], v[174:177], v[206:209], v[60:63]
	v_mfma_f32_16x16x32_bf16 v[56:59], v[164:167], v[214:217], v[56:59]
	v_mfma_f32_16x16x32_bf16 v[52:55], v[174:177], v[214:217], v[52:55]
	s_barrier
	s_add_u32 s30, s46, 0xc0000
	s_addc_u32 s31, s47, 0
	s_add_i32 s27, s27, s52
	v_lshl_add_u64 v[132:133], s[30:31], 0, v[138:139]
	s_mov_b32 m0, s27
	s_nop 0
	global_load_lds_dwordx4 v[132:133], off
	v_lshl_add_u64 v[132:133], s[30:31], 0, v[142:143]
	s_add_i32 m0, s27, 0x2000
	s_nop 0
	global_load_lds_dwordx4 v[132:133], off
	s_waitcnt vmcnt(6)
	s_barrier
	v_mfma_f32_16x16x32_bf16 v[48:51], v[236:239], v[178:181], v[48:51]
	v_mfma_f32_16x16x32_bf16 v[44:47], v[244:247], v[178:181], v[44:47]
	v_mfma_f32_16x16x32_bf16 v[40:43], v[236:239], v[186:189], v[40:43]
	v_mfma_f32_16x16x32_bf16 v[36:39], v[244:247], v[186:189], v[36:39]
	v_mfma_f32_16x16x32_bf16 v[32:35], v[236:239], v[202:205], v[32:35]
	v_mfma_f32_16x16x32_bf16 v[28:31], v[244:247], v[202:205], v[28:31]
	v_mfma_f32_16x16x32_bf16 v[24:27], v[236:239], v[210:213], v[24:27]
	v_mfma_f32_16x16x32_bf16 v[20:23], v[244:247], v[210:213], v[20:23]
	v_mfma_f32_16x16x32_bf16 v[48:51], v[240:243], v[182:185], v[48:51]
	v_mfma_f32_16x16x32_bf16 v[44:47], v[248:251], v[182:185], v[44:47]
	v_mfma_f32_16x16x32_bf16 v[40:43], v[240:243], v[190:193], v[40:43]
	v_mfma_f32_16x16x32_bf16 v[36:39], v[248:251], v[190:193], v[36:39]
	v_mfma_f32_16x16x32_bf16 v[32:35], v[240:243], v[206:209], v[32:35]
	v_mfma_f32_16x16x32_bf16 v[28:31], v[248:251], v[206:209], v[28:31]
	v_mfma_f32_16x16x32_bf16 v[24:27], v[240:243], v[214:217], v[24:27]
	v_mfma_f32_16x16x32_bf16 v[20:23], v[248:251], v[214:217], v[20:23]
	s_add_i32 s27, 0, 0x18000
	v_add_u32_e32 v2, s27, v157
	s_barrier
	ds_read_b128 v[132:135], v2
	ds_read_b128 v[164:167], v2 offset:1024
	ds_read_b128 v[168:171], v2 offset:2048
	ds_read_b128 v[174:177], v2 offset:3072
	s_add_u32 s30, s48, 0x1a0000
	s_addc_u32 s31, s49, 0
	s_mov_b32 m0, s55
	v_lshl_add_u64 v[236:237], s[30:31], 0, v[136:137]
	ds_read_b128 v[178:181], v172 offset:32768
	ds_read_b128 v[182:185], v172 offset:33792
	ds_read_b128 v[186:189], v172 offset:34816
	ds_read_b128 v[190:193], v172 offset:35840
	ds_read_b128 v[202:205], v172 offset:36864
	ds_read_b128 v[206:209], v172 offset:37888
	ds_read_b128 v[210:213], v172 offset:38912
	ds_read_b128 v[214:217], v172 offset:39936
	global_load_lds_dwordx4 v[236:237], off
	v_lshl_add_u64 v[236:237], s[30:31], 0, v[140:141]
	s_mov_b32 m0, s56
	s_nop 0
	global_load_lds_dwordx4 v[236:237], off
	s_waitcnt lgkmcnt(8)
	s_barrier
	s_waitcnt lgkmcnt(0)
	v_mfma_f32_16x16x32_bf16 v[4:7], v[132:135], v[178:181], v[4:7]
	v_mfma_f32_16x16x32_bf16 v[8:11], v[168:171], v[178:181], v[8:11]
	v_mfma_f32_16x16x32_bf16 v[128:131], v[132:135], v[186:189], v[128:131]
	v_mfma_f32_16x16x32_bf16 v[124:127], v[168:171], v[186:189], v[124:127]
	v_mfma_f32_16x16x32_bf16 v[120:123], v[132:135], v[202:205], v[120:123]
	v_mfma_f32_16x16x32_bf16 v[116:119], v[168:171], v[202:205], v[116:119]
	v_mfma_f32_16x16x32_bf16 v[112:115], v[132:135], v[210:213], v[112:115]
	v_mfma_f32_16x16x32_bf16 v[108:111], v[168:171], v[210:213], v[108:111]
	v_mfma_f32_16x16x32_bf16 v[4:7], v[164:167], v[182:185], v[4:7]
	v_mfma_f32_16x16x32_bf16 v[8:11], v[174:177], v[182:185], v[8:11]
	v_mfma_f32_16x16x32_bf16 v[128:131], v[164:167], v[190:193], v[128:131]
	v_mfma_f32_16x16x32_bf16 v[124:127], v[174:177], v[190:193], v[124:127]
	v_mfma_f32_16x16x32_bf16 v[120:123], v[164:167], v[206:209], v[120:123]
	v_mfma_f32_16x16x32_bf16 v[116:119], v[174:177], v[206:209], v[116:119]
	v_mfma_f32_16x16x32_bf16 v[112:115], v[164:167], v[214:217], v[112:115]
	v_mfma_f32_16x16x32_bf16 v[108:111], v[174:177], v[214:217], v[108:111]
	s_barrier
	s_add_i32 s36, 0, 0x1c000
	s_add_i32 s27, s27, s52
	v_add_u32_e32 v2, s36, v157
	v_lshl_add_u64 v[0:1], v[0:1], 0, s[76:77]
	s_mov_b32 m0, s27
	ds_read_b128 v[236:239], v2
	ds_read_b128 v[240:243], v2 offset:1024
	ds_read_b128 v[244:247], v2 offset:2048
	ds_read_b128 v[248:251], v2 offset:3072
	global_load_lds_dwordx4 v[0:1], off
	v_lshl_add_u64 v[0:1], v[194:195], 0, s[76:77]
	s_add_i32 m0, s27, 0x2000
	s_nop 0
	global_load_lds_dwordx4 v[0:1], off
	s_barrier
	s_waitcnt lgkmcnt(0)
	v_mfma_f32_16x16x32_bf16 v[12:15], v[236:239], v[178:181], v[12:15]
	v_mfma_f32_16x16x32_bf16 v[16:19], v[244:247], v[178:181], v[16:19]
	v_mfma_f32_16x16x32_bf16 v[104:107], v[236:239], v[186:189], v[104:107]
	v_mfma_f32_16x16x32_bf16 v[100:103], v[244:247], v[186:189], v[100:103]
	v_mfma_f32_16x16x32_bf16 v[96:99], v[236:239], v[202:205], v[96:99]
	v_mfma_f32_16x16x32_bf16 v[92:95], v[244:247], v[202:205], v[92:95]
	v_mfma_f32_16x16x32_bf16 v[88:91], v[236:239], v[210:213], v[88:91]
	v_mfma_f32_16x16x32_bf16 v[84:87], v[244:247], v[210:213], v[84:87]
	v_mfma_f32_16x16x32_bf16 v[12:15], v[240:243], v[182:185], v[12:15]
	v_mfma_f32_16x16x32_bf16 v[16:19], v[248:251], v[182:185], v[16:19]
	v_mfma_f32_16x16x32_bf16 v[104:107], v[240:243], v[190:193], v[104:107]
	v_mfma_f32_16x16x32_bf16 v[100:103], v[248:251], v[190:193], v[100:103]
	v_mfma_f32_16x16x32_bf16 v[96:99], v[240:243], v[206:209], v[96:99]
	v_mfma_f32_16x16x32_bf16 v[92:95], v[248:251], v[206:209], v[92:95]
	v_mfma_f32_16x16x32_bf16 v[88:91], v[240:243], v[214:217], v[88:91]
	v_mfma_f32_16x16x32_bf16 v[84:87], v[248:251], v[214:217], v[84:87]
	s_mov_b32 m0, s59
	v_lshl_add_u64 v[0:1], v[222:223], 0, s[76:77]
	s_barrier
	ds_read_b128 v[178:181], v172 offset:49152
	ds_read_b128 v[182:185], v172 offset:50176
	ds_read_b128 v[186:189], v172 offset:51200
	ds_read_b128 v[190:193], v172 offset:52224
	ds_read_b128 v[202:205], v172 offset:53248
	ds_read_b128 v[206:209], v172 offset:54272
	ds_read_b128 v[210:213], v172 offset:55296
	ds_read_b128 v[214:217], v172 offset:56320
	global_load_lds_dwordx4 v[0:1], off
	v_lshl_add_u64 v[0:1], v[198:199], 0, s[76:77]
	s_mov_b32 m0, s60
	s_nop 0
	global_load_lds_dwordx4 v[0:1], off
	s_barrier
	s_waitcnt lgkmcnt(0)
	v_mfma_f32_16x16x32_bf16 v[80:83], v[132:135], v[178:181], v[80:83]
	v_mfma_f32_16x16x32_bf16 v[76:79], v[168:171], v[178:181], v[76:79]
	v_mfma_f32_16x16x32_bf16 v[72:75], v[132:135], v[186:189], v[72:75]
	v_mfma_f32_16x16x32_bf16 v[68:71], v[168:171], v[186:189], v[68:71]
	v_mfma_f32_16x16x32_bf16 v[64:67], v[132:135], v[202:205], v[64:67]
	v_mfma_f32_16x16x32_bf16 v[60:63], v[168:171], v[202:205], v[60:63]
	v_mfma_f32_16x16x32_bf16 v[56:59], v[132:135], v[210:213], v[56:59]
	v_mfma_f32_16x16x32_bf16 v[52:55], v[168:171], v[210:213], v[52:55]
	v_mfma_f32_16x16x32_bf16 v[80:83], v[164:167], v[182:185], v[80:83]
	v_mfma_f32_16x16x32_bf16 v[76:79], v[174:177], v[182:185], v[76:79]
	v_mfma_f32_16x16x32_bf16 v[72:75], v[164:167], v[190:193], v[72:75]
	v_mfma_f32_16x16x32_bf16 v[68:71], v[174:177], v[190:193], v[68:71]
	v_mfma_f32_16x16x32_bf16 v[64:67], v[164:167], v[206:209], v[64:67]
	v_mfma_f32_16x16x32_bf16 v[60:63], v[174:177], v[206:209], v[60:63]
	v_mfma_f32_16x16x32_bf16 v[56:59], v[164:167], v[214:217], v[56:59]
	v_mfma_f32_16x16x32_bf16 v[52:55], v[174:177], v[214:217], v[52:55]
	s_barrier
	s_add_u32 s30, s46, 0xc0080
	s_addc_u32 s31, s47, 0
	s_add_i32 s27, s36, s52
	v_lshl_add_u64 v[0:1], s[30:31], 0, v[138:139]
	s_mov_b32 m0, s27
	s_nop 0
	global_load_lds_dwordx4 v[0:1], off
	v_lshl_add_u64 v[0:1], s[30:31], 0, v[142:143]
	s_add_i32 m0, s27, 0x2000
	s_nop 0
	global_load_lds_dwordx4 v[0:1], off
	s_waitcnt vmcnt(6)
	s_barrier
	v_mfma_f32_16x16x32_bf16 v[48:51], v[236:239], v[178:181], v[48:51]
	v_mfma_f32_16x16x32_bf16 v[44:47], v[244:247], v[178:181], v[44:47]
	v_mfma_f32_16x16x32_bf16 v[40:43], v[236:239], v[186:189], v[40:43]
	v_mfma_f32_16x16x32_bf16 v[36:39], v[244:247], v[186:189], v[36:39]
	v_mfma_f32_16x16x32_bf16 v[32:35], v[236:239], v[202:205], v[32:35]
	v_mfma_f32_16x16x32_bf16 v[28:31], v[244:247], v[202:205], v[28:31]
	v_mfma_f32_16x16x32_bf16 v[24:27], v[236:239], v[210:213], v[24:27]
	v_mfma_f32_16x16x32_bf16 v[20:23], v[244:247], v[210:213], v[20:23]
	v_mfma_f32_16x16x32_bf16 v[48:51], v[240:243], v[182:185], v[48:51]
	v_mfma_f32_16x16x32_bf16 v[44:47], v[248:251], v[182:185], v[44:47]
	v_mfma_f32_16x16x32_bf16 v[40:43], v[240:243], v[190:193], v[40:43]
	v_mfma_f32_16x16x32_bf16 v[36:39], v[248:251], v[190:193], v[36:39]
	v_mfma_f32_16x16x32_bf16 v[32:35], v[240:243], v[206:209], v[32:35]
	v_mfma_f32_16x16x32_bf16 v[28:31], v[248:251], v[206:209], v[28:31]
	v_mfma_f32_16x16x32_bf16 v[24:27], v[240:243], v[214:217], v[24:27]
	v_mfma_f32_16x16x32_bf16 v[20:23], v[248:251], v[214:217], v[20:23]
	s_add_u32 s24, s24, 0x100
	s_addc_u32 s25, s25, 0
	s_cmp_ge_i32 s26, s22
	s_mov_b64 s[40:41], s[44:45]
	s_mov_b32 s27, s26
	s_barrier
	s_cbranch_scc0 .LBB0_175
	s_lshl_b32 s46, s66, 8
	v_lshl_or_b32 v0, s20, 8, v159
	s_mov_b32 s44, 0xbfb8aa3b
	s_mov_b32 s45, 0xbfb8aa3b
	v_lshlrev_b32_e32 v0, 1, v0
	v_add_u32_e32 v0, 0x1000, v0
	s_cmp_lg_u32 s21, 1
	s_cbranch_scc0 .Lg2_kind1
	v_readlane_b32 s22, v252, 34
	v_readlane_b32 s23, v252, 35
	v_add_u32_e32 v2, s46, v144
	v_mad_u32_u24 v2, v2, s29, v0
	global_load_dwordx4 v[132:135], v2, s[96:97] offset:2048
	v_add_u32_e32 v2, s46, v144
	v_mad_u32_u24 v2, v2, s29, v0
	global_load_dwordx4 v[178:181], v2, s[96:97] offset:2304
	v_add_u32_e32 v2, s46, v146
	v_mad_u32_u24 v2, v2, s29, v0
	global_load_dwordx4 v[182:185], v2, s[96:97] offset:2048
	v_add_u32_e32 v2, s46, v146
	v_mad_u32_u24 v2, v2, s29, v0
	global_load_dwordx4 v[186:189], v2, s[96:97] offset:2304
	v_add_u32_e32 v2, s46, v148
	v_mad_u32_u24 v2, v2, s29, v0
	global_load_dwordx4 v[190:193], v2, s[96:97] offset:2048
	v_add_u32_e32 v2, s46, v148
	v_mad_u32_u24 v2, v2, s29, v0
	global_load_dwordx4 v[202:205], v2, s[96:97] offset:2304
	v_add_u32_e32 v2, s46, v150
	v_mad_u32_u24 v2, v2, s29, v0
	global_load_dwordx4 v[206:209], v2, s[96:97] offset:2048
	v_add_u32_e32 v2, s46, v150
	v_mad_u32_u24 v2, v2, s29, v0
	global_load_dwordx4 v[210:213], v2, s[96:97] offset:2304
	v_add_u32_e32 v2, s46, v152
	v_mad_u32_u24 v2, v2, s29, v0
	global_load_dwordx4 v[214:217], v2, s[96:97] offset:2048
	v_add_u32_e32 v2, s46, v152
	v_mad_u32_u24 v2, v2, s29, v0
	global_load_dwordx4 v[236:239], v2, s[96:97] offset:2304
	v_add_u32_e32 v2, s46, v154
	v_mad_u32_u24 v2, v2, s29, v0
	global_load_dwordx4 v[240:243], v2, s[96:97] offset:2048
	v_add_u32_e32 v2, s46, v154
	v_mad_u32_u24 v2, v2, s29, v0
	global_load_dwordx4 v[244:247], v2, s[96:97] offset:2304
	v_add_u32_e32 v2, s46, v156
	v_mad_u32_u24 v2, v2, s29, v0
	global_load_dwordx4 v[248:251], v2, s[96:97] offset:2048
	s_waitcnt vmcnt(12)
	v_lshlrev_b32_e32 v164, 16, v132
	v_and_b32_e32 v165, 0xffff0000, v132
	v_lshlrev_b32_e32 v166, 16, v133
	v_and_b32_e32 v167, 0xffff0000, v133
	v_lshlrev_b32_e32 v168, 16, v134
	v_and_b32_e32 v169, 0xffff0000, v134
	v_lshlrev_b32_e32 v170, 16, v135
	v_and_b32_e32 v171, 0xffff0000, v135
	v_add_u32_e32 v2, s46, v156
	v_mad_u32_u24 v2, v2, s29, v0
	global_load_dwordx4 v[132:135], v2, s[96:97] offset:2304
	v_add_u32_e32 v1, s46, v144
	v_lshl_add_u32 v1, v1, 11, v0
	v_med3_f32 v164, v164, s34, v227
	v_med3_f32 v165, v165, s34, v227
	v_med3_f32 v166, v166, s34, v227
	v_med3_f32 v167, v167, s34, v227
	v_med3_f32 v168, v168, s34, v227
	v_med3_f32 v169, v169, s34, v227
	v_med3_f32 v170, v170, s34, v227
	v_med3_f32 v171, v171, s34, v227
	v_pk_mul_f32 v[164:165], v[164:165], s[44:45]
	v_pk_mul_f32 v[166:167], v[166:167], s[44:45]
	v_pk_mul_f32 v[168:169], v[168:169], s[44:45]
	v_pk_mul_f32 v[170:171], v[170:171], s[44:45]
	v_exp_f32_e32 v164, v164
	v_exp_f32_e32 v165, v165
	v_exp_f32_e32 v166, v166
	v_exp_f32_e32 v167, v167
	v_exp_f32_e32 v168, v168
	v_exp_f32_e32 v169, v169
	v_exp_f32_e32 v170, v170
	v_exp_f32_e32 v171, v171
	v_pk_add_f32 v[164:165], v[164:165], 1.0 op_sel_hi:[1,0]
	v_pk_add_f32 v[166:167], v[166:167], 1.0 op_sel_hi:[1,0]
	v_pk_add_f32 v[168:169], v[168:169], 1.0 op_sel_hi:[1,0]
	v_pk_add_f32 v[170:171], v[170:171], 1.0 op_sel_hi:[1,0]
	v_rcp_f32_e32 v164, v164
	v_rcp_f32_e32 v165, v165
	v_rcp_f32_e32 v166, v166
	v_rcp_f32_e32 v167, v167
	v_rcp_f32_e32 v168, v168
	v_rcp_f32_e32 v169, v169
	v_rcp_f32_e32 v170, v170
	v_rcp_f32_e32 v171, v171
	v_pk_mul_f32 v[164:165], v[4:5], v[164:165]
	v_pk_mul_f32 v[166:167], v[6:7], v[166:167]
	v_pk_mul_f32 v[168:169], v[8:9], v[168:169]
	v_pk_mul_f32 v[170:171], v[10:11], v[170:171]
	v_cvt_pk_bf16_f32 v174, v164, v165
	v_cvt_pk_bf16_f32 v175, v166, v167
	v_cvt_pk_bf16_f32 v176, v168, v169
	v_cvt_pk_bf16_f32 v177, v170, v171
	global_store_dwordx4 v1, v[174:177], s[22:23] offset:-4096
	s_waitcnt vmcnt(13)
	v_lshlrev_b32_e32 v164, 16, v178
	v_and_b32_e32 v165, 0xffff0000, v178
	v_lshlrev_b32_e32 v166, 16, v179
	v_and_b32_e32 v167, 0xffff0000, v179
	v_lshlrev_b32_e32 v168, 16, v180
	v_and_b32_e32 v169, 0xffff0000, v180
	v_lshlrev_b32_e32 v170, 16, v181
	v_and_b32_e32 v171, 0xffff0000, v181
	v_add_u32_e32 v2, s46, v158
	v_mad_u32_u24 v2, v2, s29, v0
	global_load_dwordx4 v[178:181], v2, s[96:97] offset:2048
	v_med3_f32 v164, v164, s34, v227
	v_med3_f32 v165, v165, s34, v227
	v_med3_f32 v166, v166, s34, v227
	v_med3_f32 v167, v167, s34, v227
	v_med3_f32 v168, v168, s34, v227
	v_med3_f32 v169, v169, s34, v227
	v_med3_f32 v170, v170, s34, v227
	v_med3_f32 v171, v171, s34, v227
	v_pk_mul_f32 v[164:165], v[164:165], s[44:45]
	v_pk_mul_f32 v[166:167], v[166:167], s[44:45]
	v_pk_mul_f32 v[168:169], v[168:169], s[44:45]
	v_pk_mul_f32 v[170:171], v[170:171], s[44:45]
	v_exp_f32_e32 v164, v164
	v_exp_f32_e32 v165, v165
	v_exp_f32_e32 v166, v166
	v_exp_f32_e32 v167, v167
	v_exp_f32_e32 v168, v168
	v_exp_f32_e32 v169, v169
	v_exp_f32_e32 v170, v170
	v_exp_f32_e32 v171, v171
	v_pk_add_f32 v[164:165], v[164:165], 1.0 op_sel_hi:[1,0]
	v_pk_add_f32 v[166:167], v[166:167], 1.0 op_sel_hi:[1,0]
	v_pk_add_f32 v[168:169], v[168:169], 1.0 op_sel_hi:[1,0]
	v_pk_add_f32 v[170:171], v[170:171], 1.0 op_sel_hi:[1,0]
	v_rcp_f32_e32 v164, v164
	v_rcp_f32_e32 v165, v165
	v_rcp_f32_e32 v166, v166
	v_rcp_f32_e32 v167, v167
	v_rcp_f32_e32 v168, v168
	v_rcp_f32_e32 v169, v169
	v_rcp_f32_e32 v170, v170
	v_rcp_f32_e32 v171, v171
	v_pk_mul_f32 v[164:165], v[12:13], v[164:165]
	v_pk_mul_f32 v[166:167], v[14:15], v[166:167]
	v_pk_mul_f32 v[168:169], v[16:17], v[168:169]
	v_pk_mul_f32 v[170:171], v[18:19], v[170:171]
	v_cvt_pk_bf16_f32 v174, v164, v165
	v_cvt_pk_bf16_f32 v175, v166, v167
	v_cvt_pk_bf16_f32 v176, v168, v169
	v_cvt_pk_bf16_f32 v177, v170, v171
	global_store_dwordx4 v1, v[174:177], s[22:23] offset:-3840
	s_waitcnt vmcnt(14)
	v_lshlrev_b32_e32 v164, 16, v182
	v_and_b32_e32 v165, 0xffff0000, v182
	v_lshlrev_b32_e32 v166, 16, v183
	v_and_b32_e32 v167, 0xffff0000, v183
	v_lshlrev_b32_e32 v168, 16, v184
	v_and_b32_e32 v169, 0xffff0000, v184
	v_lshlrev_b32_e32 v170, 16, v185
	v_and_b32_e32 v171, 0xffff0000, v185
	v_add_u32_e32 v2, s46, v158
	v_mad_u32_u24 v2, v2, s29, v0
	global_load_dwordx4 v[182:185], v2, s[96:97] offset:2304
	v_add_u32_e32 v1, s46, v146
	v_lshl_add_u32 v1, v1, 11, v0
	v_med3_f32 v164, v164, s34, v227
	v_med3_f32 v165, v165, s34, v227
	v_med3_f32 v166, v166, s34, v227
	v_med3_f32 v167, v167, s34, v227
	v_med3_f32 v168, v168, s34, v227
	v_med3_f32 v169, v169, s34, v227
	v_med3_f32 v170, v170, s34, v227
	v_med3_f32 v171, v171, s34, v227
	v_pk_mul_f32 v[164:165], v[164:165], s[44:45]
	v_pk_mul_f32 v[166:167], v[166:167], s[44:45]
	v_pk_mul_f32 v[168:169], v[168:169], s[44:45]
	v_pk_mul_f32 v[170:171], v[170:171], s[44:45]
	v_exp_f32_e32 v164, v164
	v_exp_f32_e32 v165, v165
	v_exp_f32_e32 v166, v166
	v_exp_f32_e32 v167, v167
	v_exp_f32_e32 v168, v168
	v_exp_f32_e32 v169, v169
	v_exp_f32_e32 v170, v170
	v_exp_f32_e32 v171, v171
	v_pk_add_f32 v[164:165], v[164:165], 1.0 op_sel_hi:[1,0]
	v_pk_add_f32 v[166:167], v[166:167], 1.0 op_sel_hi:[1,0]
	v_pk_add_f32 v[168:169], v[168:169], 1.0 op_sel_hi:[1,0]
	v_pk_add_f32 v[170:171], v[170:171], 1.0 op_sel_hi:[1,0]
	v_rcp_f32_e32 v164, v164
	v_rcp_f32_e32 v165, v165
	v_rcp_f32_e32 v166, v166
	v_rcp_f32_e32 v167, v167
	v_rcp_f32_e32 v168, v168
	v_rcp_f32_e32 v169, v169
	v_rcp_f32_e32 v170, v170
	v_rcp_f32_e32 v171, v171
	v_pk_mul_f32 v[164:165], v[128:129], v[164:165]
	v_pk_mul_f32 v[166:167], v[130:131], v[166:167]
	v_pk_mul_f32 v[168:169], v[124:125], v[168:169]
	v_pk_mul_f32 v[170:171], v[126:127], v[170:171]
	v_cvt_pk_bf16_f32 v174, v164, v165
	v_cvt_pk_bf16_f32 v175, v166, v167
	v_cvt_pk_bf16_f32 v176, v168, v169
	v_cvt_pk_bf16_f32 v177, v170, v171
	global_store_dwordx4 v1, v[174:177], s[22:23] offset:-4096
	s_waitcnt vmcnt(15)
	v_lshlrev_b32_e32 v164, 16, v186
	v_and_b32_e32 v165, 0xffff0000, v186
	v_lshlrev_b32_e32 v166, 16, v187
	v_and_b32_e32 v167, 0xffff0000, v187
	v_lshlrev_b32_e32 v168, 16, v188
	v_and_b32_e32 v169, 0xffff0000, v188
	v_lshlrev_b32_e32 v170, 16, v189
	v_and_b32_e32 v171, 0xffff0000, v189
	v_med3_f32 v164, v164, s34, v227
	v_med3_f32 v165, v165, s34, v227
	v_med3_f32 v166, v166, s34, v227
	v_med3_f32 v167, v167, s34, v227
	v_med3_f32 v168, v168, s34, v227
	v_med3_f32 v169, v169, s34, v227
	v_med3_f32 v170, v170, s34, v227
	v_med3_f32 v171, v171, s34, v227
	v_pk_mul_f32 v[164:165], v[164:165], s[44:45]
	v_pk_mul_f32 v[166:167], v[166:167], s[44:45]
	v_pk_mul_f32 v[168:169], v[168:169], s[44:45]
	v_pk_mul_f32 v[170:171], v[170:171], s[44:45]
	v_exp_f32_e32 v164, v164
	v_exp_f32_e32 v165, v165
	v_exp_f32_e32 v166, v166
	v_exp_f32_e32 v167, v167
	v_exp_f32_e32 v168, v168
	v_exp_f32_e32 v169, v169
	v_exp_f32_e32 v170, v170
	v_exp_f32_e32 v171, v171
	v_pk_add_f32 v[164:165], v[164:165], 1.0 op_sel_hi:[1,0]
	v_pk_add_f32 v[166:167], v[166:167], 1.0 op_sel_hi:[1,0]
	v_pk_add_f32 v[168:169], v[168:169], 1.0 op_sel_hi:[1,0]
	v_pk_add_f32 v[170:171], v[170:171], 1.0 op_sel_hi:[1,0]
	v_rcp_f32_e32 v164, v164
	v_rcp_f32_e32 v165, v165
	v_rcp_f32_e32 v166, v166
	v_rcp_f32_e32 v167, v167
	v_rcp_f32_e32 v168, v168
	v_rcp_f32_e32 v169, v169
	v_rcp_f32_e32 v170, v170
	v_rcp_f32_e32 v171, v171
	v_pk_mul_f32 v[164:165], v[104:105], v[164:165]
	v_pk_mul_f32 v[166:167], v[106:107], v[166:167]
	v_pk_mul_f32 v[168:169], v[100:101], v[168:169]
	v_pk_mul_f32 v[170:171], v[102:103], v[170:171]
	v_cvt_pk_bf16_f32 v174, v164, v165
	v_cvt_pk_bf16_f32 v175, v166, v167
	v_cvt_pk_bf16_f32 v176, v168, v169
	v_cvt_pk_bf16_f32 v177, v170, v171
	global_store_dwordx4 v1, v[174:177], s[22:23] offset:-3840
	s_waitcnt vmcnt(15)
	v_lshlrev_b32_e32 v164, 16, v190
	v_and_b32_e32 v165, 0xffff0000, v190
	v_lshlrev_b32_e32 v166, 16, v191
	v_and_b32_e32 v167, 0xffff0000, v191
	v_lshlrev_b32_e32 v168, 16, v192
	v_and_b32_e32 v169, 0xffff0000, v192
	v_lshlrev_b32_e32 v170, 16, v193
	v_and_b32_e32 v171, 0xffff0000, v193
	v_add_u32_e32 v1, s46, v148
	v_lshl_add_u32 v1, v1, 11, v0
	v_med3_f32 v164, v164, s34, v227
	v_med3_f32 v165, v165, s34, v227
	v_med3_f32 v166, v166, s34, v227
	v_med3_f32 v167, v167, s34, v227
	v_med3_f32 v168, v168, s34, v227
	v_med3_f32 v169, v169, s34, v227
	v_med3_f32 v170, v170, s34, v227
	v_med3_f32 v171, v171, s34, v227
	v_pk_mul_f32 v[164:165], v[164:165], s[44:45]
	v_pk_mul_f32 v[166:167], v[166:167], s[44:45]
	v_pk_mul_f32 v[168:169], v[168:169], s[44:45]
	v_pk_mul_f32 v[170:171], v[170:171], s[44:45]
	v_exp_f32_e32 v164, v164
	v_exp_f32_e32 v165, v165
	v_exp_f32_e32 v166, v166
	v_exp_f32_e32 v167, v167
	v_exp_f32_e32 v168, v168
	v_exp_f32_e32 v169, v169
	v_exp_f32_e32 v170, v170
	v_exp_f32_e32 v171, v171
	v_pk_add_f32 v[164:165], v[164:165], 1.0 op_sel_hi:[1,0]
	v_pk_add_f32 v[166:167], v[166:167], 1.0 op_sel_hi:[1,0]
	v_pk_add_f32 v[168:169], v[168:169], 1.0 op_sel_hi:[1,0]
	v_pk_add_f32 v[170:171], v[170:171], 1.0 op_sel_hi:[1,0]
	v_rcp_f32_e32 v164, v164
	v_rcp_f32_e32 v165, v165
	v_rcp_f32_e32 v166, v166
	v_rcp_f32_e32 v167, v167
	v_rcp_f32_e32 v168, v168
	v_rcp_f32_e32 v169, v169
	v_rcp_f32_e32 v170, v170
	v_rcp_f32_e32 v171, v171
	v_pk_mul_f32 v[164:165], v[120:121], v[164:165]
	v_pk_mul_f32 v[166:167], v[122:123], v[166:167]
	v_pk_mul_f32 v[168:169], v[116:117], v[168:169]
	v_pk_mul_f32 v[170:171], v[118:119], v[170:171]
	v_cvt_pk_bf16_f32 v174, v164, v165
	v_cvt_pk_bf16_f32 v175, v166, v167
	v_cvt_pk_bf16_f32 v176, v168, v169
	v_cvt_pk_bf16_f32 v177, v170, v171
	global_store_dwordx4 v1, v[174:177], s[22:23] offset:-4096
	s_waitcnt vmcnt(15)
	v_lshlrev_b32_e32 v164, 16, v202
	v_and_b32_e32 v165, 0xffff0000, v202
	v_lshlrev_b32_e32 v166, 16, v203
	v_and_b32_e32 v167, 0xffff0000, v203
	v_lshlrev_b32_e32 v168, 16, v204
	v_and_b32_e32 v169, 0xffff0000, v204
	v_lshlrev_b32_e32 v170, 16, v205
	v_and_b32_e32 v171, 0xffff0000, v205
	v_med3_f32 v164, v164, s34, v227
	v_med3_f32 v165, v165, s34, v227
	v_med3_f32 v166, v166, s34, v227
	v_med3_f32 v167, v167, s34, v227
	v_med3_f32 v168, v168, s34, v227
	v_med3_f32 v169, v169, s34, v227
	v_med3_f32 v170, v170, s34, v227
	v_med3_f32 v171, v171, s34, v227
	v_pk_mul_f32 v[164:165], v[164:165], s[44:45]
	v_pk_mul_f32 v[166:167], v[166:167], s[44:45]
	v_pk_mul_f32 v[168:169], v[168:169], s[44:45]
	v_pk_mul_f32 v[170:171], v[170:171], s[44:45]
	v_exp_f32_e32 v164, v164
	v_exp_f32_e32 v165, v165
	v_exp_f32_e32 v166, v166
	v_exp_f32_e32 v167, v167
	v_exp_f32_e32 v168, v168
	v_exp_f32_e32 v169, v169
	v_exp_f32_e32 v170, v170
	v_exp_f32_e32 v171, v171
	v_pk_add_f32 v[164:165], v[164:165], 1.0 op_sel_hi:[1,0]
	v_pk_add_f32 v[166:167], v[166:167], 1.0 op_sel_hi:[1,0]
	v_pk_add_f32 v[168:169], v[168:169], 1.0 op_sel_hi:[1,0]
	v_pk_add_f32 v[170:171], v[170:171], 1.0 op_sel_hi:[1,0]
	v_rcp_f32_e32 v164, v164
	v_rcp_f32_e32 v165, v165
	v_rcp_f32_e32 v166, v166
	v_rcp_f32_e32 v167, v167
	v_rcp_f32_e32 v168, v168
	v_rcp_f32_e32 v169, v169
	v_rcp_f32_e32 v170, v170
	v_rcp_f32_e32 v171, v171
	v_pk_mul_f32 v[164:165], v[96:97], v[164:165]
	v_pk_mul_f32 v[166:167], v[98:99], v[166:167]
	v_pk_mul_f32 v[168:169], v[92:93], v[168:169]
	v_pk_mul_f32 v[170:171], v[94:95], v[170:171]
	v_cvt_pk_bf16_f32 v174, v164, v165
	v_cvt_pk_bf16_f32 v175, v166, v167
	v_cvt_pk_bf16_f32 v176, v168, v169
	v_cvt_pk_bf16_f32 v177, v170, v171
	global_store_dwordx4 v1, v[174:177], s[22:23] offset:-3840
	s_waitcnt vmcnt(15)
	v_lshlrev_b32_e32 v164, 16, v206
	v_and_b32_e32 v165, 0xffff0000, v206
	v_lshlrev_b32_e32 v166, 16, v207
	v_and_b32_e32 v167, 0xffff0000, v207
	v_lshlrev_b32_e32 v168, 16, v208
	v_and_b32_e32 v169, 0xffff0000, v208
	v_lshlrev_b32_e32 v170, 16, v209
	v_and_b32_e32 v171, 0xffff0000, v209
	v_add_u32_e32 v1, s46, v150
	v_lshl_add_u32 v1, v1, 11, v0
	v_med3_f32 v164, v164, s34, v227
	v_med3_f32 v165, v165, s34, v227
	v_med3_f32 v166, v166, s34, v227
	v_med3_f32 v167, v167, s34, v227
	v_med3_f32 v168, v168, s34, v227
	v_med3_f32 v169, v169, s34, v227
	v_med3_f32 v170, v170, s34, v227
	v_med3_f32 v171, v171, s34, v227
	v_pk_mul_f32 v[164:165], v[164:165], s[44:45]
	v_pk_mul_f32 v[166:167], v[166:167], s[44:45]
	v_pk_mul_f32 v[168:169], v[168:169], s[44:45]
	v_pk_mul_f32 v[170:171], v[170:171], s[44:45]
	v_exp_f32_e32 v164, v164
	v_exp_f32_e32 v165, v165
	v_exp_f32_e32 v166, v166
	v_exp_f32_e32 v167, v167
	v_exp_f32_e32 v168, v168
	v_exp_f32_e32 v169, v169
	v_exp_f32_e32 v170, v170
	v_exp_f32_e32 v171, v171
	v_pk_add_f32 v[164:165], v[164:165], 1.0 op_sel_hi:[1,0]
	v_pk_add_f32 v[166:167], v[166:167], 1.0 op_sel_hi:[1,0]
	v_pk_add_f32 v[168:169], v[168:169], 1.0 op_sel_hi:[1,0]
	v_pk_add_f32 v[170:171], v[170:171], 1.0 op_sel_hi:[1,0]
	v_rcp_f32_e32 v164, v164
	v_rcp_f32_e32 v165, v165
	v_rcp_f32_e32 v166, v166
	v_rcp_f32_e32 v167, v167
	v_rcp_f32_e32 v168, v168
	v_rcp_f32_e32 v169, v169
	v_rcp_f32_e32 v170, v170
	v_rcp_f32_e32 v171, v171
	v_pk_mul_f32 v[164:165], v[112:113], v[164:165]
	v_pk_mul_f32 v[166:167], v[114:115], v[166:167]
	v_pk_mul_f32 v[168:169], v[108:109], v[168:169]
	v_pk_mul_f32 v[170:171], v[110:111], v[170:171]
	v_cvt_pk_bf16_f32 v174, v164, v165
	v_cvt_pk_bf16_f32 v175, v166, v167
	v_cvt_pk_bf16_f32 v176, v168, v169
	v_cvt_pk_bf16_f32 v177, v170, v171
	global_store_dwordx4 v1, v[174:177], s[22:23] offset:-4096
	s_waitcnt vmcnt(15)
	v_lshlrev_b32_e32 v164, 16, v210
	v_and_b32_e32 v165, 0xffff0000, v210
	v_lshlrev_b32_e32 v166, 16, v211
	v_and_b32_e32 v167, 0xffff0000, v211
	v_lshlrev_b32_e32 v168, 16, v212
	v_and_b32_e32 v169, 0xffff0000, v212
	v_lshlrev_b32_e32 v170, 16, v213
	v_and_b32_e32 v171, 0xffff0000, v213
	v_med3_f32 v164, v164, s34, v227
	v_med3_f32 v165, v165, s34, v227
	v_med3_f32 v166, v166, s34, v227
	v_med3_f32 v167, v167, s34, v227
	v_med3_f32 v168, v168, s34, v227
	v_med3_f32 v169, v169, s34, v227
	v_med3_f32 v170, v170, s34, v227
	v_med3_f32 v171, v171, s34, v227
	v_pk_mul_f32 v[164:165], v[164:165], s[44:45]
	v_pk_mul_f32 v[166:167], v[166:167], s[44:45]
	v_pk_mul_f32 v[168:169], v[168:169], s[44:45]
	v_pk_mul_f32 v[170:171], v[170:171], s[44:45]
	v_exp_f32_e32 v164, v164
	v_exp_f32_e32 v165, v165
	v_exp_f32_e32 v166, v166
	v_exp_f32_e32 v167, v167
	v_exp_f32_e32 v168, v168
	v_exp_f32_e32 v169, v169
	v_exp_f32_e32 v170, v170
	v_exp_f32_e32 v171, v171
	v_pk_add_f32 v[164:165], v[164:165], 1.0 op_sel_hi:[1,0]
	v_pk_add_f32 v[166:167], v[166:167], 1.0 op_sel_hi:[1,0]
	v_pk_add_f32 v[168:169], v[168:169], 1.0 op_sel_hi:[1,0]
	v_pk_add_f32 v[170:171], v[170:171], 1.0 op_sel_hi:[1,0]
	v_rcp_f32_e32 v164, v164
	v_rcp_f32_e32 v165, v165
	v_rcp_f32_e32 v166, v166
	v_rcp_f32_e32 v167, v167
	v_rcp_f32_e32 v168, v168
	v_rcp_f32_e32 v169, v169
	v_rcp_f32_e32 v170, v170
	v_rcp_f32_e32 v171, v171
	v_pk_mul_f32 v[164:165], v[88:89], v[164:165]
	v_pk_mul_f32 v[166:167], v[90:91], v[166:167]
	v_pk_mul_f32 v[168:169], v[84:85], v[168:169]
	v_pk_mul_f32 v[170:171], v[86:87], v[170:171]
	v_cvt_pk_bf16_f32 v174, v164, v165
	v_cvt_pk_bf16_f32 v175, v166, v167
	v_cvt_pk_bf16_f32 v176, v168, v169
	v_cvt_pk_bf16_f32 v177, v170, v171
	global_store_dwordx4 v1, v[174:177], s[22:23] offset:-3840
	s_waitcnt vmcnt(15)
	v_lshlrev_b32_e32 v164, 16, v214
	v_and_b32_e32 v165, 0xffff0000, v214
	v_lshlrev_b32_e32 v166, 16, v215
	v_and_b32_e32 v167, 0xffff0000, v215
	v_lshlrev_b32_e32 v168, 16, v216
	v_and_b32_e32 v169, 0xffff0000, v216
	v_lshlrev_b32_e32 v170, 16, v217
	v_and_b32_e32 v171, 0xffff0000, v217
	v_add_u32_e32 v1, s46, v152
	v_lshl_add_u32 v1, v1, 11, v0
	v_med3_f32 v164, v164, s34, v227
	v_med3_f32 v165, v165, s34, v227
	v_med3_f32 v166, v166, s34, v227
	v_med3_f32 v167, v167, s34, v227
	v_med3_f32 v168, v168, s34, v227
	v_med3_f32 v169, v169, s34, v227
	v_med3_f32 v170, v170, s34, v227
	v_med3_f32 v171, v171, s34, v227
	v_pk_mul_f32 v[164:165], v[164:165], s[44:45]
	v_pk_mul_f32 v[166:167], v[166:167], s[44:45]
	v_pk_mul_f32 v[168:169], v[168:169], s[44:45]
	v_pk_mul_f32 v[170:171], v[170:171], s[44:45]
	v_exp_f32_e32 v164, v164
	v_exp_f32_e32 v165, v165
	v_exp_f32_e32 v166, v166
	v_exp_f32_e32 v167, v167
	v_exp_f32_e32 v168, v168
	v_exp_f32_e32 v169, v169
	v_exp_f32_e32 v170, v170
	v_exp_f32_e32 v171, v171
	v_pk_add_f32 v[164:165], v[164:165], 1.0 op_sel_hi:[1,0]
	v_pk_add_f32 v[166:167], v[166:167], 1.0 op_sel_hi:[1,0]
	v_pk_add_f32 v[168:169], v[168:169], 1.0 op_sel_hi:[1,0]
	v_pk_add_f32 v[170:171], v[170:171], 1.0 op_sel_hi:[1,0]
	v_rcp_f32_e32 v164, v164
	v_rcp_f32_e32 v165, v165
	v_rcp_f32_e32 v166, v166
	v_rcp_f32_e32 v167, v167
	v_rcp_f32_e32 v168, v168
	v_rcp_f32_e32 v169, v169
	v_rcp_f32_e32 v170, v170
	v_rcp_f32_e32 v171, v171
	v_pk_mul_f32 v[164:165], v[80:81], v[164:165]
	v_pk_mul_f32 v[166:167], v[82:83], v[166:167]
	v_pk_mul_f32 v[168:169], v[76:77], v[168:169]
	v_pk_mul_f32 v[170:171], v[78:79], v[170:171]
	v_cvt_pk_bf16_f32 v174, v164, v165
	v_cvt_pk_bf16_f32 v175, v166, v167
	v_cvt_pk_bf16_f32 v176, v168, v169
	v_cvt_pk_bf16_f32 v177, v170, v171
	global_store_dwordx4 v1, v[174:177], s[22:23] offset:-4096
	s_waitcnt vmcnt(15)
	v_lshlrev_b32_e32 v164, 16, v236
	v_and_b32_e32 v165, 0xffff0000, v236
	v_lshlrev_b32_e32 v166, 16, v237
	v_and_b32_e32 v167, 0xffff0000, v237
	v_lshlrev_b32_e32 v168, 16, v238
	v_and_b32_e32 v169, 0xffff0000, v238
	v_lshlrev_b32_e32 v170, 16, v239
	v_and_b32_e32 v171, 0xffff0000, v239
	v_med3_f32 v164, v164, s34, v227
	v_med3_f32 v165, v165, s34, v227
	v_med3_f32 v166, v166, s34, v227
	v_med3_f32 v167, v167, s34, v227
	v_med3_f32 v168, v168, s34, v227
	v_med3_f32 v169, v169, s34, v227
	v_med3_f32 v170, v170, s34, v227
	v_med3_f32 v171, v171, s34, v227
	v_pk_mul_f32 v[164:165], v[164:165], s[44:45]
	v_pk_mul_f32 v[166:167], v[166:167], s[44:45]
	v_pk_mul_f32 v[168:169], v[168:169], s[44:45]
	v_pk_mul_f32 v[170:171], v[170:171], s[44:45]
	v_exp_f32_e32 v164, v164
	v_exp_f32_e32 v165, v165
	v_exp_f32_e32 v166, v166
	v_exp_f32_e32 v167, v167
	v_exp_f32_e32 v168, v168
	v_exp_f32_e32 v169, v169
	v_exp_f32_e32 v170, v170
	v_exp_f32_e32 v171, v171
	v_pk_add_f32 v[164:165], v[164:165], 1.0 op_sel_hi:[1,0]
	v_pk_add_f32 v[166:167], v[166:167], 1.0 op_sel_hi:[1,0]
	v_pk_add_f32 v[168:169], v[168:169], 1.0 op_sel_hi:[1,0]
	v_pk_add_f32 v[170:171], v[170:171], 1.0 op_sel_hi:[1,0]
	v_rcp_f32_e32 v164, v164
	v_rcp_f32_e32 v165, v165
	v_rcp_f32_e32 v166, v166
	v_rcp_f32_e32 v167, v167
	v_rcp_f32_e32 v168, v168
	v_rcp_f32_e32 v169, v169
	v_rcp_f32_e32 v170, v170
	v_rcp_f32_e32 v171, v171
	v_pk_mul_f32 v[164:165], v[48:49], v[164:165]
	v_pk_mul_f32 v[166:167], v[50:51], v[166:167]
	v_pk_mul_f32 v[168:169], v[44:45], v[168:169]
	v_pk_mul_f32 v[170:171], v[46:47], v[170:171]
	v_cvt_pk_bf16_f32 v174, v164, v165
	v_cvt_pk_bf16_f32 v175, v166, v167
	v_cvt_pk_bf16_f32 v176, v168, v169
	v_cvt_pk_bf16_f32 v177, v170, v171
	global_store_dwordx4 v1, v[174:177], s[22:23] offset:-3840
	s_waitcnt vmcnt(15)
	v_lshlrev_b32_e32 v164, 16, v240
	v_and_b32_e32 v165, 0xffff0000, v240
	v_lshlrev_b32_e32 v166, 16, v241
	v_and_b32_e32 v167, 0xffff0000, v241
	v_lshlrev_b32_e32 v168, 16, v242
	v_and_b32_e32 v169, 0xffff0000, v242
	v_lshlrev_b32_e32 v170, 16, v243
	v_and_b32_e32 v171, 0xffff0000, v243
	v_add_u32_e32 v1, s46, v154
	v_lshl_add_u32 v1, v1, 11, v0
	v_med3_f32 v164, v164, s34, v227
	v_med3_f32 v165, v165, s34, v227
	v_med3_f32 v166, v166, s34, v227
	v_med3_f32 v167, v167, s34, v227
	v_med3_f32 v168, v168, s34, v227
	v_med3_f32 v169, v169, s34, v227
	v_med3_f32 v170, v170, s34, v227
	v_med3_f32 v171, v171, s34, v227
	v_pk_mul_f32 v[164:165], v[164:165], s[44:45]
	v_pk_mul_f32 v[166:167], v[166:167], s[44:45]
	v_pk_mul_f32 v[168:169], v[168:169], s[44:45]
	v_pk_mul_f32 v[170:171], v[170:171], s[44:45]
	v_exp_f32_e32 v164, v164
	v_exp_f32_e32 v165, v165
	v_exp_f32_e32 v166, v166
	v_exp_f32_e32 v167, v167
	v_exp_f32_e32 v168, v168
	v_exp_f32_e32 v169, v169
	v_exp_f32_e32 v170, v170
	v_exp_f32_e32 v171, v171
	v_pk_add_f32 v[164:165], v[164:165], 1.0 op_sel_hi:[1,0]
	v_pk_add_f32 v[166:167], v[166:167], 1.0 op_sel_hi:[1,0]
	v_pk_add_f32 v[168:169], v[168:169], 1.0 op_sel_hi:[1,0]
	v_pk_add_f32 v[170:171], v[170:171], 1.0 op_sel_hi:[1,0]
	v_rcp_f32_e32 v164, v164
	v_rcp_f32_e32 v165, v165
	v_rcp_f32_e32 v166, v166
	v_rcp_f32_e32 v167, v167
	v_rcp_f32_e32 v168, v168
	v_rcp_f32_e32 v169, v169
	v_rcp_f32_e32 v170, v170
	v_rcp_f32_e32 v171, v171
	v_pk_mul_f32 v[164:165], v[72:73], v[164:165]
	v_pk_mul_f32 v[166:167], v[74:75], v[166:167]
	v_pk_mul_f32 v[168:169], v[68:69], v[168:169]
	v_pk_mul_f32 v[170:171], v[70:71], v[170:171]
	v_cvt_pk_bf16_f32 v174, v164, v165
	v_cvt_pk_bf16_f32 v175, v166, v167
	v_cvt_pk_bf16_f32 v176, v168, v169
	v_cvt_pk_bf16_f32 v177, v170, v171
	global_store_dwordx4 v1, v[174:177], s[22:23] offset:-4096
	s_waitcnt vmcnt(15)
	v_lshlrev_b32_e32 v164, 16, v244
	v_and_b32_e32 v165, 0xffff0000, v244
	v_lshlrev_b32_e32 v166, 16, v245
	v_and_b32_e32 v167, 0xffff0000, v245
	v_lshlrev_b32_e32 v168, 16, v246
	v_and_b32_e32 v169, 0xffff0000, v246
	v_lshlrev_b32_e32 v170, 16, v247
	v_and_b32_e32 v171, 0xffff0000, v247
	v_med3_f32 v164, v164, s34, v227
	v_med3_f32 v165, v165, s34, v227
	v_med3_f32 v166, v166, s34, v227
	v_med3_f32 v167, v167, s34, v227
	v_med3_f32 v168, v168, s34, v227
	v_med3_f32 v169, v169, s34, v227
	v_med3_f32 v170, v170, s34, v227
	v_med3_f32 v171, v171, s34, v227
	v_pk_mul_f32 v[164:165], v[164:165], s[44:45]
	v_pk_mul_f32 v[166:167], v[166:167], s[44:45]
	v_pk_mul_f32 v[168:169], v[168:169], s[44:45]
	v_pk_mul_f32 v[170:171], v[170:171], s[44:45]
	v_exp_f32_e32 v164, v164
	v_exp_f32_e32 v165, v165
	v_exp_f32_e32 v166, v166
	v_exp_f32_e32 v167, v167
	v_exp_f32_e32 v168, v168
	v_exp_f32_e32 v169, v169
	v_exp_f32_e32 v170, v170
	v_exp_f32_e32 v171, v171
	v_pk_add_f32 v[164:165], v[164:165], 1.0 op_sel_hi:[1,0]
	v_pk_add_f32 v[166:167], v[166:167], 1.0 op_sel_hi:[1,0]
	v_pk_add_f32 v[168:169], v[168:169], 1.0 op_sel_hi:[1,0]
	v_pk_add_f32 v[170:171], v[170:171], 1.0 op_sel_hi:[1,0]
	v_rcp_f32_e32 v164, v164
	v_rcp_f32_e32 v165, v165
	v_rcp_f32_e32 v166, v166
	v_rcp_f32_e32 v167, v167
	v_rcp_f32_e32 v168, v168
	v_rcp_f32_e32 v169, v169
	v_rcp_f32_e32 v170, v170
	v_rcp_f32_e32 v171, v171
	v_pk_mul_f32 v[164:165], v[40:41], v[164:165]
	v_pk_mul_f32 v[166:167], v[42:43], v[166:167]
	v_pk_mul_f32 v[168:169], v[36:37], v[168:169]
	v_pk_mul_f32 v[170:171], v[38:39], v[170:171]
	v_cvt_pk_bf16_f32 v174, v164, v165
	v_cvt_pk_bf16_f32 v175, v166, v167
	v_cvt_pk_bf16_f32 v176, v168, v169
	v_cvt_pk_bf16_f32 v177, v170, v171
	global_store_dwordx4 v1, v[174:177], s[22:23] offset:-3840
	s_waitcnt vmcnt(15)
	v_lshlrev_b32_e32 v164, 16, v248
	v_and_b32_e32 v165, 0xffff0000, v248
	v_lshlrev_b32_e32 v166, 16, v249
	v_and_b32_e32 v167, 0xffff0000, v249
	v_lshlrev_b32_e32 v168, 16, v250
	v_and_b32_e32 v169, 0xffff0000, v250
	v_lshlrev_b32_e32 v170, 16, v251
	v_and_b32_e32 v171, 0xffff0000, v251
	v_add_u32_e32 v1, s46, v156
	v_lshl_add_u32 v1, v1, 11, v0
	v_med3_f32 v164, v164, s34, v227
	v_med3_f32 v165, v165, s34, v227
	v_med3_f32 v166, v166, s34, v227
	v_med3_f32 v167, v167, s34, v227
	v_med3_f32 v168, v168, s34, v227
	v_med3_f32 v169, v169, s34, v227
	v_med3_f32 v170, v170, s34, v227
	v_med3_f32 v171, v171, s34, v227
	v_pk_mul_f32 v[164:165], v[164:165], s[44:45]
	v_pk_mul_f32 v[166:167], v[166:167], s[44:45]
	v_pk_mul_f32 v[168:169], v[168:169], s[44:45]
	v_pk_mul_f32 v[170:171], v[170:171], s[44:45]
	v_exp_f32_e32 v164, v164
	v_exp_f32_e32 v165, v165
	v_exp_f32_e32 v166, v166
	v_exp_f32_e32 v167, v167
	v_exp_f32_e32 v168, v168
	v_exp_f32_e32 v169, v169
	v_exp_f32_e32 v170, v170
	v_exp_f32_e32 v171, v171
	v_pk_add_f32 v[164:165], v[164:165], 1.0 op_sel_hi:[1,0]
	v_pk_add_f32 v[166:167], v[166:167], 1.0 op_sel_hi:[1,0]
	v_pk_add_f32 v[168:169], v[168:169], 1.0 op_sel_hi:[1,0]
	v_pk_add_f32 v[170:171], v[170:171], 1.0 op_sel_hi:[1,0]
	v_rcp_f32_e32 v164, v164
	v_rcp_f32_e32 v165, v165
	v_rcp_f32_e32 v166, v166
	v_rcp_f32_e32 v167, v167
	v_rcp_f32_e32 v168, v168
	v_rcp_f32_e32 v169, v169
	v_rcp_f32_e32 v170, v170
	v_rcp_f32_e32 v171, v171
	v_pk_mul_f32 v[164:165], v[64:65], v[164:165]
	v_pk_mul_f32 v[166:167], v[66:67], v[166:167]
	v_pk_mul_f32 v[168:169], v[60:61], v[168:169]
	v_pk_mul_f32 v[170:171], v[62:63], v[170:171]
	v_cvt_pk_bf16_f32 v174, v164, v165
	v_cvt_pk_bf16_f32 v175, v166, v167
	v_cvt_pk_bf16_f32 v176, v168, v169
	v_cvt_pk_bf16_f32 v177, v170, v171
	global_store_dwordx4 v1, v[174:177], s[22:23] offset:-4096
	s_waitcnt vmcnt(15)
	v_lshlrev_b32_e32 v164, 16, v132
	v_and_b32_e32 v165, 0xffff0000, v132
	v_lshlrev_b32_e32 v166, 16, v133
	v_and_b32_e32 v167, 0xffff0000, v133
	v_lshlrev_b32_e32 v168, 16, v134
	v_and_b32_e32 v169, 0xffff0000, v134
	v_lshlrev_b32_e32 v170, 16, v135
	v_and_b32_e32 v171, 0xffff0000, v135
	v_med3_f32 v164, v164, s34, v227
	v_med3_f32 v165, v165, s34, v227
	v_med3_f32 v166, v166, s34, v227
	v_med3_f32 v167, v167, s34, v227
	v_med3_f32 v168, v168, s34, v227
	v_med3_f32 v169, v169, s34, v227
	v_med3_f32 v170, v170, s34, v227
	v_med3_f32 v171, v171, s34, v227
	v_pk_mul_f32 v[164:165], v[164:165], s[44:45]
	v_pk_mul_f32 v[166:167], v[166:167], s[44:45]
	v_pk_mul_f32 v[168:169], v[168:169], s[44:45]
	v_pk_mul_f32 v[170:171], v[170:171], s[44:45]
	v_exp_f32_e32 v164, v164
	v_exp_f32_e32 v165, v165
	v_exp_f32_e32 v166, v166
	v_exp_f32_e32 v167, v167
	v_exp_f32_e32 v168, v168
	v_exp_f32_e32 v169, v169
	v_exp_f32_e32 v170, v170
	v_exp_f32_e32 v171, v171
	v_pk_add_f32 v[164:165], v[164:165], 1.0 op_sel_hi:[1,0]
	v_pk_add_f32 v[166:167], v[166:167], 1.0 op_sel_hi:[1,0]
	v_pk_add_f32 v[168:169], v[168:169], 1.0 op_sel_hi:[1,0]
	v_pk_add_f32 v[170:171], v[170:171], 1.0 op_sel_hi:[1,0]
	v_rcp_f32_e32 v164, v164
	v_rcp_f32_e32 v165, v165
	v_rcp_f32_e32 v166, v166
	v_rcp_f32_e32 v167, v167
	v_rcp_f32_e32 v168, v168
	v_rcp_f32_e32 v169, v169
	v_rcp_f32_e32 v170, v170
	v_rcp_f32_e32 v171, v171
	v_pk_mul_f32 v[164:165], v[32:33], v[164:165]
	v_pk_mul_f32 v[166:167], v[34:35], v[166:167]
	v_pk_mul_f32 v[168:169], v[28:29], v[168:169]
	v_pk_mul_f32 v[170:171], v[30:31], v[170:171]
	v_cvt_pk_bf16_f32 v174, v164, v165
	v_cvt_pk_bf16_f32 v175, v166, v167
	v_cvt_pk_bf16_f32 v176, v168, v169
	v_cvt_pk_bf16_f32 v177, v170, v171
	global_store_dwordx4 v1, v[174:177], s[22:23] offset:-3840
	s_waitcnt vmcnt(14)
	v_lshlrev_b32_e32 v164, 16, v178
	v_and_b32_e32 v165, 0xffff0000, v178
	v_lshlrev_b32_e32 v166, 16, v179
	v_and_b32_e32 v167, 0xffff0000, v179
	v_lshlrev_b32_e32 v168, 16, v180
	v_and_b32_e32 v169, 0xffff0000, v180
	v_lshlrev_b32_e32 v170, 16, v181
	v_and_b32_e32 v171, 0xffff0000, v181
	v_add_u32_e32 v1, s46, v158
	v_lshl_add_u32 v1, v1, 11, v0
	v_med3_f32 v164, v164, s34, v227
	v_med3_f32 v165, v165, s34, v227
	v_med3_f32 v166, v166, s34, v227
	v_med3_f32 v167, v167, s34, v227
	v_med3_f32 v168, v168, s34, v227
	v_med3_f32 v169, v169, s34, v227
	v_med3_f32 v170, v170, s34, v227
	v_med3_f32 v171, v171, s34, v227
	v_pk_mul_f32 v[164:165], v[164:165], s[44:45]
	v_pk_mul_f32 v[166:167], v[166:167], s[44:45]
	v_pk_mul_f32 v[168:169], v[168:169], s[44:45]
	v_pk_mul_f32 v[170:171], v[170:171], s[44:45]
	v_exp_f32_e32 v164, v164
	v_exp_f32_e32 v165, v165
	v_exp_f32_e32 v166, v166
	v_exp_f32_e32 v167, v167
	v_exp_f32_e32 v168, v168
	v_exp_f32_e32 v169, v169
	v_exp_f32_e32 v170, v170
	v_exp_f32_e32 v171, v171
	v_pk_add_f32 v[164:165], v[164:165], 1.0 op_sel_hi:[1,0]
	v_pk_add_f32 v[166:167], v[166:167], 1.0 op_sel_hi:[1,0]
	v_pk_add_f32 v[168:169], v[168:169], 1.0 op_sel_hi:[1,0]
	v_pk_add_f32 v[170:171], v[170:171], 1.0 op_sel_hi:[1,0]
	v_rcp_f32_e32 v164, v164
	v_rcp_f32_e32 v165, v165
	v_rcp_f32_e32 v166, v166
	v_rcp_f32_e32 v167, v167
	v_rcp_f32_e32 v168, v168
	v_rcp_f32_e32 v169, v169
	v_rcp_f32_e32 v170, v170
	v_rcp_f32_e32 v171, v171
	v_pk_mul_f32 v[164:165], v[56:57], v[164:165]
	v_pk_mul_f32 v[166:167], v[58:59], v[166:167]
	v_pk_mul_f32 v[168:169], v[52:53], v[168:169]
	v_pk_mul_f32 v[170:171], v[54:55], v[170:171]
	v_cvt_pk_bf16_f32 v174, v164, v165
	v_cvt_pk_bf16_f32 v175, v166, v167
	v_cvt_pk_bf16_f32 v176, v168, v169
	v_cvt_pk_bf16_f32 v177, v170, v171
	global_store_dwordx4 v1, v[174:177], s[22:23] offset:-4096
	s_waitcnt vmcnt(13)
	v_lshlrev_b32_e32 v164, 16, v182
	v_and_b32_e32 v165, 0xffff0000, v182
	v_lshlrev_b32_e32 v166, 16, v183
	v_and_b32_e32 v167, 0xffff0000, v183
	v_lshlrev_b32_e32 v168, 16, v184
	v_and_b32_e32 v169, 0xffff0000, v184
	v_lshlrev_b32_e32 v170, 16, v185
	v_and_b32_e32 v171, 0xffff0000, v185
	v_med3_f32 v164, v164, s34, v227
	v_med3_f32 v165, v165, s34, v227
	v_med3_f32 v166, v166, s34, v227
	v_med3_f32 v167, v167, s34, v227
	v_med3_f32 v168, v168, s34, v227
	v_med3_f32 v169, v169, s34, v227
	v_med3_f32 v170, v170, s34, v227
	v_med3_f32 v171, v171, s34, v227
	v_pk_mul_f32 v[164:165], v[164:165], s[44:45]
	v_pk_mul_f32 v[166:167], v[166:167], s[44:45]
	v_pk_mul_f32 v[168:169], v[168:169], s[44:45]
	v_pk_mul_f32 v[170:171], v[170:171], s[44:45]
	v_exp_f32_e32 v164, v164
	v_exp_f32_e32 v165, v165
	v_exp_f32_e32 v166, v166
	v_exp_f32_e32 v167, v167
	v_exp_f32_e32 v168, v168
	v_exp_f32_e32 v169, v169
	v_exp_f32_e32 v170, v170
	v_exp_f32_e32 v171, v171
	v_pk_add_f32 v[164:165], v[164:165], 1.0 op_sel_hi:[1,0]
	v_pk_add_f32 v[166:167], v[166:167], 1.0 op_sel_hi:[1,0]
	v_pk_add_f32 v[168:169], v[168:169], 1.0 op_sel_hi:[1,0]
	v_pk_add_f32 v[170:171], v[170:171], 1.0 op_sel_hi:[1,0]
	v_rcp_f32_e32 v164, v164
	v_rcp_f32_e32 v165, v165
	v_rcp_f32_e32 v166, v166
	v_rcp_f32_e32 v167, v167
	v_rcp_f32_e32 v168, v168
	v_rcp_f32_e32 v169, v169
	v_rcp_f32_e32 v170, v170
	v_rcp_f32_e32 v171, v171
	v_pk_mul_f32 v[164:165], v[24:25], v[164:165]
	v_pk_mul_f32 v[166:167], v[26:27], v[166:167]
	v_pk_mul_f32 v[168:169], v[20:21], v[168:169]
	v_pk_mul_f32 v[170:171], v[22:23], v[170:171]
	v_cvt_pk_bf16_f32 v174, v164, v165
	v_cvt_pk_bf16_f32 v175, v166, v167
	v_cvt_pk_bf16_f32 v176, v168, v169
	v_cvt_pk_bf16_f32 v177, v170, v171
	global_store_dwordx4 v1, v[174:177], s[22:23] offset:-3840
	s_mov_b64 s[40:41], 0
	s_branch .LBB0_206

.LBB0_242:
	s_add_u32 s23, s0, 0xfffc0080
	s_addc_u32 s24, s1, -1
	s_add_i32 s25, 0, 0x10000
	v_add_u32_e32 v2, s25, v187
	ds_read_b128 v[132:135], v2
	ds_read_b128 v[136:139], v2 offset:1024
	ds_read_b128 v[140:143], v2 offset:2048
	ds_read_b128 v[144:147], v2 offset:3072
	s_cmp_eq_u32 s22, 12
	s_cselect_b32 s47, s57, s24
	s_cselect_b32 s46, s56, s23
	s_cselect_b32 s45, s59, s21
	s_cselect_b32 s44, s58, s20
	v_lshl_add_u64 v[208:209], s[0:1], 0, v[194:195]
	s_add_i32 m0, s67, 0xc000
	ds_read_b128 v[148:151], v240
	ds_read_b128 v[152:155], v240 offset:1024
	ds_read_b128 v[156:159], v240 offset:2048
	ds_read_b128 v[160:163], v240 offset:3072
	ds_read_b128 v[164:167], v240 offset:4096
	ds_read_b128 v[168:171], v240 offset:5120
	ds_read_b128 v[172:175], v240 offset:6144
	ds_read_b128 v[204:207], v240 offset:7168
	global_load_lds_dwordx4 v[208:209], off
	v_lshl_add_u64 v[208:209], s[0:1], 0, v[202:203]
	s_add_i32 m0, s67, 0xe000
	s_nop 0
	global_load_lds_dwordx4 v[208:209], off
	s_waitcnt lgkmcnt(8)
	s_barrier
	s_waitcnt lgkmcnt(0)
	v_mfma_f32_16x16x32_bf16 v[128:131], v[132:135], v[148:151], v[128:131]
	v_mfma_f32_16x16x32_bf16 v[124:127], v[140:143], v[148:151], v[124:127]
	v_mfma_f32_16x16x32_bf16 v[120:123], v[132:135], v[156:159], v[120:123]
	v_mfma_f32_16x16x32_bf16 v[116:119], v[140:143], v[156:159], v[116:119]
	v_mfma_f32_16x16x32_bf16 v[112:115], v[132:135], v[164:167], v[112:115]
	v_mfma_f32_16x16x32_bf16 v[108:111], v[140:143], v[164:167], v[108:111]
	v_mfma_f32_16x16x32_bf16 v[104:107], v[132:135], v[172:175], v[104:107]
	v_mfma_f32_16x16x32_bf16 v[100:103], v[140:143], v[172:175], v[100:103]
	v_mfma_f32_16x16x32_bf16 v[128:131], v[136:139], v[152:155], v[128:131]
	v_mfma_f32_16x16x32_bf16 v[124:127], v[144:147], v[152:155], v[124:127]
	v_mfma_f32_16x16x32_bf16 v[120:123], v[136:139], v[160:163], v[120:123]
	v_mfma_f32_16x16x32_bf16 v[116:119], v[144:147], v[160:163], v[116:119]
	v_mfma_f32_16x16x32_bf16 v[112:115], v[136:139], v[168:171], v[112:115]
	v_mfma_f32_16x16x32_bf16 v[108:111], v[144:147], v[168:171], v[108:111]
	v_mfma_f32_16x16x32_bf16 v[104:107], v[136:139], v[204:207], v[104:107]
	v_mfma_f32_16x16x32_bf16 v[100:103], v[144:147], v[204:207], v[100:103]
	s_barrier
	s_add_i32 s23, 0, 0x14000
	s_add_i32 s24, s25, s61
	v_add_u32_e32 v2, s23, v187
	v_lshl_add_u64 v[222:223], s[44:45], 0, v[176:177]
	s_mov_b32 m0, s24
	ds_read_b128 v[208:211], v2
	ds_read_b128 v[212:215], v2 offset:1024
	ds_read_b128 v[242:245], v2 offset:2048
	ds_read_b128 v[246:249], v2 offset:3072
	global_load_lds_dwordx4 v[222:223], off
	v_lshl_add_u64 v[250:251], s[44:45], 0, v[180:181]
	s_add_i32 m0, s24, 0x2000
	s_nop 0
	global_load_lds_dwordx4 v[250:251], off
	s_barrier
	s_waitcnt lgkmcnt(0)
	v_mfma_f32_16x16x32_bf16 v[64:67], v[208:211], v[148:151], v[64:67]
	v_mfma_f32_16x16x32_bf16 v[60:63], v[242:245], v[148:151], v[60:63]
	v_mfma_f32_16x16x32_bf16 v[56:59], v[208:211], v[156:159], v[56:59]
	v_mfma_f32_16x16x32_bf16 v[52:55], v[242:245], v[156:159], v[52:55]
	v_mfma_f32_16x16x32_bf16 v[48:51], v[208:211], v[164:167], v[48:51]
	v_mfma_f32_16x16x32_bf16 v[44:47], v[242:245], v[164:167], v[44:47]
	v_mfma_f32_16x16x32_bf16 v[40:43], v[208:211], v[172:175], v[40:43]
	v_mfma_f32_16x16x32_bf16 v[36:39], v[242:245], v[172:175], v[36:39]
	v_mfma_f32_16x16x32_bf16 v[64:67], v[212:215], v[152:155], v[64:67]
	v_mfma_f32_16x16x32_bf16 v[60:63], v[246:249], v[152:155], v[60:63]
	v_mfma_f32_16x16x32_bf16 v[56:59], v[212:215], v[160:163], v[56:59]
	v_mfma_f32_16x16x32_bf16 v[52:55], v[246:249], v[160:163], v[52:55]
	v_mfma_f32_16x16x32_bf16 v[48:51], v[212:215], v[168:171], v[48:51]
	v_mfma_f32_16x16x32_bf16 v[44:47], v[246:249], v[168:171], v[44:47]
	v_mfma_f32_16x16x32_bf16 v[40:43], v[212:215], v[204:207], v[40:43]
	v_mfma_f32_16x16x32_bf16 v[36:39], v[246:249], v[204:207], v[36:39]
	s_mov_b32 m0, s67
	v_lshl_add_u64 v[216:217], s[46:47], 0, v[0:1]
	s_barrier
	ds_read_b128 v[148:151], v240 offset:16384
	ds_read_b128 v[152:155], v240 offset:17408
	ds_read_b128 v[156:159], v240 offset:18432
	ds_read_b128 v[160:163], v240 offset:19456
	ds_read_b128 v[164:167], v240 offset:20480
	ds_read_b128 v[168:171], v240 offset:21504
	ds_read_b128 v[172:175], v240 offset:22528
	ds_read_b128 v[204:207], v240 offset:23552
	global_load_lds_dwordx4 v[216:217], off
	v_lshl_add_u64 v[236:237], s[46:47], 0, v[178:179]
	s_mov_b32 m0, s74
	s_nop 0
	global_load_lds_dwordx4 v[236:237], off
	s_barrier
	s_waitcnt lgkmcnt(0)
	v_mfma_f32_16x16x32_bf16 v[96:99], v[132:135], v[148:151], v[96:99]
	v_mfma_f32_16x16x32_bf16 v[92:95], v[140:143], v[148:151], v[92:95]
	v_mfma_f32_16x16x32_bf16 v[88:91], v[132:135], v[156:159], v[88:91]
	v_mfma_f32_16x16x32_bf16 v[84:87], v[140:143], v[156:159], v[84:87]
	v_mfma_f32_16x16x32_bf16 v[80:83], v[132:135], v[164:167], v[80:83]
	v_mfma_f32_16x16x32_bf16 v[76:79], v[140:143], v[164:167], v[76:79]
	v_mfma_f32_16x16x32_bf16 v[72:75], v[132:135], v[172:175], v[72:75]
	v_mfma_f32_16x16x32_bf16 v[68:71], v[140:143], v[172:175], v[68:71]
	v_mfma_f32_16x16x32_bf16 v[96:99], v[136:139], v[152:155], v[96:99]
	v_mfma_f32_16x16x32_bf16 v[92:95], v[144:147], v[152:155], v[92:95]
	v_mfma_f32_16x16x32_bf16 v[88:91], v[136:139], v[160:163], v[88:91]
	v_mfma_f32_16x16x32_bf16 v[84:87], v[144:147], v[160:163], v[84:87]
	v_mfma_f32_16x16x32_bf16 v[80:83], v[136:139], v[168:171], v[80:83]
	v_mfma_f32_16x16x32_bf16 v[76:79], v[144:147], v[168:171], v[76:79]
	v_mfma_f32_16x16x32_bf16 v[72:75], v[136:139], v[204:207], v[72:75]
	v_mfma_f32_16x16x32_bf16 v[68:71], v[144:147], v[204:207], v[68:71]
	s_barrier
	s_add_u32 s24, s44, 0x40000
	s_addc_u32 s25, s45, 0
	s_add_i32 s23, s23, s61
	v_lshl_add_u64 v[132:133], s[24:25], 0, v[176:177]
	s_mov_b32 m0, s23
	s_nop 0
	global_load_lds_dwordx4 v[132:133], off
	v_lshl_add_u64 v[132:133], s[24:25], 0, v[180:181]
	s_add_i32 m0, s23, 0x2000
	s_nop 0
	global_load_lds_dwordx4 v[132:133], off
	s_waitcnt vmcnt(6)
	s_barrier
	v_mfma_f32_16x16x32_bf16 v[32:35], v[208:211], v[148:151], v[32:35]
	v_mfma_f32_16x16x32_bf16 v[28:31], v[242:245], v[148:151], v[28:31]
	v_mfma_f32_16x16x32_bf16 v[24:27], v[208:211], v[156:159], v[24:27]
	v_mfma_f32_16x16x32_bf16 v[20:23], v[242:245], v[156:159], v[20:23]
	v_mfma_f32_16x16x32_bf16 v[16:19], v[208:211], v[164:167], v[16:19]
	v_mfma_f32_16x16x32_bf16 v[12:15], v[242:245], v[164:167], v[12:15]
	v_mfma_f32_16x16x32_bf16 v[8:11], v[208:211], v[172:175], v[8:11]
	v_mfma_f32_16x16x32_bf16 v[4:7], v[242:245], v[172:175], v[4:7]
	v_mfma_f32_16x16x32_bf16 v[32:35], v[212:215], v[152:155], v[32:35]
	v_mfma_f32_16x16x32_bf16 v[28:31], v[246:249], v[152:155], v[28:31]
	v_mfma_f32_16x16x32_bf16 v[24:27], v[212:215], v[160:163], v[24:27]
	v_mfma_f32_16x16x32_bf16 v[20:23], v[246:249], v[160:163], v[20:23]
	v_mfma_f32_16x16x32_bf16 v[16:19], v[212:215], v[168:171], v[16:19]
	v_mfma_f32_16x16x32_bf16 v[12:15], v[246:249], v[168:171], v[12:15]
	v_mfma_f32_16x16x32_bf16 v[8:11], v[212:215], v[204:207], v[8:11]
	v_mfma_f32_16x16x32_bf16 v[4:7], v[246:249], v[204:207], v[4:7]
	s_add_i32 s23, 0, 0x18000
	v_add_u32_e32 v2, s23, v187
	s_barrier
	ds_read_b128 v[132:135], v2
	ds_read_b128 v[136:139], v2 offset:1024
	ds_read_b128 v[140:143], v2 offset:2048
	ds_read_b128 v[144:147], v2 offset:3072
	s_add_u32 s24, s46, 0x40000
	s_addc_u32 s25, s47, 0
	s_mov_b32 m0, s75
	v_lshl_add_u64 v[208:209], s[24:25], 0, v[0:1]
	ds_read_b128 v[148:151], v240 offset:32768
	ds_read_b128 v[152:155], v240 offset:33792
	ds_read_b128 v[156:159], v240 offset:34816
	ds_read_b128 v[160:163], v240 offset:35840
	ds_read_b128 v[164:167], v240 offset:36864
	ds_read_b128 v[168:171], v240 offset:37888
	ds_read_b128 v[172:175], v240 offset:38912
	ds_read_b128 v[204:207], v240 offset:39936
	global_load_lds_dwordx4 v[208:209], off
	v_lshl_add_u64 v[208:209], s[24:25], 0, v[178:179]
	s_mov_b32 m0, s82
	s_nop 0
	global_load_lds_dwordx4 v[208:209], off
	s_waitcnt lgkmcnt(8)
	s_barrier
	s_waitcnt lgkmcnt(0)
	v_mfma_f32_16x16x32_bf16 v[128:131], v[132:135], v[148:151], v[128:131]
	v_mfma_f32_16x16x32_bf16 v[124:127], v[140:143], v[148:151], v[124:127]
	v_mfma_f32_16x16x32_bf16 v[120:123], v[132:135], v[156:159], v[120:123]
	v_mfma_f32_16x16x32_bf16 v[116:119], v[140:143], v[156:159], v[116:119]
	v_mfma_f32_16x16x32_bf16 v[112:115], v[132:135], v[164:167], v[112:115]
	v_mfma_f32_16x16x32_bf16 v[108:111], v[140:143], v[164:167], v[108:111]
	v_mfma_f32_16x16x32_bf16 v[104:107], v[132:135], v[172:175], v[104:107]
	v_mfma_f32_16x16x32_bf16 v[100:103], v[140:143], v[172:175], v[100:103]
	v_mfma_f32_16x16x32_bf16 v[128:131], v[136:139], v[152:155], v[128:131]
	v_mfma_f32_16x16x32_bf16 v[124:127], v[144:147], v[152:155], v[124:127]
	v_mfma_f32_16x16x32_bf16 v[120:123], v[136:139], v[160:163], v[120:123]
	v_mfma_f32_16x16x32_bf16 v[116:119], v[144:147], v[160:163], v[116:119]
	v_mfma_f32_16x16x32_bf16 v[112:115], v[136:139], v[168:171], v[112:115]
	v_mfma_f32_16x16x32_bf16 v[108:111], v[144:147], v[168:171], v[108:111]
	v_mfma_f32_16x16x32_bf16 v[104:107], v[136:139], v[204:207], v[104:107]
	v_mfma_f32_16x16x32_bf16 v[100:103], v[144:147], v[204:207], v[100:103]
	s_barrier
	s_add_i32 s26, 0, 0x1c000
	s_add_i32 s23, s23, s61
	v_add_u32_e32 v2, s26, v187
	v_lshl_add_u64 v[222:223], v[222:223], 0, s[76:77]
	s_mov_b32 m0, s23
	ds_read_b128 v[208:211], v2
	ds_read_b128 v[212:215], v2 offset:1024
	ds_read_b128 v[242:245], v2 offset:2048
	ds_read_b128 v[246:249], v2 offset:3072
	global_load_lds_dwordx4 v[222:223], off
	v_lshl_add_u64 v[222:223], v[250:251], 0, s[76:77]
	s_add_i32 m0, s23, 0x2000
	s_nop 0
	global_load_lds_dwordx4 v[222:223], off
	s_barrier
	s_waitcnt lgkmcnt(0)
	v_mfma_f32_16x16x32_bf16 v[64:67], v[208:211], v[148:151], v[64:67]
	v_mfma_f32_16x16x32_bf16 v[60:63], v[242:245], v[148:151], v[60:63]
	v_mfma_f32_16x16x32_bf16 v[56:59], v[208:211], v[156:159], v[56:59]
	v_mfma_f32_16x16x32_bf16 v[52:55], v[242:245], v[156:159], v[52:55]
	v_mfma_f32_16x16x32_bf16 v[48:51], v[208:211], v[164:167], v[48:51]
	v_mfma_f32_16x16x32_bf16 v[44:47], v[242:245], v[164:167], v[44:47]
	v_mfma_f32_16x16x32_bf16 v[40:43], v[208:211], v[172:175], v[40:43]
	v_mfma_f32_16x16x32_bf16 v[36:39], v[242:245], v[172:175], v[36:39]
	v_mfma_f32_16x16x32_bf16 v[64:67], v[212:215], v[152:155], v[64:67]
	v_mfma_f32_16x16x32_bf16 v[60:63], v[246:249], v[152:155], v[60:63]
	v_mfma_f32_16x16x32_bf16 v[56:59], v[212:215], v[160:163], v[56:59]
	v_mfma_f32_16x16x32_bf16 v[52:55], v[246:249], v[160:163], v[52:55]
	v_mfma_f32_16x16x32_bf16 v[48:51], v[212:215], v[168:171], v[48:51]
	v_mfma_f32_16x16x32_bf16 v[44:47], v[246:249], v[168:171], v[44:47]
	v_mfma_f32_16x16x32_bf16 v[40:43], v[212:215], v[204:207], v[40:43]
	v_mfma_f32_16x16x32_bf16 v[36:39], v[246:249], v[204:207], v[36:39]
	s_mov_b32 m0, s48
	v_lshl_add_u64 v[216:217], v[216:217], 0, s[76:77]
	s_barrier
	ds_read_b128 v[148:151], v240 offset:49152
	ds_read_b128 v[152:155], v240 offset:50176
	ds_read_b128 v[156:159], v240 offset:51200
	ds_read_b128 v[160:163], v240 offset:52224
	ds_read_b128 v[164:167], v240 offset:53248
	ds_read_b128 v[168:171], v240 offset:54272
	ds_read_b128 v[172:175], v240 offset:55296
	ds_read_b128 v[204:207], v240 offset:56320
	global_load_lds_dwordx4 v[216:217], off
	v_lshl_add_u64 v[216:217], v[236:237], 0, s[76:77]
	s_mov_b32 m0, s50
	s_nop 0
	global_load_lds_dwordx4 v[216:217], off
	s_barrier
	s_waitcnt lgkmcnt(0)
	v_mfma_f32_16x16x32_bf16 v[96:99], v[132:135], v[148:151], v[96:99]
	v_mfma_f32_16x16x32_bf16 v[92:95], v[140:143], v[148:151], v[92:95]
	v_mfma_f32_16x16x32_bf16 v[88:91], v[132:135], v[156:159], v[88:91]
	v_mfma_f32_16x16x32_bf16 v[84:87], v[140:143], v[156:159], v[84:87]
	v_mfma_f32_16x16x32_bf16 v[80:83], v[132:135], v[164:167], v[80:83]
	v_mfma_f32_16x16x32_bf16 v[76:79], v[140:143], v[164:167], v[76:79]
	v_mfma_f32_16x16x32_bf16 v[72:75], v[132:135], v[172:175], v[72:75]
	v_mfma_f32_16x16x32_bf16 v[68:71], v[140:143], v[172:175], v[68:71]
	v_mfma_f32_16x16x32_bf16 v[96:99], v[136:139], v[152:155], v[96:99]
	v_mfma_f32_16x16x32_bf16 v[92:95], v[144:147], v[152:155], v[92:95]
	v_mfma_f32_16x16x32_bf16 v[88:91], v[136:139], v[160:163], v[88:91]
	v_mfma_f32_16x16x32_bf16 v[84:87], v[144:147], v[160:163], v[84:87]
	v_mfma_f32_16x16x32_bf16 v[80:83], v[136:139], v[168:171], v[80:83]
	v_mfma_f32_16x16x32_bf16 v[76:79], v[144:147], v[168:171], v[76:79]
	v_mfma_f32_16x16x32_bf16 v[72:75], v[136:139], v[204:207], v[72:75]
	v_mfma_f32_16x16x32_bf16 v[68:71], v[144:147], v[204:207], v[68:71]
	s_barrier
	s_add_u32 s24, s44, 0x40080
	s_addc_u32 s25, s45, 0
	s_add_i32 s23, s26, s61
	v_lshl_add_u64 v[132:133], s[24:25], 0, v[176:177]
	s_mov_b32 m0, s23
	s_nop 0
	global_load_lds_dwordx4 v[132:133], off
	v_lshl_add_u64 v[132:133], s[24:25], 0, v[180:181]
	s_add_i32 m0, s23, 0x2000
	s_nop 0
	global_load_lds_dwordx4 v[132:133], off
	s_waitcnt vmcnt(6)
	s_barrier
	v_mfma_f32_16x16x32_bf16 v[32:35], v[208:211], v[148:151], v[32:35]
	v_mfma_f32_16x16x32_bf16 v[28:31], v[242:245], v[148:151], v[28:31]
	v_mfma_f32_16x16x32_bf16 v[24:27], v[208:211], v[156:159], v[24:27]
	v_mfma_f32_16x16x32_bf16 v[20:23], v[242:245], v[156:159], v[20:23]
	v_mfma_f32_16x16x32_bf16 v[16:19], v[208:211], v[164:167], v[16:19]
	v_mfma_f32_16x16x32_bf16 v[12:15], v[242:245], v[164:167], v[12:15]
	v_mfma_f32_16x16x32_bf16 v[8:11], v[208:211], v[172:175], v[8:11]
	v_mfma_f32_16x16x32_bf16 v[4:7], v[242:245], v[172:175], v[4:7]
	v_mfma_f32_16x16x32_bf16 v[32:35], v[212:215], v[152:155], v[32:35]
	v_mfma_f32_16x16x32_bf16 v[28:31], v[246:249], v[152:155], v[28:31]
	v_mfma_f32_16x16x32_bf16 v[24:27], v[212:215], v[160:163], v[24:27]
	v_mfma_f32_16x16x32_bf16 v[20:23], v[246:249], v[160:163], v[20:23]
	v_mfma_f32_16x16x32_bf16 v[16:19], v[212:215], v[168:171], v[16:19]
	v_mfma_f32_16x16x32_bf16 v[12:15], v[246:249], v[168:171], v[12:15]
	v_mfma_f32_16x16x32_bf16 v[8:11], v[212:215], v[204:207], v[8:11]
	v_mfma_f32_16x16x32_bf16 v[4:7], v[246:249], v[204:207], v[4:7]
	s_add_i32 s22, s22, 2
	s_add_u32 s0, s0, 0x100
	s_addc_u32 s1, s1, 0
	s_add_u32 s20, s20, 0x100
	s_addc_u32 s21, s21, 0
	s_cmp_gt_u32 s22, 13
	s_barrier
	s_cbranch_scc0 .LBB0_242
	s_add_i32 s0, s66, -8
	s_cmp_lt_u32 s0, 12
	s_mov_b64 s[0:1], -1
	s_cbranch_scc1 .LBB0_266
	s_cmp_gt_i32 s66, 33
	s_cselect_b64 s[64:65], -1, 0
	s_lshl_b32 s0, s66, 8
	s_lshl_b32 s53, s60, 8
	s_add_i32 s1, s0, 0xffffee00
	s_cmp_lt_i32 s66, 26
	v_cndmask_b32_e64 v2, 0, 1, s[80:81]
	s_cselect_b32 s62, s0, s1
	s_mov_b64 s[0:1], -1
	s_and_b64 vcc, exec, s[64:65]
	v_cmp_ne_u32_e64 s[44:45], 1, v2
	s_cbranch_vccz .LBB0_248
	s_and_b64 vcc, exec, s[44:45]
	s_cbranch_vccnz .LBB0_247
	v_add_u32_e32 v132, s53, v185
	v_ashrrev_i32_e32 v133, 31, v132
	v_lshlrev_b64 v[140:141], 7, v[132:133]
	global_load_dwordx4 v[132:135], v[188:189], off offset:16
	global_load_dwordx4 v[136:139], v[188:189], off
	s_mov_b32 s3, 0xbfb8aa3b
	s_mov_b32 s2, 0x800000
	s_mov_b32 s5, 0x3f317217
	s_mov_b32 s6, 0x7f800000
	s_waitcnt vmcnt(0)
	v_add_f32_e32 v147, v126, v134
	v_add_f32_e32 v2, v128, v136
	v_max_f32_e32 v142, 0, v2
	v_mul_f32_e64 v2, |v2|, s3
	v_exp_f32_e32 v2, v2
	v_add_f32_e32 v136, v124, v132
	v_add_f32_e32 v149, v127, v135
	v_add_f32_e32 v2, 1.0, v2
	v_cmp_gt_f32_e32 vcc, s2, v2
	s_nop 1
	v_cndmask_b32_e64 v132, 0, 32, vcc
	v_ldexp_f32 v2, v2, v132
	v_log_f32_e32 v2, v2
	s_nop 0
	v_mul_f32_e32 v132, 0x3f317217, v2
	v_fma_f32 v132, v2, s5, -v132
	v_fmac_f32_e32 v132, 0x3377d1cf, v2
	v_fmac_f32_e32 v132, 0x3f317217, v2
	v_cmp_lt_f32_e64 s[0:1], |v2|, s6
	s_nop 1
	v_cndmask_b32_e64 v2, v2, v132, s[0:1]
	v_cndmask_b32_e32 v132, 0, v228, vcc
	v_sub_f32_e32 v144, v2, v132
	v_mul_f32_e64 v2, |v136|, s3
	v_exp_f32_e32 v2, v2
	v_max_f32_e32 v132, 0, v136
	v_add_f32_e32 v2, 1.0, v2
	v_cmp_gt_f32_e32 vcc, s2, v2
	s_nop 1
	v_cndmask_b32_e64 v136, 0, 32, vcc
	v_ldexp_f32 v2, v2, v136
	v_log_f32_e32 v2, v2
	s_nop 0
	v_mul_f32_e32 v136, 0x3f317217, v2
	v_fma_f32 v136, v2, s5, -v136
	v_fmac_f32_e32 v136, 0x3377d1cf, v2
	v_fmac_f32_e32 v136, 0x3f317217, v2
	v_cmp_lt_f32_e64 s[0:1], |v2|, s6
	s_nop 1
	v_cndmask_b32_e64 v2, v2, v136, s[0:1]
	v_cndmask_b32_e32 v136, 0, v228, vcc
	v_sub_f32_e32 v136, v2, v136
	v_add_f32_e32 v2, v129, v137
	v_max_f32_e32 v143, 0, v2
	v_mul_f32_e64 v2, |v2|, s3
	v_exp_f32_e32 v2, v2
	v_add_f32_e32 v137, v125, v133
	v_add_f32_e32 v2, 1.0, v2
	v_cmp_gt_f32_e32 vcc, s2, v2
	s_nop 1
	v_cndmask_b32_e64 v133, 0, 32, vcc
	v_ldexp_f32 v2, v2, v133
	v_log_f32_e32 v2, v2
	s_nop 0
	v_mul_f32_e32 v133, 0x3f317217, v2
	v_fma_f32 v133, v2, s5, -v133
	v_fmac_f32_e32 v133, 0x3377d1cf, v2
	v_fmac_f32_e32 v133, 0x3f317217, v2
	v_cmp_lt_f32_e64 s[0:1], |v2|, s6
	s_nop 1
	v_cndmask_b32_e64 v2, v2, v133, s[0:1]
	v_cndmask_b32_e32 v133, 0, v228, vcc
	v_sub_f32_e32 v145, v2, v133
	v_mul_f32_e64 v2, |v137|, s3
	v_exp_f32_e32 v2, v2
	v_max_f32_e32 v133, 0, v137
	v_pk_add_f32 v[142:143], v[142:143], v[144:145]
	v_add_f32_e32 v2, 1.0, v2
	v_cmp_gt_f32_e32 vcc, s2, v2
	s_nop 1
	v_cndmask_b32_e64 v137, 0, 32, vcc
	v_ldexp_f32 v2, v2, v137
	v_log_f32_e32 v2, v2
	s_nop 0
	v_mul_f32_e32 v137, 0x3f317217, v2
	v_fma_f32 v137, v2, s5, -v137
	v_fmac_f32_e32 v137, 0x3377d1cf, v2
	v_fmac_f32_e32 v137, 0x3f317217, v2
	v_cmp_lt_f32_e64 s[0:1], |v2|, s6
	s_nop 1
	v_cndmask_b32_e64 v2, v2, v137, s[0:1]
	v_cndmask_b32_e32 v137, 0, v228, vcc
	v_sub_f32_e32 v137, v2, v137
	v_add_f32_e32 v2, v130, v138
	v_max_f32_e32 v138, 0, v2
	v_mul_f32_e64 v2, |v2|, s3
	v_exp_f32_e32 v2, v2
	v_pk_add_f32 v[132:133], v[132:133], v[136:137]
	v_lshl_add_u64 v[136:137], v[190:191], 0, v[140:141]
	v_add_f32_e32 v2, 1.0, v2
	v_cmp_gt_f32_e32 vcc, s2, v2
	s_nop 1
	v_cndmask_b32_e64 v134, 0, 32, vcc
	v_ldexp_f32 v2, v2, v134
	v_log_f32_e32 v2, v2
	s_nop 0
	v_mul_f32_e32 v134, 0x3f317217, v2
	v_fma_f32 v134, v2, s5, -v134
	v_fmac_f32_e32 v134, 0x3377d1cf, v2
	v_fmac_f32_e32 v134, 0x3f317217, v2
	v_cmp_lt_f32_e64 s[0:1], |v2|, s6
	s_nop 1
	v_cndmask_b32_e64 v2, v2, v134, s[0:1]
	v_cndmask_b32_e32 v134, 0, v228, vcc
	v_sub_f32_e32 v146, v2, v134
	v_mul_f32_e64 v2, |v147|, s3
	v_exp_f32_e32 v2, v2
	v_max_f32_e32 v134, 0, v147
	v_add_f32_e32 v2, 1.0, v2
	v_cmp_gt_f32_e32 vcc, s2, v2
	s_nop 1
	v_cndmask_b32_e64 v147, 0, 32, vcc
	v_ldexp_f32 v2, v2, v147
	v_log_f32_e32 v2, v2
	s_nop 0
	v_mul_f32_e32 v147, 0x3f317217, v2
	v_fma_f32 v147, v2, s5, -v147
	v_fmac_f32_e32 v147, 0x3377d1cf, v2
	v_fmac_f32_e32 v147, 0x3f317217, v2
	v_cmp_lt_f32_e64 s[0:1], |v2|, s6
	s_nop 1
	v_cndmask_b32_e64 v2, v2, v147, s[0:1]
	v_cndmask_b32_e32 v147, 0, v228, vcc
	v_sub_f32_e32 v148, v2, v147
	v_add_f32_e32 v2, v131, v139
	v_max_f32_e32 v139, 0, v2
	v_mul_f32_e64 v2, |v2|, s3
	v_exp_f32_e32 v2, v2
	s_nop 0
	v_add_f32_e32 v2, 1.0, v2
	v_cmp_gt_f32_e32 vcc, s2, v2
	s_nop 1
	v_cndmask_b32_e64 v135, 0, 32, vcc
	v_ldexp_f32 v2, v2, v135
	v_log_f32_e32 v2, v2
	s_nop 0
	v_mul_f32_e32 v135, 0x3f317217, v2
	v_fma_f32 v135, v2, s5, -v135
	v_fmac_f32_e32 v135, 0x3377d1cf, v2
	v_fmac_f32_e32 v135, 0x3f317217, v2
	v_cmp_lt_f32_e64 s[0:1], |v2|, s6
	s_nop 1
	v_cndmask_b32_e64 v2, v2, v135, s[0:1]
	v_cndmask_b32_e32 v135, 0, v228, vcc
	v_sub_f32_e32 v147, v2, v135
	v_mul_f32_e64 v2, |v149|, s3
	v_exp_f32_e32 v2, v2
	v_pk_add_f32 v[144:145], v[138:139], v[146:147]
	v_max_f32_e32 v135, 0, v149
	v_add_f32_e32 v2, 1.0, v2
	v_cmp_gt_f32_e32 vcc, s2, v2
	s_nop 1
	v_cndmask_b32_e64 v138, 0, 32, vcc
	v_ldexp_f32 v2, v2, v138
	v_log_f32_e32 v2, v2
	s_nop 0
	v_mul_f32_e32 v138, 0x3f317217, v2
	v_fma_f32 v138, v2, s5, -v138
	v_fmac_f32_e32 v138, 0x3377d1cf, v2
	v_fmac_f32_e32 v138, 0x3f317217, v2
	v_cmp_lt_f32_e64 s[0:1], |v2|, s6
	s_nop 1
	v_cndmask_b32_e64 v2, v2, v138, s[0:1]
	v_cndmask_b32_e32 v138, 0, v228, vcc
	v_sub_f32_e32 v149, v2, v138
	v_pk_add_f32 v[134:135], v[134:135], v[148:149]
	global_store_dwordx4 v[136:137], v[142:145], off
	global_store_dwordx4 v[136:137], v[132:135], off offset:16

.LBB0_427:
	s_add_u32 s23, s0, 0xfffc0080
	s_addc_u32 s24, s1, -1
	s_add_i32 s25, 0, 0x10000
	v_add_u32_e32 v2, s25, v187
	ds_read_b128 v[132:135], v2
	ds_read_b128 v[136:139], v2 offset:1024
	ds_read_b128 v[140:143], v2 offset:2048
	ds_read_b128 v[144:147], v2 offset:3072
	s_cmp_eq_u32 s22, 12
	s_cselect_b32 s47, s57, s24
	s_cselect_b32 s46, s56, s23
	s_cselect_b32 s45, s59, s21
	s_cselect_b32 s44, s58, s20
	v_lshl_add_u64 v[208:209], s[0:1], 0, v[194:195]
	s_add_i32 m0, s74, 0xc000
	ds_read_b128 v[148:151], v240
	ds_read_b128 v[152:155], v240 offset:1024
	ds_read_b128 v[156:159], v240 offset:2048
	ds_read_b128 v[160:163], v240 offset:3072
	ds_read_b128 v[164:167], v240 offset:4096
	ds_read_b128 v[168:171], v240 offset:5120
	ds_read_b128 v[172:175], v240 offset:6144
	ds_read_b128 v[204:207], v240 offset:7168
	global_load_lds_dwordx4 v[208:209], off
	v_lshl_add_u64 v[208:209], s[0:1], 0, v[202:203]
	s_add_i32 m0, s74, 0xe000
	s_nop 0
	global_load_lds_dwordx4 v[208:209], off
	s_waitcnt lgkmcnt(8)
	s_barrier
	s_waitcnt lgkmcnt(0)
	v_mfma_f32_16x16x32_bf16 v[128:131], v[132:135], v[148:151], v[128:131]
	v_mfma_f32_16x16x32_bf16 v[124:127], v[140:143], v[148:151], v[124:127]
	v_mfma_f32_16x16x32_bf16 v[120:123], v[132:135], v[156:159], v[120:123]
	v_mfma_f32_16x16x32_bf16 v[116:119], v[140:143], v[156:159], v[116:119]
	v_mfma_f32_16x16x32_bf16 v[112:115], v[132:135], v[164:167], v[112:115]
	v_mfma_f32_16x16x32_bf16 v[108:111], v[140:143], v[164:167], v[108:111]
	v_mfma_f32_16x16x32_bf16 v[104:107], v[132:135], v[172:175], v[104:107]
	v_mfma_f32_16x16x32_bf16 v[100:103], v[140:143], v[172:175], v[100:103]
	v_mfma_f32_16x16x32_bf16 v[128:131], v[136:139], v[152:155], v[128:131]
	v_mfma_f32_16x16x32_bf16 v[124:127], v[144:147], v[152:155], v[124:127]
	v_mfma_f32_16x16x32_bf16 v[120:123], v[136:139], v[160:163], v[120:123]
	v_mfma_f32_16x16x32_bf16 v[116:119], v[144:147], v[160:163], v[116:119]
	v_mfma_f32_16x16x32_bf16 v[112:115], v[136:139], v[168:171], v[112:115]
	v_mfma_f32_16x16x32_bf16 v[108:111], v[144:147], v[168:171], v[108:111]
	v_mfma_f32_16x16x32_bf16 v[104:107], v[136:139], v[204:207], v[104:107]
	v_mfma_f32_16x16x32_bf16 v[100:103], v[144:147], v[204:207], v[100:103]
	s_barrier
	s_add_i32 s23, 0, 0x14000
	s_add_i32 s24, s25, s67
	v_add_u32_e32 v2, s23, v187
	v_lshl_add_u64 v[250:251], s[44:45], 0, v[176:177]
	s_mov_b32 m0, s24
	ds_read_b128 v[208:211], v2
	ds_read_b128 v[212:215], v2 offset:1024
	ds_read_b128 v[242:245], v2 offset:2048
	ds_read_b128 v[246:249], v2 offset:3072
	global_load_lds_dwordx4 v[250:251], off
	v_lshl_add_u64 v[222:223], s[44:45], 0, v[180:181]
	s_add_i32 m0, s24, 0x2000
	s_nop 0
	global_load_lds_dwordx4 v[222:223], off
	s_barrier
	s_waitcnt lgkmcnt(0)
	v_mfma_f32_16x16x32_bf16 v[64:67], v[208:211], v[148:151], v[64:67]
	v_mfma_f32_16x16x32_bf16 v[60:63], v[242:245], v[148:151], v[60:63]
	v_mfma_f32_16x16x32_bf16 v[56:59], v[208:211], v[156:159], v[56:59]
	v_mfma_f32_16x16x32_bf16 v[52:55], v[242:245], v[156:159], v[52:55]
	v_mfma_f32_16x16x32_bf16 v[48:51], v[208:211], v[164:167], v[48:51]
	v_mfma_f32_16x16x32_bf16 v[44:47], v[242:245], v[164:167], v[44:47]
	v_mfma_f32_16x16x32_bf16 v[40:43], v[208:211], v[172:175], v[40:43]
	v_mfma_f32_16x16x32_bf16 v[36:39], v[242:245], v[172:175], v[36:39]
	v_mfma_f32_16x16x32_bf16 v[64:67], v[212:215], v[152:155], v[64:67]
	v_mfma_f32_16x16x32_bf16 v[60:63], v[246:249], v[152:155], v[60:63]
	v_mfma_f32_16x16x32_bf16 v[56:59], v[212:215], v[160:163], v[56:59]
	v_mfma_f32_16x16x32_bf16 v[52:55], v[246:249], v[160:163], v[52:55]
	v_mfma_f32_16x16x32_bf16 v[48:51], v[212:215], v[168:171], v[48:51]
	v_mfma_f32_16x16x32_bf16 v[44:47], v[246:249], v[168:171], v[44:47]
	v_mfma_f32_16x16x32_bf16 v[40:43], v[212:215], v[204:207], v[40:43]
	v_mfma_f32_16x16x32_bf16 v[36:39], v[246:249], v[204:207], v[36:39]
	s_mov_b32 m0, s74
	v_lshl_add_u64 v[216:217], s[46:47], 0, v[0:1]
	s_barrier
	ds_read_b128 v[148:151], v240 offset:16384
	ds_read_b128 v[152:155], v240 offset:17408
	ds_read_b128 v[156:159], v240 offset:18432
	ds_read_b128 v[160:163], v240 offset:19456
	ds_read_b128 v[164:167], v240 offset:20480
	ds_read_b128 v[168:171], v240 offset:21504
	ds_read_b128 v[172:175], v240 offset:22528
	ds_read_b128 v[204:207], v240 offset:23552
	global_load_lds_dwordx4 v[216:217], off
	v_lshl_add_u64 v[236:237], s[46:47], 0, v[178:179]
	s_mov_b32 m0, s75
	s_nop 0
	global_load_lds_dwordx4 v[236:237], off
	s_barrier
	s_waitcnt lgkmcnt(0)
	v_mfma_f32_16x16x32_bf16 v[96:99], v[132:135], v[148:151], v[96:99]
	v_mfma_f32_16x16x32_bf16 v[92:95], v[140:143], v[148:151], v[92:95]
	v_mfma_f32_16x16x32_bf16 v[88:91], v[132:135], v[156:159], v[88:91]
	v_mfma_f32_16x16x32_bf16 v[84:87], v[140:143], v[156:159], v[84:87]
	v_mfma_f32_16x16x32_bf16 v[80:83], v[132:135], v[164:167], v[80:83]
	v_mfma_f32_16x16x32_bf16 v[76:79], v[140:143], v[164:167], v[76:79]
	v_mfma_f32_16x16x32_bf16 v[72:75], v[132:135], v[172:175], v[72:75]
	v_mfma_f32_16x16x32_bf16 v[68:71], v[140:143], v[172:175], v[68:71]
	v_mfma_f32_16x16x32_bf16 v[96:99], v[136:139], v[152:155], v[96:99]
	v_mfma_f32_16x16x32_bf16 v[92:95], v[144:147], v[152:155], v[92:95]
	v_mfma_f32_16x16x32_bf16 v[88:91], v[136:139], v[160:163], v[88:91]
	v_mfma_f32_16x16x32_bf16 v[84:87], v[144:147], v[160:163], v[84:87]
	v_mfma_f32_16x16x32_bf16 v[80:83], v[136:139], v[168:171], v[80:83]
	v_mfma_f32_16x16x32_bf16 v[76:79], v[144:147], v[168:171], v[76:79]
	v_mfma_f32_16x16x32_bf16 v[72:75], v[136:139], v[204:207], v[72:75]
	v_mfma_f32_16x16x32_bf16 v[68:71], v[144:147], v[204:207], v[68:71]
	s_barrier
	s_add_u32 s24, s44, 0x40000
	s_addc_u32 s25, s45, 0
	s_add_i32 s23, s23, s67
	v_lshl_add_u64 v[132:133], s[24:25], 0, v[176:177]
	s_mov_b32 m0, s23
	s_nop 0
	global_load_lds_dwordx4 v[132:133], off
	v_lshl_add_u64 v[132:133], s[24:25], 0, v[180:181]
	s_add_i32 m0, s23, 0x2000
	s_nop 0
	global_load_lds_dwordx4 v[132:133], off
	s_waitcnt vmcnt(6)
	s_barrier
	v_mfma_f32_16x16x32_bf16 v[32:35], v[208:211], v[148:151], v[32:35]
	v_mfma_f32_16x16x32_bf16 v[28:31], v[242:245], v[148:151], v[28:31]
	v_mfma_f32_16x16x32_bf16 v[24:27], v[208:211], v[156:159], v[24:27]
	v_mfma_f32_16x16x32_bf16 v[20:23], v[242:245], v[156:159], v[20:23]
	v_mfma_f32_16x16x32_bf16 v[16:19], v[208:211], v[164:167], v[16:19]
	v_mfma_f32_16x16x32_bf16 v[12:15], v[242:245], v[164:167], v[12:15]
	v_mfma_f32_16x16x32_bf16 v[8:11], v[208:211], v[172:175], v[8:11]
	v_mfma_f32_16x16x32_bf16 v[4:7], v[242:245], v[172:175], v[4:7]
	v_mfma_f32_16x16x32_bf16 v[32:35], v[212:215], v[152:155], v[32:35]
	v_mfma_f32_16x16x32_bf16 v[28:31], v[246:249], v[152:155], v[28:31]
	v_mfma_f32_16x16x32_bf16 v[24:27], v[212:215], v[160:163], v[24:27]
	v_mfma_f32_16x16x32_bf16 v[20:23], v[246:249], v[160:163], v[20:23]
	v_mfma_f32_16x16x32_bf16 v[16:19], v[212:215], v[168:171], v[16:19]
	v_mfma_f32_16x16x32_bf16 v[12:15], v[246:249], v[168:171], v[12:15]
	v_mfma_f32_16x16x32_bf16 v[8:11], v[212:215], v[204:207], v[8:11]
	v_mfma_f32_16x16x32_bf16 v[4:7], v[246:249], v[204:207], v[4:7]
	s_add_i32 s23, 0, 0x18000
	v_add_u32_e32 v2, s23, v187
	s_barrier
	ds_read_b128 v[132:135], v2
	ds_read_b128 v[136:139], v2 offset:1024
	ds_read_b128 v[140:143], v2 offset:2048
	ds_read_b128 v[144:147], v2 offset:3072
	s_add_u32 s24, s46, 0x40000
	s_addc_u32 s25, s47, 0
	s_mov_b32 m0, s82
	v_lshl_add_u64 v[208:209], s[24:25], 0, v[0:1]
	ds_read_b128 v[148:151], v240 offset:32768
	ds_read_b128 v[152:155], v240 offset:33792
	ds_read_b128 v[156:159], v240 offset:34816
	ds_read_b128 v[160:163], v240 offset:35840
	ds_read_b128 v[164:167], v240 offset:36864
	ds_read_b128 v[168:171], v240 offset:37888
	ds_read_b128 v[172:175], v240 offset:38912
	ds_read_b128 v[204:207], v240 offset:39936
	global_load_lds_dwordx4 v[208:209], off
	v_lshl_add_u64 v[208:209], s[24:25], 0, v[178:179]
	s_mov_b32 m0, s83
	s_nop 0
	global_load_lds_dwordx4 v[208:209], off
	s_waitcnt lgkmcnt(8)
	s_barrier
	s_waitcnt lgkmcnt(0)
	v_mfma_f32_16x16x32_bf16 v[128:131], v[132:135], v[148:151], v[128:131]
	v_mfma_f32_16x16x32_bf16 v[124:127], v[140:143], v[148:151], v[124:127]
	v_mfma_f32_16x16x32_bf16 v[120:123], v[132:135], v[156:159], v[120:123]
	v_mfma_f32_16x16x32_bf16 v[116:119], v[140:143], v[156:159], v[116:119]
	v_mfma_f32_16x16x32_bf16 v[112:115], v[132:135], v[164:167], v[112:115]
	v_mfma_f32_16x16x32_bf16 v[108:111], v[140:143], v[164:167], v[108:111]
	v_mfma_f32_16x16x32_bf16 v[104:107], v[132:135], v[172:175], v[104:107]
	v_mfma_f32_16x16x32_bf16 v[100:103], v[140:143], v[172:175], v[100:103]
	v_mfma_f32_16x16x32_bf16 v[128:131], v[136:139], v[152:155], v[128:131]
	v_mfma_f32_16x16x32_bf16 v[124:127], v[144:147], v[152:155], v[124:127]
	v_mfma_f32_16x16x32_bf16 v[120:123], v[136:139], v[160:163], v[120:123]
	v_mfma_f32_16x16x32_bf16 v[116:119], v[144:147], v[160:163], v[116:119]
	v_mfma_f32_16x16x32_bf16 v[112:115], v[136:139], v[168:171], v[112:115]
	v_mfma_f32_16x16x32_bf16 v[108:111], v[144:147], v[168:171], v[108:111]
	v_mfma_f32_16x16x32_bf16 v[104:107], v[136:139], v[204:207], v[104:107]
	v_mfma_f32_16x16x32_bf16 v[100:103], v[144:147], v[204:207], v[100:103]
	s_barrier
	s_add_i32 s26, 0, 0x1c000
	s_add_i32 s23, s23, s67
	v_add_u32_e32 v2, s26, v187
	v_lshl_add_u64 v[250:251], v[250:251], 0, s[76:77]
	s_mov_b32 m0, s23
	ds_read_b128 v[208:211], v2
	ds_read_b128 v[212:215], v2 offset:1024
	ds_read_b128 v[242:245], v2 offset:2048
	ds_read_b128 v[246:249], v2 offset:3072
	global_load_lds_dwordx4 v[250:251], off
	v_lshl_add_u64 v[222:223], v[222:223], 0, s[76:77]
	s_add_i32 m0, s23, 0x2000
	s_nop 0
	global_load_lds_dwordx4 v[222:223], off
	s_barrier
	s_waitcnt lgkmcnt(0)
	v_mfma_f32_16x16x32_bf16 v[64:67], v[208:211], v[148:151], v[64:67]
	v_mfma_f32_16x16x32_bf16 v[60:63], v[242:245], v[148:151], v[60:63]
	v_mfma_f32_16x16x32_bf16 v[56:59], v[208:211], v[156:159], v[56:59]
	v_mfma_f32_16x16x32_bf16 v[52:55], v[242:245], v[156:159], v[52:55]
	v_mfma_f32_16x16x32_bf16 v[48:51], v[208:211], v[164:167], v[48:51]
	v_mfma_f32_16x16x32_bf16 v[44:47], v[242:245], v[164:167], v[44:47]
	v_mfma_f32_16x16x32_bf16 v[40:43], v[208:211], v[172:175], v[40:43]
	v_mfma_f32_16x16x32_bf16 v[36:39], v[242:245], v[172:175], v[36:39]
	v_mfma_f32_16x16x32_bf16 v[64:67], v[212:215], v[152:155], v[64:67]
	v_mfma_f32_16x16x32_bf16 v[60:63], v[246:249], v[152:155], v[60:63]
	v_mfma_f32_16x16x32_bf16 v[56:59], v[212:215], v[160:163], v[56:59]
	v_mfma_f32_16x16x32_bf16 v[52:55], v[246:249], v[160:163], v[52:55]
	v_mfma_f32_16x16x32_bf16 v[48:51], v[212:215], v[168:171], v[48:51]
	v_mfma_f32_16x16x32_bf16 v[44:47], v[246:249], v[168:171], v[44:47]
	v_mfma_f32_16x16x32_bf16 v[40:43], v[212:215], v[204:207], v[40:43]
	v_mfma_f32_16x16x32_bf16 v[36:39], v[246:249], v[204:207], v[36:39]
	s_mov_b32 m0, s48
	v_lshl_add_u64 v[216:217], v[216:217], 0, s[76:77]
	s_barrier
	ds_read_b128 v[148:151], v240 offset:49152
	ds_read_b128 v[152:155], v240 offset:50176
	ds_read_b128 v[156:159], v240 offset:51200
	ds_read_b128 v[160:163], v240 offset:52224
	ds_read_b128 v[164:167], v240 offset:53248
	ds_read_b128 v[168:171], v240 offset:54272
	ds_read_b128 v[172:175], v240 offset:55296
	ds_read_b128 v[204:207], v240 offset:56320
	global_load_lds_dwordx4 v[216:217], off
	v_lshl_add_u64 v[216:217], v[236:237], 0, s[76:77]
	s_mov_b32 m0, s50
	s_nop 0
	global_load_lds_dwordx4 v[216:217], off
	s_barrier
	s_waitcnt lgkmcnt(0)
	v_mfma_f32_16x16x32_bf16 v[96:99], v[132:135], v[148:151], v[96:99]
	v_mfma_f32_16x16x32_bf16 v[92:95], v[140:143], v[148:151], v[92:95]
	v_mfma_f32_16x16x32_bf16 v[88:91], v[132:135], v[156:159], v[88:91]
	v_mfma_f32_16x16x32_bf16 v[84:87], v[140:143], v[156:159], v[84:87]
	v_mfma_f32_16x16x32_bf16 v[80:83], v[132:135], v[164:167], v[80:83]
	v_mfma_f32_16x16x32_bf16 v[76:79], v[140:143], v[164:167], v[76:79]
	v_mfma_f32_16x16x32_bf16 v[72:75], v[132:135], v[172:175], v[72:75]
	v_mfma_f32_16x16x32_bf16 v[68:71], v[140:143], v[172:175], v[68:71]
	v_mfma_f32_16x16x32_bf16 v[96:99], v[136:139], v[152:155], v[96:99]
	v_mfma_f32_16x16x32_bf16 v[92:95], v[144:147], v[152:155], v[92:95]
	v_mfma_f32_16x16x32_bf16 v[88:91], v[136:139], v[160:163], v[88:91]
	v_mfma_f32_16x16x32_bf16 v[84:87], v[144:147], v[160:163], v[84:87]
	v_mfma_f32_16x16x32_bf16 v[80:83], v[136:139], v[168:171], v[80:83]
	v_mfma_f32_16x16x32_bf16 v[76:79], v[144:147], v[168:171], v[76:79]
	v_mfma_f32_16x16x32_bf16 v[72:75], v[136:139], v[204:207], v[72:75]
	v_mfma_f32_16x16x32_bf16 v[68:71], v[144:147], v[204:207], v[68:71]
	s_barrier
	s_add_u32 s24, s44, 0x40080
	s_addc_u32 s25, s45, 0
	s_add_i32 s23, s26, s67
	v_lshl_add_u64 v[132:133], s[24:25], 0, v[176:177]
	s_mov_b32 m0, s23
	s_nop 0
	global_load_lds_dwordx4 v[132:133], off
	v_lshl_add_u64 v[132:133], s[24:25], 0, v[180:181]
	s_add_i32 m0, s23, 0x2000
	s_nop 0
	global_load_lds_dwordx4 v[132:133], off
	s_waitcnt vmcnt(6)
	s_barrier
	v_mfma_f32_16x16x32_bf16 v[32:35], v[208:211], v[148:151], v[32:35]
	v_mfma_f32_16x16x32_bf16 v[28:31], v[242:245], v[148:151], v[28:31]
	v_mfma_f32_16x16x32_bf16 v[24:27], v[208:211], v[156:159], v[24:27]
	v_mfma_f32_16x16x32_bf16 v[20:23], v[242:245], v[156:159], v[20:23]
	v_mfma_f32_16x16x32_bf16 v[16:19], v[208:211], v[164:167], v[16:19]
	v_mfma_f32_16x16x32_bf16 v[12:15], v[242:245], v[164:167], v[12:15]
	v_mfma_f32_16x16x32_bf16 v[8:11], v[208:211], v[172:175], v[8:11]
	v_mfma_f32_16x16x32_bf16 v[4:7], v[242:245], v[172:175], v[4:7]
	v_mfma_f32_16x16x32_bf16 v[32:35], v[212:215], v[152:155], v[32:35]
	v_mfma_f32_16x16x32_bf16 v[28:31], v[246:249], v[152:155], v[28:31]
	v_mfma_f32_16x16x32_bf16 v[24:27], v[212:215], v[160:163], v[24:27]
	v_mfma_f32_16x16x32_bf16 v[20:23], v[246:249], v[160:163], v[20:23]
	v_mfma_f32_16x16x32_bf16 v[16:19], v[212:215], v[168:171], v[16:19]
	v_mfma_f32_16x16x32_bf16 v[12:15], v[246:249], v[168:171], v[12:15]
	v_mfma_f32_16x16x32_bf16 v[8:11], v[212:215], v[204:207], v[8:11]
	v_mfma_f32_16x16x32_bf16 v[4:7], v[246:249], v[204:207], v[4:7]
	s_add_i32 s22, s22, 2
	s_add_u32 s0, s0, 0x100
	s_addc_u32 s1, s1, 0
	s_add_u32 s20, s20, 0x100
	s_addc_u32 s21, s21, 0
	s_cmp_gt_u32 s22, 13
	s_barrier
	s_cbranch_scc0 .LBB0_427
	s_add_i32 s0, s61, -8
	s_cmp_lt_u32 s0, 12
	s_mov_b64 s[0:1], -1
	s_cbranch_scc1 .LBB0_451
	s_cmp_gt_i32 s61, 33
	s_cselect_b64 s[64:65], -1, 0
	s_lshl_b32 s0, s61, 8
	s_lshl_b32 s53, s60, 8
	s_add_i32 s1, s0, 0xffffee00
	s_cmp_lt_i32 s61, 26
	v_cndmask_b32_e64 v2, 0, 1, s[36:37]
	s_cselect_b32 s62, s0, s1
	s_mov_b64 s[0:1], -1
	s_and_b64 vcc, exec, s[64:65]
	v_cmp_ne_u32_e64 s[44:45], 1, v2
	s_cbranch_vccz .LBB0_433
	s_and_b64 vcc, exec, s[44:45]
	s_cbranch_vccnz .LBB0_432
	v_add_u32_e32 v132, s53, v185
	v_ashrrev_i32_e32 v133, 31, v132
	v_lshlrev_b64 v[140:141], 7, v[132:133]
	global_load_dwordx4 v[204:207], v[188:189], off offset:16
	global_load_dwordx4 v[208:211], v[188:189], off
	s_mov_b32 s3, 0xbfb8aa3b
	s_mov_b32 s2, 0x800000
	s_mov_b32 s4, 0x3f317217
	s_mov_b32 s5, 0x7f800000
	s_waitcnt vmcnt(0)
	v_mov_b32_e32 v132, v204
	v_mov_b32_e32 v133, v205
	v_mov_b32_e32 v134, v206
	v_mov_b32_e32 v135, v207
	v_mov_b32_e32 v136, v208
	v_mov_b32_e32 v137, v209
	v_mov_b32_e32 v138, v210
	v_mov_b32_e32 v139, v211
	v_add_f32_e32 v147, v126, v134
	v_add_f32_e32 v2, v128, v136
	v_max_f32_e32 v142, 0, v2
	v_mul_f32_e64 v2, |v2|, s3
	v_exp_f32_e32 v2, v2
	v_add_f32_e32 v136, v124, v132
	v_add_f32_e32 v149, v127, v135
	v_add_f32_e32 v2, 1.0, v2
	v_cmp_gt_f32_e32 vcc, s2, v2
	s_nop 1
	v_cndmask_b32_e64 v132, 0, 32, vcc
	v_ldexp_f32 v2, v2, v132
	v_log_f32_e32 v2, v2
	s_nop 0
	v_mul_f32_e32 v132, 0x3f317217, v2
	v_fma_f32 v132, v2, s4, -v132
	v_fmac_f32_e32 v132, 0x3377d1cf, v2
	v_fmac_f32_e32 v132, 0x3f317217, v2
	v_cmp_lt_f32_e64 s[0:1], |v2|, s5
	s_nop 1
	v_cndmask_b32_e64 v2, v2, v132, s[0:1]
	v_cndmask_b32_e32 v132, 0, v228, vcc
	v_sub_f32_e32 v144, v2, v132
	v_mul_f32_e64 v2, |v136|, s3
	v_exp_f32_e32 v2, v2
	v_max_f32_e32 v132, 0, v136
	v_add_f32_e32 v2, 1.0, v2
	v_cmp_gt_f32_e32 vcc, s2, v2
	s_nop 1
	v_cndmask_b32_e64 v136, 0, 32, vcc
	v_ldexp_f32 v2, v2, v136
	v_log_f32_e32 v2, v2
	s_nop 0
	v_mul_f32_e32 v136, 0x3f317217, v2
	v_fma_f32 v136, v2, s4, -v136
	v_fmac_f32_e32 v136, 0x3377d1cf, v2
	v_fmac_f32_e32 v136, 0x3f317217, v2
	v_cmp_lt_f32_e64 s[0:1], |v2|, s5
	s_nop 1
	v_cndmask_b32_e64 v2, v2, v136, s[0:1]
	v_cndmask_b32_e32 v136, 0, v228, vcc
	v_sub_f32_e32 v136, v2, v136
	v_add_f32_e32 v2, v129, v137
	v_max_f32_e32 v143, 0, v2
	v_mul_f32_e64 v2, |v2|, s3
	v_exp_f32_e32 v2, v2
	v_add_f32_e32 v137, v125, v133
	v_add_f32_e32 v2, 1.0, v2
	v_cmp_gt_f32_e32 vcc, s2, v2
	s_nop 1
	v_cndmask_b32_e64 v133, 0, 32, vcc
	v_ldexp_f32 v2, v2, v133
	v_log_f32_e32 v2, v2
	s_nop 0
	v_mul_f32_e32 v133, 0x3f317217, v2
	v_fma_f32 v133, v2, s4, -v133
	v_fmac_f32_e32 v133, 0x3377d1cf, v2
	v_fmac_f32_e32 v133, 0x3f317217, v2
	v_cmp_lt_f32_e64 s[0:1], |v2|, s5
	s_nop 1
	v_cndmask_b32_e64 v2, v2, v133, s[0:1]
	v_cndmask_b32_e32 v133, 0, v228, vcc
	v_sub_f32_e32 v145, v2, v133
	v_mul_f32_e64 v2, |v137|, s3
	v_exp_f32_e32 v2, v2
	v_max_f32_e32 v133, 0, v137
	v_pk_add_f32 v[142:143], v[142:143], v[144:145]
	v_add_f32_e32 v2, 1.0, v2
	v_cmp_gt_f32_e32 vcc, s2, v2
	s_nop 1
	v_cndmask_b32_e64 v137, 0, 32, vcc
	v_ldexp_f32 v2, v2, v137
	v_log_f32_e32 v2, v2
	s_nop 0
	v_mul_f32_e32 v137, 0x3f317217, v2
	v_fma_f32 v137, v2, s4, -v137
	v_fmac_f32_e32 v137, 0x3377d1cf, v2
	v_fmac_f32_e32 v137, 0x3f317217, v2
	v_cmp_lt_f32_e64 s[0:1], |v2|, s5
	s_nop 1
	v_cndmask_b32_e64 v2, v2, v137, s[0:1]
	v_cndmask_b32_e32 v137, 0, v228, vcc
	v_sub_f32_e32 v137, v2, v137
	v_add_f32_e32 v2, v130, v138
	v_max_f32_e32 v138, 0, v2
	v_mul_f32_e64 v2, |v2|, s3
	v_exp_f32_e32 v2, v2
	v_pk_add_f32 v[132:133], v[132:133], v[136:137]
	v_lshl_add_u64 v[136:137], v[190:191], 0, v[140:141]
	v_add_f32_e32 v2, 1.0, v2
	v_cmp_gt_f32_e32 vcc, s2, v2
	s_nop 1
	v_cndmask_b32_e64 v134, 0, 32, vcc
	v_ldexp_f32 v2, v2, v134
	v_log_f32_e32 v2, v2
	s_nop 0
	v_mul_f32_e32 v134, 0x3f317217, v2
	v_fma_f32 v134, v2, s4, -v134
	v_fmac_f32_e32 v134, 0x3377d1cf, v2
	v_fmac_f32_e32 v134, 0x3f317217, v2
	v_cmp_lt_f32_e64 s[0:1], |v2|, s5
	s_nop 1
	v_cndmask_b32_e64 v2, v2, v134, s[0:1]
	v_cndmask_b32_e32 v134, 0, v228, vcc
	v_sub_f32_e32 v146, v2, v134
	v_mul_f32_e64 v2, |v147|, s3
	v_exp_f32_e32 v2, v2
	v_max_f32_e32 v134, 0, v147
	v_add_f32_e32 v2, 1.0, v2
	v_cmp_gt_f32_e32 vcc, s2, v2
	s_nop 1
	v_cndmask_b32_e64 v147, 0, 32, vcc
	v_ldexp_f32 v2, v2, v147
	v_log_f32_e32 v2, v2
	s_nop 0
	v_mul_f32_e32 v147, 0x3f317217, v2
	v_fma_f32 v147, v2, s4, -v147
	v_fmac_f32_e32 v147, 0x3377d1cf, v2
	v_fmac_f32_e32 v147, 0x3f317217, v2
	v_cmp_lt_f32_e64 s[0:1], |v2|, s5
	s_nop 1
	v_cndmask_b32_e64 v2, v2, v147, s[0:1]
	v_cndmask_b32_e32 v147, 0, v228, vcc
	v_sub_f32_e32 v148, v2, v147
	v_add_f32_e32 v2, v131, v139
	v_max_f32_e32 v139, 0, v2
	v_mul_f32_e64 v2, |v2|, s3
	v_exp_f32_e32 v2, v2
	s_nop 0
	v_add_f32_e32 v2, 1.0, v2
	v_cmp_gt_f32_e32 vcc, s2, v2
	s_nop 1
	v_cndmask_b32_e64 v135, 0, 32, vcc
	v_ldexp_f32 v2, v2, v135
	v_log_f32_e32 v2, v2
	s_nop 0
	v_mul_f32_e32 v135, 0x3f317217, v2
	v_fma_f32 v135, v2, s4, -v135
	v_fmac_f32_e32 v135, 0x3377d1cf, v2
	v_fmac_f32_e32 v135, 0x3f317217, v2
	v_cmp_lt_f32_e64 s[0:1], |v2|, s5
	s_nop 1
	v_cndmask_b32_e64 v2, v2, v135, s[0:1]
	v_cndmask_b32_e32 v135, 0, v228, vcc
	v_sub_f32_e32 v147, v2, v135
	v_mul_f32_e64 v2, |v149|, s3
	v_exp_f32_e32 v2, v2
	v_pk_add_f32 v[144:145], v[138:139], v[146:147]
	v_max_f32_e32 v135, 0, v149
	v_add_f32_e32 v2, 1.0, v2
	v_cmp_gt_f32_e32 vcc, s2, v2
	s_nop 1
	v_cndmask_b32_e64 v138, 0, 32, vcc
	v_ldexp_f32 v2, v2, v138
	v_log_f32_e32 v2, v2
	s_nop 0
	v_mul_f32_e32 v138, 0x3f317217, v2
	v_fma_f32 v138, v2, s4, -v138
	v_fmac_f32_e32 v138, 0x3377d1cf, v2
	v_fmac_f32_e32 v138, 0x3f317217, v2
	v_cmp_lt_f32_e64 s[0:1], |v2|, s5
	s_nop 1
	v_cndmask_b32_e64 v2, v2, v138, s[0:1]
	v_cndmask_b32_e32 v138, 0, v228, vcc
	v_sub_f32_e32 v149, v2, v138
	v_pk_add_f32 v[134:135], v[134:135], v[148:149]
	global_store_dwordx4 v[136:137], v[142:145], off
	global_store_dwordx4 v[136:137], v[132:135], off offset:16
